# K-loop LDS-DMA loads converted to saddr form (SGPR base + 32-bit VGPR offset): 120 v_lshl_add_u64 per-iteration address adds deleted across the 8 GEMM loops; on top of v7
# speedup vs baseline: 1.0236x; 1.0028x over previous
.LBB0_154:
	ds_read_b128 v[150:153], v147
	ds_read_b128 v[154:157], v147 offset:1024
	ds_read_b128 v[158:161], v147 offset:2048
	ds_read_b128 v[162:165], v147 offset:3072
	s_add_u32 s18, s16, 0xfff80080
	s_addc_u32 s19, s17, -1
	s_cmp_eq_u32 s40, 28
	s_cselect_b32 s21, s11, s19
	s_cselect_b32 s20, s36, s18
	s_cselect_b32 s19, s9, s39
	s_cselect_b32 s18, s37, s38
	s_add_i32 m0, s7, 0xc000
	ds_read_b128 v[166:169], v148
	ds_read_b128 v[170:173], v148 offset:1024
	ds_read_b128 v[174:177], v148 offset:2048
	ds_read_b128 v[178:181], v148 offset:3072
	ds_read_b128 v[182:185], v148 offset:4096
	ds_read_b128 v[186:189], v148 offset:5120
	ds_read_b128 v[190:193], v148 offset:6144
	ds_read_b128 v[194:197], v148 offset:7168
	global_load_lds_dwordx4 v136, s[16:17]
	s_add_i32 m0, s7, 0xe000
	s_nop 0
	global_load_lds_dwordx4 v138, s[16:17]
	s_waitcnt lgkmcnt(8)
	s_barrier
	s_waitcnt lgkmcnt(0)
	s_waitcnt lgkmcnt(0)
	v_mfma_f32_16x16x32_bf16 v[124:127], v[150:153], v[166:169], v[124:127]
	v_mfma_f32_16x16x32_bf16 v[120:123], v[158:161], v[166:169], v[120:123]
	v_mfma_f32_16x16x32_bf16 v[116:119], v[150:153], v[174:177], v[116:119]
	v_mfma_f32_16x16x32_bf16 v[112:115], v[158:161], v[174:177], v[112:115]
	v_mfma_f32_16x16x32_bf16 v[100:103], v[150:153], v[182:185], v[100:103]
	v_mfma_f32_16x16x32_bf16 v[96:99], v[158:161], v[182:185], v[96:99]
	v_mfma_f32_16x16x32_bf16 v[84:87], v[150:153], v[190:193], v[84:87]
	v_mfma_f32_16x16x32_bf16 v[80:83], v[158:161], v[190:193], v[80:83]
	v_mfma_f32_16x16x32_bf16 v[124:127], v[154:157], v[170:173], v[124:127]
	v_mfma_f32_16x16x32_bf16 v[120:123], v[162:165], v[170:173], v[120:123]
	v_mfma_f32_16x16x32_bf16 v[116:119], v[154:157], v[178:181], v[116:119]
	v_mfma_f32_16x16x32_bf16 v[112:115], v[162:165], v[178:181], v[112:115]
	v_mfma_f32_16x16x32_bf16 v[100:103], v[154:157], v[186:189], v[100:103]
	v_mfma_f32_16x16x32_bf16 v[96:99], v[162:165], v[186:189], v[96:99]
	v_mfma_f32_16x16x32_bf16 v[84:87], v[154:157], v[194:197], v[84:87]
	v_mfma_f32_16x16x32_bf16 v[80:83], v[162:165], v[194:197], v[80:83]
	s_barrier
	s_add_i32 s41, s31, s23
	s_mov_b32 m0, s41
	ds_read_b128 v[198:201], v149
	ds_read_b128 v[204:207], v149 offset:1024
	ds_read_b128 v[208:211], v149 offset:2048
	ds_read_b128 v[212:215], v149 offset:3072
	global_load_lds_dwordx4 v132, s[18:19]
	s_add_i32 m0, s41, 0x2000
	s_nop 0
	global_load_lds_dwordx4 v128, s[18:19]
	s_barrier
	s_waitcnt lgkmcnt(0)
	s_waitcnt lgkmcnt(0)
	v_mfma_f32_16x16x32_bf16 v[108:111], v[198:201], v[166:169], v[108:111]
	v_mfma_f32_16x16x32_bf16 v[104:107], v[208:211], v[166:169], v[104:107]
	v_mfma_f32_16x16x32_bf16 v[92:95], v[198:201], v[174:177], v[92:95]
	v_mfma_f32_16x16x32_bf16 v[88:91], v[208:211], v[174:177], v[88:91]
	v_mfma_f32_16x16x32_bf16 v[76:79], v[198:201], v[182:185], v[76:79]
	v_mfma_f32_16x16x32_bf16 v[72:75], v[208:211], v[182:185], v[72:75]
	v_mfma_f32_16x16x32_bf16 v[68:71], v[198:201], v[190:193], v[68:71]
	v_mfma_f32_16x16x32_bf16 v[64:67], v[208:211], v[190:193], v[64:67]
	v_mfma_f32_16x16x32_bf16 v[108:111], v[204:207], v[170:173], v[108:111]
	v_mfma_f32_16x16x32_bf16 v[104:107], v[212:215], v[170:173], v[104:107]
	v_mfma_f32_16x16x32_bf16 v[92:95], v[204:207], v[178:181], v[92:95]
	v_mfma_f32_16x16x32_bf16 v[88:91], v[212:215], v[178:181], v[88:91]
	v_mfma_f32_16x16x32_bf16 v[76:79], v[204:207], v[186:189], v[76:79]
	v_mfma_f32_16x16x32_bf16 v[72:75], v[212:215], v[186:189], v[72:75]
	v_mfma_f32_16x16x32_bf16 v[68:71], v[204:207], v[194:197], v[68:71]
	v_mfma_f32_16x16x32_bf16 v[64:67], v[212:215], v[194:197], v[64:67]
	s_mov_b32 m0, s7
	s_mov_b64 s[98:99], s[20:21]
	s_barrier
	ds_read_b128 v[166:169], v148 offset:16384
	ds_read_b128 v[170:173], v148 offset:17408
	ds_read_b128 v[174:177], v148 offset:18432
	ds_read_b128 v[178:181], v148 offset:19456
	ds_read_b128 v[182:185], v148 offset:20480
	ds_read_b128 v[186:189], v148 offset:21504
	ds_read_b128 v[190:193], v148 offset:22528
	ds_read_b128 v[194:197], v148 offset:23552
	global_load_lds_dwordx4 v134, s[20:21]
	s_mov_b32 m0, s25
	s_nop 0
	global_load_lds_dwordx4 v130, s[20:21]
	s_barrier
	s_waitcnt lgkmcnt(0)
	s_waitcnt lgkmcnt(0)
	v_mfma_f32_16x16x32_bf16 v[60:63], v[150:153], v[166:169], v[60:63]
	v_mfma_f32_16x16x32_bf16 v[56:59], v[158:161], v[166:169], v[56:59]
	v_mfma_f32_16x16x32_bf16 v[52:55], v[150:153], v[174:177], v[52:55]
	v_mfma_f32_16x16x32_bf16 v[48:51], v[158:161], v[174:177], v[48:51]
	v_mfma_f32_16x16x32_bf16 v[36:39], v[150:153], v[182:185], v[36:39]
	v_mfma_f32_16x16x32_bf16 v[32:35], v[158:161], v[182:185], v[32:35]
	v_mfma_f32_16x16x32_bf16 v[20:23], v[150:153], v[190:193], v[20:23]
	v_mfma_f32_16x16x32_bf16 v[16:19], v[158:161], v[190:193], v[16:19]
	v_mfma_f32_16x16x32_bf16 v[60:63], v[154:157], v[170:173], v[60:63]
	v_mfma_f32_16x16x32_bf16 v[56:59], v[162:165], v[170:173], v[56:59]
	v_mfma_f32_16x16x32_bf16 v[52:55], v[154:157], v[178:181], v[52:55]
	v_mfma_f32_16x16x32_bf16 v[48:51], v[162:165], v[178:181], v[48:51]
	v_mfma_f32_16x16x32_bf16 v[36:39], v[154:157], v[186:189], v[36:39]
	v_mfma_f32_16x16x32_bf16 v[32:35], v[162:165], v[186:189], v[32:35]
	v_mfma_f32_16x16x32_bf16 v[20:23], v[154:157], v[194:197], v[20:23]
	v_mfma_f32_16x16x32_bf16 v[16:19], v[162:165], v[194:197], v[16:19]
	s_barrier
	s_add_u32 s42, s18, 0x20000
	s_addc_u32 s43, s19, 0
	s_add_i32 s41, s33, s23
	s_mov_b32 m0, s41
	s_nop 0
	global_load_lds_dwordx4 v132, s[42:43]
	s_add_i32 m0, s41, 0x2000
	s_nop 0
	global_load_lds_dwordx4 v128, s[42:43]
	s_waitcnt vmcnt(6)
	s_barrier
	v_mfma_f32_16x16x32_bf16 v[44:47], v[198:201], v[166:169], v[44:47]
	v_mfma_f32_16x16x32_bf16 v[40:43], v[208:211], v[166:169], v[40:43]
	v_mfma_f32_16x16x32_bf16 v[28:31], v[198:201], v[174:177], v[28:31]
	v_mfma_f32_16x16x32_bf16 v[24:27], v[208:211], v[174:177], v[24:27]
	v_mfma_f32_16x16x32_bf16 v[12:15], v[198:201], v[182:185], v[12:15]
	v_mfma_f32_16x16x32_bf16 v[8:11], v[208:211], v[182:185], v[8:11]
	v_mfma_f32_16x16x32_bf16 v[4:7], v[198:201], v[190:193], v[4:7]
	v_mfma_f32_16x16x32_bf16 v[0:3], v[208:211], v[190:193], v[0:3]
	v_mfma_f32_16x16x32_bf16 v[44:47], v[204:207], v[170:173], v[44:47]
	v_mfma_f32_16x16x32_bf16 v[40:43], v[212:215], v[170:173], v[40:43]
	v_mfma_f32_16x16x32_bf16 v[28:31], v[204:207], v[178:181], v[28:31]
	v_mfma_f32_16x16x32_bf16 v[24:27], v[212:215], v[178:181], v[24:27]
	v_mfma_f32_16x16x32_bf16 v[12:15], v[204:207], v[186:189], v[12:15]
	v_mfma_f32_16x16x32_bf16 v[8:11], v[212:215], v[186:189], v[8:11]
	v_mfma_f32_16x16x32_bf16 v[4:7], v[204:207], v[194:197], v[4:7]
	v_mfma_f32_16x16x32_bf16 v[0:3], v[212:215], v[194:197], v[0:3]
	s_add_i32 s41, 0, 0x18000
	v_add_u32_e32 v162, s41, v145
	s_barrier
	ds_read_b128 v[150:153], v162
	ds_read_b128 v[154:157], v162 offset:1024
	ds_read_b128 v[158:161], v162 offset:2048
	ds_read_b128 v[162:165], v162 offset:3072
	s_add_u32 s20, s20, 0x80000
	s_addc_u32 s21, s21, 0
	s_mov_b32 m0, s26
	ds_read_b128 v[166:169], v148 offset:32768
	ds_read_b128 v[170:173], v148 offset:33792
	ds_read_b128 v[174:177], v148 offset:34816
	ds_read_b128 v[178:181], v148 offset:35840
	ds_read_b128 v[182:185], v148 offset:36864
	ds_read_b128 v[186:189], v148 offset:37888
	ds_read_b128 v[190:193], v148 offset:38912
	ds_read_b128 v[194:197], v148 offset:39936
	global_load_lds_dwordx4 v134, s[20:21]
	s_mov_b32 m0, s27
	s_nop 0
	global_load_lds_dwordx4 v130, s[20:21]
	s_waitcnt lgkmcnt(8)
	s_barrier
	s_waitcnt lgkmcnt(0)
	s_waitcnt lgkmcnt(0)
	v_mfma_f32_16x16x32_bf16 v[124:127], v[150:153], v[166:169], v[124:127]
	v_mfma_f32_16x16x32_bf16 v[120:123], v[158:161], v[166:169], v[120:123]
	v_mfma_f32_16x16x32_bf16 v[116:119], v[150:153], v[174:177], v[116:119]
	v_mfma_f32_16x16x32_bf16 v[112:115], v[158:161], v[174:177], v[112:115]
	v_mfma_f32_16x16x32_bf16 v[100:103], v[150:153], v[182:185], v[100:103]
	v_mfma_f32_16x16x32_bf16 v[96:99], v[158:161], v[182:185], v[96:99]
	v_mfma_f32_16x16x32_bf16 v[84:87], v[150:153], v[190:193], v[84:87]
	v_mfma_f32_16x16x32_bf16 v[80:83], v[158:161], v[190:193], v[80:83]
	v_mfma_f32_16x16x32_bf16 v[124:127], v[154:157], v[170:173], v[124:127]
	v_mfma_f32_16x16x32_bf16 v[120:123], v[162:165], v[170:173], v[120:123]
	v_mfma_f32_16x16x32_bf16 v[116:119], v[154:157], v[178:181], v[116:119]
	v_mfma_f32_16x16x32_bf16 v[112:115], v[162:165], v[178:181], v[112:115]
	v_mfma_f32_16x16x32_bf16 v[100:103], v[154:157], v[186:189], v[100:103]
	v_mfma_f32_16x16x32_bf16 v[96:99], v[162:165], v[186:189], v[96:99]
	v_mfma_f32_16x16x32_bf16 v[84:87], v[154:157], v[194:197], v[84:87]
	v_mfma_f32_16x16x32_bf16 v[80:83], v[162:165], v[194:197], v[80:83]
	s_barrier
	s_add_i32 s20, 0, 0x1c000
	s_add_i32 s21, s41, s23
	v_add_u32_e32 v212, s20, v145
	s_mov_b32 m0, s21
	ds_read_b128 v[198:201], v212
	ds_read_b128 v[204:207], v212 offset:1024
	ds_read_b128 v[208:211], v212 offset:2048
	ds_read_b128 v[212:215], v212 offset:3072
	s_add_u32 s100, s18, 0x80
	s_addc_u32 s101, s19, 0
	global_load_lds_dwordx4 v132, s[100:101]
	s_add_i32 m0, s21, 0x2000
	s_nop 0
	s_add_u32 s100, s18, 0x80
	s_addc_u32 s101, s19, 0
	global_load_lds_dwordx4 v128, s[100:101]
	s_barrier
	s_waitcnt lgkmcnt(0)
	s_waitcnt lgkmcnt(0)
	v_mfma_f32_16x16x32_bf16 v[108:111], v[198:201], v[166:169], v[108:111]
	v_mfma_f32_16x16x32_bf16 v[104:107], v[208:211], v[166:169], v[104:107]
	v_mfma_f32_16x16x32_bf16 v[92:95], v[198:201], v[174:177], v[92:95]
	v_mfma_f32_16x16x32_bf16 v[88:91], v[208:211], v[174:177], v[88:91]
	v_mfma_f32_16x16x32_bf16 v[76:79], v[198:201], v[182:185], v[76:79]
	v_mfma_f32_16x16x32_bf16 v[72:75], v[208:211], v[182:185], v[72:75]
	v_mfma_f32_16x16x32_bf16 v[68:71], v[198:201], v[190:193], v[68:71]
	v_mfma_f32_16x16x32_bf16 v[64:67], v[208:211], v[190:193], v[64:67]
	v_mfma_f32_16x16x32_bf16 v[108:111], v[204:207], v[170:173], v[108:111]
	v_mfma_f32_16x16x32_bf16 v[104:107], v[212:215], v[170:173], v[104:107]
	v_mfma_f32_16x16x32_bf16 v[92:95], v[204:207], v[178:181], v[92:95]
	v_mfma_f32_16x16x32_bf16 v[88:91], v[212:215], v[178:181], v[88:91]
	v_mfma_f32_16x16x32_bf16 v[76:79], v[204:207], v[186:189], v[76:79]
	v_mfma_f32_16x16x32_bf16 v[72:75], v[212:215], v[186:189], v[72:75]
	v_mfma_f32_16x16x32_bf16 v[68:71], v[204:207], v[194:197], v[68:71]
	v_mfma_f32_16x16x32_bf16 v[64:67], v[212:215], v[194:197], v[64:67]
	s_mov_b32 m0, s29
	s_barrier
	ds_read_b128 v[166:169], v148 offset:49152
	ds_read_b128 v[170:173], v148 offset:50176
	ds_read_b128 v[174:177], v148 offset:51200
	ds_read_b128 v[178:181], v148 offset:52224
	ds_read_b128 v[182:185], v148 offset:53248
	ds_read_b128 v[186:189], v148 offset:54272
	ds_read_b128 v[190:193], v148 offset:55296
	ds_read_b128 v[194:197], v148 offset:56320
	s_add_u32 s100, s98, 0x80
	s_addc_u32 s101, s99, 0
	global_load_lds_dwordx4 v134, s[100:101]
	s_mov_b32 m0, s30
	s_nop 0
	s_add_u32 s100, s98, 0x80
	s_addc_u32 s101, s99, 0
	global_load_lds_dwordx4 v130, s[100:101]
	s_barrier
	s_waitcnt lgkmcnt(0)
	s_waitcnt lgkmcnt(0)
	v_mfma_f32_16x16x32_bf16 v[60:63], v[150:153], v[166:169], v[60:63]
	v_mfma_f32_16x16x32_bf16 v[56:59], v[158:161], v[166:169], v[56:59]
	v_mfma_f32_16x16x32_bf16 v[52:55], v[150:153], v[174:177], v[52:55]
	v_mfma_f32_16x16x32_bf16 v[48:51], v[158:161], v[174:177], v[48:51]
	v_mfma_f32_16x16x32_bf16 v[36:39], v[150:153], v[182:185], v[36:39]
	v_mfma_f32_16x16x32_bf16 v[32:35], v[158:161], v[182:185], v[32:35]
	v_mfma_f32_16x16x32_bf16 v[20:23], v[150:153], v[190:193], v[20:23]
	v_mfma_f32_16x16x32_bf16 v[16:19], v[158:161], v[190:193], v[16:19]
	v_mfma_f32_16x16x32_bf16 v[60:63], v[154:157], v[170:173], v[60:63]
	v_mfma_f32_16x16x32_bf16 v[56:59], v[162:165], v[170:173], v[56:59]
	v_mfma_f32_16x16x32_bf16 v[52:55], v[154:157], v[178:181], v[52:55]
	v_mfma_f32_16x16x32_bf16 v[48:51], v[162:165], v[178:181], v[48:51]
	v_mfma_f32_16x16x32_bf16 v[36:39], v[154:157], v[186:189], v[36:39]
	v_mfma_f32_16x16x32_bf16 v[32:35], v[162:165], v[186:189], v[32:35]
	v_mfma_f32_16x16x32_bf16 v[20:23], v[154:157], v[194:197], v[20:23]
	v_mfma_f32_16x16x32_bf16 v[16:19], v[162:165], v[194:197], v[16:19]
	s_barrier
	s_add_u32 s18, s18, 0x20080
	s_addc_u32 s19, s19, 0
	s_add_i32 s20, s20, s23
	s_mov_b32 m0, s20
	s_nop 0
	global_load_lds_dwordx4 v132, s[18:19]
	s_add_i32 m0, s20, 0x2000
	s_nop 0
	global_load_lds_dwordx4 v128, s[18:19]
	s_waitcnt vmcnt(6)
	s_barrier
	v_mfma_f32_16x16x32_bf16 v[44:47], v[198:201], v[166:169], v[44:47]
	v_mfma_f32_16x16x32_bf16 v[40:43], v[208:211], v[166:169], v[40:43]
	v_mfma_f32_16x16x32_bf16 v[28:31], v[198:201], v[174:177], v[28:31]
	v_mfma_f32_16x16x32_bf16 v[24:27], v[208:211], v[174:177], v[24:27]
	v_mfma_f32_16x16x32_bf16 v[12:15], v[198:201], v[182:185], v[12:15]
	v_mfma_f32_16x16x32_bf16 v[8:11], v[208:211], v[182:185], v[8:11]
	v_mfma_f32_16x16x32_bf16 v[4:7], v[198:201], v[190:193], v[4:7]
	v_mfma_f32_16x16x32_bf16 v[0:3], v[208:211], v[190:193], v[0:3]
	v_mfma_f32_16x16x32_bf16 v[44:47], v[204:207], v[170:173], v[44:47]
	v_mfma_f32_16x16x32_bf16 v[40:43], v[212:215], v[170:173], v[40:43]
	v_mfma_f32_16x16x32_bf16 v[28:31], v[204:207], v[178:181], v[28:31]
	v_mfma_f32_16x16x32_bf16 v[24:27], v[212:215], v[178:181], v[24:27]
	v_mfma_f32_16x16x32_bf16 v[12:15], v[204:207], v[186:189], v[12:15]
	v_mfma_f32_16x16x32_bf16 v[8:11], v[212:215], v[186:189], v[8:11]
	v_mfma_f32_16x16x32_bf16 v[4:7], v[204:207], v[194:197], v[4:7]
	v_mfma_f32_16x16x32_bf16 v[0:3], v[212:215], v[194:197], v[0:3]
	s_add_i32 s40, s40, 2
	s_add_u32 s16, s16, 0x100
	s_addc_u32 s17, s17, 0
	s_add_u32 s38, s38, 0x100
	s_addc_u32 s39, s39, 0
	s_cmp_gt_u32 s40, 29
	s_barrier
	s_cbranch_scc0 .LBB0_154
	v_readlane_b32 s100, v248, 63
	v_readlane_b32 s101, v247, 0
	v_and_b32_e32 v242, 15, v202
	v_bfe_u32 v243, v202, 4, 2
	v_bfe_u32 v244, v202, 6, 2
	v_lshrrev_b32_e32 v245, 8, v202
	v_and_b32_e32 v240, 7, v242
	v_lshl_add_u32 v240, v245, 6, v240
	v_lshl_add_u32 v240, s6, 8, v240
	v_mul_u32_u24_e32 v240, 0x3000, v240
	v_lshrrev_b32_e32 v241, 3, v242
	v_lshlrev_b32_e32 v241, 6, v241
	v_lshl_add_u32 v241, v244, 7, v241
	v_lshl_add_u32 v241, v243, 4, v241
	v_add_u32_e32 v240, v240, v241
	s_lshl_b32 s98, s35, 9
	v_add_u32_e32 v240, s98, v240
	v_cvt_pk_bf16_f32 v228, v124, v125
	v_cvt_pk_bf16_f32 v229, v126, v127
	v_cvt_pk_bf16_f32 v230, v120, v121
	v_cvt_pk_bf16_f32 v231, v122, v123
	v_cvt_pk_bf16_f32 v232, v108, v109
	v_cvt_pk_bf16_f32 v233, v110, v111
	v_cvt_pk_bf16_f32 v234, v104, v105
	v_cvt_pk_bf16_f32 v235, v106, v107
	v_mov_b32_e32 v236, v228
	v_mov_b32_e32 v237, v229
	v_mov_b32_e32 v238, v230
	v_mov_b32_e32 v239, v231
	v_mov_b32_dpp v228, v232 row_ror:8 row_mask:0xf bank_mask:0xc
	v_mov_b32_dpp v229, v233 row_ror:8 row_mask:0xf bank_mask:0xc
	v_mov_b32_dpp v230, v234 row_ror:8 row_mask:0xf bank_mask:0xc
	v_mov_b32_dpp v231, v235 row_ror:8 row_mask:0xf bank_mask:0xc
	v_mov_b32_dpp v232, v236 row_ror:8 row_mask:0xf bank_mask:0x3
	v_mov_b32_dpp v233, v237 row_ror:8 row_mask:0xf bank_mask:0x3
	v_mov_b32_dpp v234, v238 row_ror:8 row_mask:0xf bank_mask:0x3
	v_mov_b32_dpp v235, v239 row_ror:8 row_mask:0xf bank_mask:0x3
	global_store_dwordx4 v240, v[228:231], s[100:101]
	s_add_u32 s100, s100, 0x18000
	s_addc_u32 s101, s101, 0
	global_store_dwordx4 v240, v[232:235], s[100:101]
	v_cvt_pk_bf16_f32 v228, v116, v117
	v_cvt_pk_bf16_f32 v229, v118, v119
	v_cvt_pk_bf16_f32 v230, v112, v113
	v_cvt_pk_bf16_f32 v231, v114, v115
	v_cvt_pk_bf16_f32 v232, v92, v93
	v_cvt_pk_bf16_f32 v233, v94, v95
	v_cvt_pk_bf16_f32 v234, v88, v89
	v_cvt_pk_bf16_f32 v235, v90, v91
	v_mov_b32_e32 v236, v228
	v_mov_b32_e32 v237, v229
	v_mov_b32_e32 v238, v230
	v_mov_b32_e32 v239, v231
	v_mov_b32_dpp v228, v232 row_ror:8 row_mask:0xf bank_mask:0xc
	v_mov_b32_dpp v229, v233 row_ror:8 row_mask:0xf bank_mask:0xc
	v_mov_b32_dpp v230, v234 row_ror:8 row_mask:0xf bank_mask:0xc
	v_mov_b32_dpp v231, v235 row_ror:8 row_mask:0xf bank_mask:0xc
	v_mov_b32_dpp v232, v236 row_ror:8 row_mask:0xf bank_mask:0x3
	v_mov_b32_dpp v233, v237 row_ror:8 row_mask:0xf bank_mask:0x3
	v_mov_b32_dpp v234, v238 row_ror:8 row_mask:0xf bank_mask:0x3
	v_mov_b32_dpp v235, v239 row_ror:8 row_mask:0xf bank_mask:0x3
	s_add_u32 s100, s100, 0x18000
	s_addc_u32 s101, s101, 0
	global_store_dwordx4 v240, v[228:231], s[100:101]
	s_add_u32 s100, s100, 0x18000
	s_addc_u32 s101, s101, 0
	global_store_dwordx4 v240, v[232:235], s[100:101]
	v_cvt_pk_bf16_f32 v228, v100, v101
	v_cvt_pk_bf16_f32 v229, v102, v103
	v_cvt_pk_bf16_f32 v230, v96, v97
	v_cvt_pk_bf16_f32 v231, v98, v99
	v_cvt_pk_bf16_f32 v232, v76, v77
	v_cvt_pk_bf16_f32 v233, v78, v79
	v_cvt_pk_bf16_f32 v234, v72, v73
	v_cvt_pk_bf16_f32 v235, v74, v75
	v_mov_b32_e32 v236, v228
	v_mov_b32_e32 v237, v229
	v_mov_b32_e32 v238, v230
	v_mov_b32_e32 v239, v231
	v_mov_b32_dpp v228, v232 row_ror:8 row_mask:0xf bank_mask:0xc
	v_mov_b32_dpp v229, v233 row_ror:8 row_mask:0xf bank_mask:0xc
	v_mov_b32_dpp v230, v234 row_ror:8 row_mask:0xf bank_mask:0xc
	v_mov_b32_dpp v231, v235 row_ror:8 row_mask:0xf bank_mask:0xc
	v_mov_b32_dpp v232, v236 row_ror:8 row_mask:0xf bank_mask:0x3
	v_mov_b32_dpp v233, v237 row_ror:8 row_mask:0xf bank_mask:0x3
	v_mov_b32_dpp v234, v238 row_ror:8 row_mask:0xf bank_mask:0x3
	v_mov_b32_dpp v235, v239 row_ror:8 row_mask:0xf bank_mask:0x3
	s_add_u32 s100, s100, 0x18000
	s_addc_u32 s101, s101, 0
	global_store_dwordx4 v240, v[228:231], s[100:101]
	s_add_u32 s100, s100, 0x18000
	s_addc_u32 s101, s101, 0
	global_store_dwordx4 v240, v[232:235], s[100:101]
	v_cvt_pk_bf16_f32 v228, v84, v85
	v_cvt_pk_bf16_f32 v229, v86, v87
	v_cvt_pk_bf16_f32 v230, v80, v81
	v_cvt_pk_bf16_f32 v231, v82, v83
	v_cvt_pk_bf16_f32 v232, v68, v69
	v_cvt_pk_bf16_f32 v233, v70, v71
	v_cvt_pk_bf16_f32 v234, v64, v65
	v_cvt_pk_bf16_f32 v235, v66, v67
	v_mov_b32_e32 v236, v228
	v_mov_b32_e32 v237, v229
	v_mov_b32_e32 v238, v230
	v_mov_b32_e32 v239, v231
	v_mov_b32_dpp v228, v232 row_ror:8 row_mask:0xf bank_mask:0xc
	v_mov_b32_dpp v229, v233 row_ror:8 row_mask:0xf bank_mask:0xc
	v_mov_b32_dpp v230, v234 row_ror:8 row_mask:0xf bank_mask:0xc
	v_mov_b32_dpp v231, v235 row_ror:8 row_mask:0xf bank_mask:0xc
	v_mov_b32_dpp v232, v236 row_ror:8 row_mask:0xf bank_mask:0x3
	v_mov_b32_dpp v233, v237 row_ror:8 row_mask:0xf bank_mask:0x3
	v_mov_b32_dpp v234, v238 row_ror:8 row_mask:0xf bank_mask:0x3
	v_mov_b32_dpp v235, v239 row_ror:8 row_mask:0xf bank_mask:0x3
	s_add_u32 s100, s100, 0x18000
	s_addc_u32 s101, s101, 0
	global_store_dwordx4 v240, v[228:231], s[100:101]
	s_add_u32 s100, s100, 0x18000
	s_addc_u32 s101, s101, 0
	global_store_dwordx4 v240, v[232:235], s[100:101]
	v_cvt_pk_bf16_f32 v228, v60, v61
	v_cvt_pk_bf16_f32 v229, v62, v63
	v_cvt_pk_bf16_f32 v230, v56, v57
	v_cvt_pk_bf16_f32 v231, v58, v59
	v_cvt_pk_bf16_f32 v232, v44, v45
	v_cvt_pk_bf16_f32 v233, v46, v47
	v_cvt_pk_bf16_f32 v234, v40, v41
	v_cvt_pk_bf16_f32 v235, v42, v43
	v_mov_b32_e32 v236, v228
	v_mov_b32_e32 v237, v229
	v_mov_b32_e32 v238, v230
	v_mov_b32_e32 v239, v231
	v_mov_b32_dpp v228, v232 row_ror:8 row_mask:0xf bank_mask:0xc
	v_mov_b32_dpp v229, v233 row_ror:8 row_mask:0xf bank_mask:0xc
	v_mov_b32_dpp v230, v234 row_ror:8 row_mask:0xf bank_mask:0xc
	v_mov_b32_dpp v231, v235 row_ror:8 row_mask:0xf bank_mask:0xc
	v_mov_b32_dpp v232, v236 row_ror:8 row_mask:0xf bank_mask:0x3
	v_mov_b32_dpp v233, v237 row_ror:8 row_mask:0xf bank_mask:0x3
	v_mov_b32_dpp v234, v238 row_ror:8 row_mask:0xf bank_mask:0x3
	v_mov_b32_dpp v235, v239 row_ror:8 row_mask:0xf bank_mask:0x3
	s_add_u32 s100, s100, 0xd8000
	s_addc_u32 s101, s101, 0
	global_store_dwordx4 v240, v[228:231], s[100:101]
	s_add_u32 s100, s100, 0x18000
	s_addc_u32 s101, s101, 0
	global_store_dwordx4 v240, v[232:235], s[100:101]
	v_cvt_pk_bf16_f32 v228, v52, v53
	v_cvt_pk_bf16_f32 v229, v54, v55
	v_cvt_pk_bf16_f32 v230, v48, v49
	v_cvt_pk_bf16_f32 v231, v50, v51
	v_cvt_pk_bf16_f32 v232, v28, v29
	v_cvt_pk_bf16_f32 v233, v30, v31
	v_cvt_pk_bf16_f32 v234, v24, v25
	v_cvt_pk_bf16_f32 v235, v26, v27
	v_mov_b32_e32 v236, v228
	v_mov_b32_e32 v237, v229
	v_mov_b32_e32 v238, v230
	v_mov_b32_e32 v239, v231
	v_mov_b32_dpp v228, v232 row_ror:8 row_mask:0xf bank_mask:0xc
	v_mov_b32_dpp v229, v233 row_ror:8 row_mask:0xf bank_mask:0xc
	v_mov_b32_dpp v230, v234 row_ror:8 row_mask:0xf bank_mask:0xc
	v_mov_b32_dpp v231, v235 row_ror:8 row_mask:0xf bank_mask:0xc
	v_mov_b32_dpp v232, v236 row_ror:8 row_mask:0xf bank_mask:0x3
	v_mov_b32_dpp v233, v237 row_ror:8 row_mask:0xf bank_mask:0x3
	v_mov_b32_dpp v234, v238 row_ror:8 row_mask:0xf bank_mask:0x3
	v_mov_b32_dpp v235, v239 row_ror:8 row_mask:0xf bank_mask:0x3
	s_add_u32 s100, s100, 0x18000
	s_addc_u32 s101, s101, 0
	global_store_dwordx4 v240, v[228:231], s[100:101]
	s_add_u32 s100, s100, 0x18000
	s_addc_u32 s101, s101, 0
	global_store_dwordx4 v240, v[232:235], s[100:101]
	v_cvt_pk_bf16_f32 v228, v36, v37
	v_cvt_pk_bf16_f32 v229, v38, v39
	v_cvt_pk_bf16_f32 v230, v32, v33
	v_cvt_pk_bf16_f32 v231, v34, v35
	v_cvt_pk_bf16_f32 v232, v12, v13
	v_cvt_pk_bf16_f32 v233, v14, v15
	v_cvt_pk_bf16_f32 v234, v8, v9
	v_cvt_pk_bf16_f32 v235, v10, v11
	v_mov_b32_e32 v236, v228
	v_mov_b32_e32 v237, v229
	v_mov_b32_e32 v238, v230
	v_mov_b32_e32 v239, v231
	v_mov_b32_dpp v228, v232 row_ror:8 row_mask:0xf bank_mask:0xc
	v_mov_b32_dpp v229, v233 row_ror:8 row_mask:0xf bank_mask:0xc
	v_mov_b32_dpp v230, v234 row_ror:8 row_mask:0xf bank_mask:0xc
	v_mov_b32_dpp v231, v235 row_ror:8 row_mask:0xf bank_mask:0xc
	v_mov_b32_dpp v232, v236 row_ror:8 row_mask:0xf bank_mask:0x3
	v_mov_b32_dpp v233, v237 row_ror:8 row_mask:0xf bank_mask:0x3
	v_mov_b32_dpp v234, v238 row_ror:8 row_mask:0xf bank_mask:0x3
	v_mov_b32_dpp v235, v239 row_ror:8 row_mask:0xf bank_mask:0x3
	s_add_u32 s100, s100, 0x18000
	s_addc_u32 s101, s101, 0
	global_store_dwordx4 v240, v[228:231], s[100:101]
	s_add_u32 s100, s100, 0x18000
	s_addc_u32 s101, s101, 0
	global_store_dwordx4 v240, v[232:235], s[100:101]
	v_cvt_pk_bf16_f32 v228, v20, v21
	v_cvt_pk_bf16_f32 v229, v22, v23
	v_cvt_pk_bf16_f32 v230, v16, v17
	v_cvt_pk_bf16_f32 v231, v18, v19
	v_cvt_pk_bf16_f32 v232, v4, v5
	v_cvt_pk_bf16_f32 v233, v6, v7
	v_cvt_pk_bf16_f32 v234, v0, v1
	v_cvt_pk_bf16_f32 v235, v2, v3
	v_mov_b32_e32 v236, v228
	v_mov_b32_e32 v237, v229
	v_mov_b32_e32 v238, v230
	v_mov_b32_e32 v239, v231
	v_mov_b32_dpp v228, v232 row_ror:8 row_mask:0xf bank_mask:0xc
	v_mov_b32_dpp v229, v233 row_ror:8 row_mask:0xf bank_mask:0xc
	v_mov_b32_dpp v230, v234 row_ror:8 row_mask:0xf bank_mask:0xc
	v_mov_b32_dpp v231, v235 row_ror:8 row_mask:0xf bank_mask:0xc
	v_mov_b32_dpp v232, v236 row_ror:8 row_mask:0xf bank_mask:0x3
	v_mov_b32_dpp v233, v237 row_ror:8 row_mask:0xf bank_mask:0x3
	v_mov_b32_dpp v234, v238 row_ror:8 row_mask:0xf bank_mask:0x3
	v_mov_b32_dpp v235, v239 row_ror:8 row_mask:0xf bank_mask:0x3
	s_add_u32 s100, s100, 0x18000
	s_addc_u32 s101, s101, 0
	global_store_dwordx4 v240, v[228:231], s[100:101]
	s_add_u32 s100, s100, 0x18000
	s_addc_u32 s101, s101, 0
	global_store_dwordx4 v240, v[232:235], s[100:101]
	s_and_b64 vcc, exec, s[2:3]
	s_mov_b32 s35, s8
	s_mov_b32 s6, s10
	s_mov_b64 s[18:19], s[14:15]
	s_mov_b64 s[16:17], s[12:13]
	s_cbranch_vccz .LBB0_151
	s_waitcnt vmcnt(0)
	s_cmpk_gt_u32 s22, 0xff
	s_cbranch_scc1 .LBB0_158
	s_barrier

.LBB0_368:
	ds_read_b128 v[146:149], v143
	ds_read_b128 v[150:153], v143 offset:1024
	ds_read_b128 v[154:157], v143 offset:2048
	ds_read_b128 v[158:161], v143 offset:3072
	s_add_i32 s52, s26, 2
	s_add_u32 s27, s24, 0xfff80080
	s_addc_u32 s28, s25, -1
	s_cmp_eq_u32 s49, s26
	s_cselect_b32 s26, s48, s50
	s_cselect_b32 s29, s7, s28
	s_cselect_b32 s28, s9, s27
	s_cselect_b32 s27, s47, s51
	s_add_i32 m0, s1, 0xc000
	ds_read_b128 v[162:165], v144
	ds_read_b128 v[166:169], v144 offset:1024
	ds_read_b128 v[170:173], v144 offset:2048
	ds_read_b128 v[174:177], v144 offset:3072
	ds_read_b128 v[178:181], v144 offset:4096
	ds_read_b128 v[182:185], v144 offset:5120
	ds_read_b128 v[186:189], v144 offset:6144
	ds_read_b128 v[190:193], v144 offset:7168
	global_load_lds_dwordx4 v136, s[24:25]
	s_add_i32 m0, s1, 0xe000
	s_nop 0
	global_load_lds_dwordx4 v138, s[24:25]
	s_waitcnt lgkmcnt(8)
	s_barrier
	s_waitcnt lgkmcnt(0)
	s_waitcnt lgkmcnt(0)
	v_mfma_f32_16x16x32_bf16 v[124:127], v[146:149], v[162:165], v[124:127]
	v_mfma_f32_16x16x32_bf16 v[120:123], v[154:157], v[162:165], v[120:123]
	v_mfma_f32_16x16x32_bf16 v[108:111], v[146:149], v[170:173], v[108:111]
	v_mfma_f32_16x16x32_bf16 v[104:107], v[154:157], v[170:173], v[104:107]
	v_mfma_f32_16x16x32_bf16 v[92:95], v[146:149], v[178:181], v[92:95]
	v_mfma_f32_16x16x32_bf16 v[88:91], v[154:157], v[178:181], v[88:91]
	v_mfma_f32_16x16x32_bf16 v[76:79], v[146:149], v[186:189], v[76:79]
	v_mfma_f32_16x16x32_bf16 v[72:75], v[154:157], v[186:189], v[72:75]
	v_mfma_f32_16x16x32_bf16 v[124:127], v[150:153], v[166:169], v[124:127]
	v_mfma_f32_16x16x32_bf16 v[120:123], v[158:161], v[166:169], v[120:123]
	v_mfma_f32_16x16x32_bf16 v[108:111], v[150:153], v[174:177], v[108:111]
	v_mfma_f32_16x16x32_bf16 v[104:107], v[158:161], v[174:177], v[104:107]
	v_mfma_f32_16x16x32_bf16 v[92:95], v[150:153], v[182:185], v[92:95]
	v_mfma_f32_16x16x32_bf16 v[88:91], v[158:161], v[182:185], v[88:91]
	v_mfma_f32_16x16x32_bf16 v[76:79], v[150:153], v[190:193], v[76:79]
	v_mfma_f32_16x16x32_bf16 v[72:75], v[158:161], v[190:193], v[72:75]
	s_barrier
	s_add_i32 s53, s42, s31
	s_mov_b32 m0, s53
	ds_read_b128 v[194:197], v145
	ds_read_b128 v[198:201], v145 offset:1024
	ds_read_b128 v[204:207], v145 offset:2048
	ds_read_b128 v[208:211], v145 offset:3072
	global_load_lds_dwordx4 v132, s[26:27]
	s_add_i32 m0, s53, 0x2000
	s_nop 0
	global_load_lds_dwordx4 v128, s[26:27]
	s_barrier
	s_waitcnt lgkmcnt(0)
	s_waitcnt lgkmcnt(0)
	v_mfma_f32_16x16x32_bf16 v[116:119], v[194:197], v[162:165], v[116:119]
	v_mfma_f32_16x16x32_bf16 v[112:115], v[204:207], v[162:165], v[112:115]
	v_mfma_f32_16x16x32_bf16 v[100:103], v[194:197], v[170:173], v[100:103]
	v_mfma_f32_16x16x32_bf16 v[96:99], v[204:207], v[170:173], v[96:99]
	v_mfma_f32_16x16x32_bf16 v[84:87], v[194:197], v[178:181], v[84:87]
	v_mfma_f32_16x16x32_bf16 v[80:83], v[204:207], v[178:181], v[80:83]
	v_mfma_f32_16x16x32_bf16 v[68:71], v[194:197], v[186:189], v[68:71]
	v_mfma_f32_16x16x32_bf16 v[64:67], v[204:207], v[186:189], v[64:67]
	v_mfma_f32_16x16x32_bf16 v[116:119], v[198:201], v[166:169], v[116:119]
	v_mfma_f32_16x16x32_bf16 v[112:115], v[208:211], v[166:169], v[112:115]
	v_mfma_f32_16x16x32_bf16 v[100:103], v[198:201], v[174:177], v[100:103]
	v_mfma_f32_16x16x32_bf16 v[96:99], v[208:211], v[174:177], v[96:99]
	v_mfma_f32_16x16x32_bf16 v[84:87], v[198:201], v[182:185], v[84:87]
	v_mfma_f32_16x16x32_bf16 v[80:83], v[208:211], v[182:185], v[80:83]
	v_mfma_f32_16x16x32_bf16 v[68:71], v[198:201], v[190:193], v[68:71]
	v_mfma_f32_16x16x32_bf16 v[64:67], v[208:211], v[190:193], v[64:67]
	s_mov_b32 m0, s1
	s_mov_b64 s[98:99], s[28:29]
	s_barrier
	ds_read_b128 v[162:165], v144 offset:16384
	ds_read_b128 v[166:169], v144 offset:17408
	ds_read_b128 v[170:173], v144 offset:18432
	ds_read_b128 v[174:177], v144 offset:19456
	ds_read_b128 v[178:181], v144 offset:20480
	ds_read_b128 v[182:185], v144 offset:21504
	ds_read_b128 v[186:189], v144 offset:22528
	ds_read_b128 v[190:193], v144 offset:23552
	global_load_lds_dwordx4 v134, s[28:29]
	s_mov_b32 m0, s33
	s_nop 0
	global_load_lds_dwordx4 v130, s[28:29]
	s_barrier
	s_waitcnt lgkmcnt(0)
	s_waitcnt lgkmcnt(0)
	v_mfma_f32_16x16x32_bf16 v[60:63], v[146:149], v[162:165], v[60:63]
	v_mfma_f32_16x16x32_bf16 v[56:59], v[154:157], v[162:165], v[56:59]
	v_mfma_f32_16x16x32_bf16 v[44:47], v[146:149], v[170:173], v[44:47]
	v_mfma_f32_16x16x32_bf16 v[40:43], v[154:157], v[170:173], v[40:43]
	v_mfma_f32_16x16x32_bf16 v[28:31], v[146:149], v[178:181], v[28:31]
	v_mfma_f32_16x16x32_bf16 v[24:27], v[154:157], v[178:181], v[24:27]
	v_mfma_f32_16x16x32_bf16 v[12:15], v[146:149], v[186:189], v[12:15]
	v_mfma_f32_16x16x32_bf16 v[8:11], v[154:157], v[186:189], v[8:11]
	v_mfma_f32_16x16x32_bf16 v[60:63], v[150:153], v[166:169], v[60:63]
	v_mfma_f32_16x16x32_bf16 v[56:59], v[158:161], v[166:169], v[56:59]
	v_mfma_f32_16x16x32_bf16 v[44:47], v[150:153], v[174:177], v[44:47]
	v_mfma_f32_16x16x32_bf16 v[40:43], v[158:161], v[174:177], v[40:43]
	v_mfma_f32_16x16x32_bf16 v[28:31], v[150:153], v[182:185], v[28:31]
	v_mfma_f32_16x16x32_bf16 v[24:27], v[158:161], v[182:185], v[24:27]
	v_mfma_f32_16x16x32_bf16 v[12:15], v[150:153], v[190:193], v[12:15]
	v_mfma_f32_16x16x32_bf16 v[8:11], v[158:161], v[190:193], v[8:11]
	s_barrier
	s_add_u32 s54, s26, 0x20000
	s_addc_u32 s55, s27, 0
	s_add_i32 s53, s43, s31
	s_mov_b32 m0, s53
	s_nop 0
	global_load_lds_dwordx4 v132, s[54:55]
	s_add_i32 m0, s53, 0x2000
	s_nop 0
	global_load_lds_dwordx4 v128, s[54:55]
	s_waitcnt vmcnt(6)
	s_barrier
	v_mfma_f32_16x16x32_bf16 v[52:55], v[194:197], v[162:165], v[52:55]
	v_mfma_f32_16x16x32_bf16 v[48:51], v[204:207], v[162:165], v[48:51]
	v_mfma_f32_16x16x32_bf16 v[36:39], v[194:197], v[170:173], v[36:39]
	v_mfma_f32_16x16x32_bf16 v[32:35], v[204:207], v[170:173], v[32:35]
	v_mfma_f32_16x16x32_bf16 v[20:23], v[194:197], v[178:181], v[20:23]
	v_mfma_f32_16x16x32_bf16 v[16:19], v[204:207], v[178:181], v[16:19]
	v_mfma_f32_16x16x32_bf16 v[4:7], v[194:197], v[186:189], v[4:7]
	v_mfma_f32_16x16x32_bf16 v[0:3], v[204:207], v[186:189], v[0:3]
	v_mfma_f32_16x16x32_bf16 v[52:55], v[198:201], v[166:169], v[52:55]
	v_mfma_f32_16x16x32_bf16 v[48:51], v[208:211], v[166:169], v[48:51]
	v_mfma_f32_16x16x32_bf16 v[36:39], v[198:201], v[174:177], v[36:39]
	v_mfma_f32_16x16x32_bf16 v[32:35], v[208:211], v[174:177], v[32:35]
	v_mfma_f32_16x16x32_bf16 v[20:23], v[198:201], v[182:185], v[20:23]
	v_mfma_f32_16x16x32_bf16 v[16:19], v[208:211], v[182:185], v[16:19]
	v_mfma_f32_16x16x32_bf16 v[4:7], v[198:201], v[190:193], v[4:7]
	v_mfma_f32_16x16x32_bf16 v[0:3], v[208:211], v[190:193], v[0:3]
	s_add_i32 s53, 0, 0x18000
	v_add_u32_e32 v158, s53, v141
	s_barrier
	ds_read_b128 v[146:149], v158
	ds_read_b128 v[150:153], v158 offset:1024
	ds_read_b128 v[154:157], v158 offset:2048
	ds_read_b128 v[158:161], v158 offset:3072
	s_add_u32 s28, s28, 0x80000
	s_addc_u32 s29, s29, 0
	s_mov_b32 m0, s34
	ds_read_b128 v[162:165], v144 offset:32768
	ds_read_b128 v[166:169], v144 offset:33792
	ds_read_b128 v[170:173], v144 offset:34816
	ds_read_b128 v[174:177], v144 offset:35840
	ds_read_b128 v[178:181], v144 offset:36864
	ds_read_b128 v[182:185], v144 offset:37888
	ds_read_b128 v[186:189], v144 offset:38912
	ds_read_b128 v[190:193], v144 offset:39936
	global_load_lds_dwordx4 v134, s[28:29]
	s_mov_b32 m0, s35
	s_nop 0
	global_load_lds_dwordx4 v130, s[28:29]
	s_waitcnt lgkmcnt(8)
	s_barrier
	s_waitcnt lgkmcnt(0)
	s_waitcnt lgkmcnt(0)
	v_mfma_f32_16x16x32_bf16 v[124:127], v[146:149], v[162:165], v[124:127]
	v_mfma_f32_16x16x32_bf16 v[120:123], v[154:157], v[162:165], v[120:123]
	v_mfma_f32_16x16x32_bf16 v[108:111], v[146:149], v[170:173], v[108:111]
	v_mfma_f32_16x16x32_bf16 v[104:107], v[154:157], v[170:173], v[104:107]
	v_mfma_f32_16x16x32_bf16 v[92:95], v[146:149], v[178:181], v[92:95]
	v_mfma_f32_16x16x32_bf16 v[88:91], v[154:157], v[178:181], v[88:91]
	v_mfma_f32_16x16x32_bf16 v[76:79], v[146:149], v[186:189], v[76:79]
	v_mfma_f32_16x16x32_bf16 v[72:75], v[154:157], v[186:189], v[72:75]
	v_mfma_f32_16x16x32_bf16 v[124:127], v[150:153], v[166:169], v[124:127]
	v_mfma_f32_16x16x32_bf16 v[120:123], v[158:161], v[166:169], v[120:123]
	v_mfma_f32_16x16x32_bf16 v[108:111], v[150:153], v[174:177], v[108:111]
	v_mfma_f32_16x16x32_bf16 v[104:107], v[158:161], v[174:177], v[104:107]
	v_mfma_f32_16x16x32_bf16 v[92:95], v[150:153], v[182:185], v[92:95]
	v_mfma_f32_16x16x32_bf16 v[88:91], v[158:161], v[182:185], v[88:91]
	v_mfma_f32_16x16x32_bf16 v[76:79], v[150:153], v[190:193], v[76:79]
	v_mfma_f32_16x16x32_bf16 v[72:75], v[158:161], v[190:193], v[72:75]
	s_barrier
	s_add_i32 s28, 0, 0x1c000
	s_add_i32 s29, s53, s31
	v_add_u32_e32 v208, s28, v141
	s_mov_b32 m0, s29
	ds_read_b128 v[194:197], v208
	ds_read_b128 v[198:201], v208 offset:1024
	ds_read_b128 v[204:207], v208 offset:2048
	ds_read_b128 v[208:211], v208 offset:3072
	s_add_u32 s100, s26, 0x80
	s_addc_u32 s101, s27, 0
	global_load_lds_dwordx4 v132, s[100:101]
	s_add_i32 m0, s29, 0x2000
	s_nop 0
	s_add_u32 s100, s26, 0x80
	s_addc_u32 s101, s27, 0
	global_load_lds_dwordx4 v128, s[100:101]
	s_barrier
	s_waitcnt lgkmcnt(0)
	s_waitcnt lgkmcnt(0)
	v_mfma_f32_16x16x32_bf16 v[116:119], v[194:197], v[162:165], v[116:119]
	v_mfma_f32_16x16x32_bf16 v[112:115], v[204:207], v[162:165], v[112:115]
	v_mfma_f32_16x16x32_bf16 v[100:103], v[194:197], v[170:173], v[100:103]
	v_mfma_f32_16x16x32_bf16 v[96:99], v[204:207], v[170:173], v[96:99]
	v_mfma_f32_16x16x32_bf16 v[84:87], v[194:197], v[178:181], v[84:87]
	v_mfma_f32_16x16x32_bf16 v[80:83], v[204:207], v[178:181], v[80:83]
	v_mfma_f32_16x16x32_bf16 v[68:71], v[194:197], v[186:189], v[68:71]
	v_mfma_f32_16x16x32_bf16 v[64:67], v[204:207], v[186:189], v[64:67]
	v_mfma_f32_16x16x32_bf16 v[116:119], v[198:201], v[166:169], v[116:119]
	v_mfma_f32_16x16x32_bf16 v[112:115], v[208:211], v[166:169], v[112:115]
	v_mfma_f32_16x16x32_bf16 v[100:103], v[198:201], v[174:177], v[100:103]
	v_mfma_f32_16x16x32_bf16 v[96:99], v[208:211], v[174:177], v[96:99]
	v_mfma_f32_16x16x32_bf16 v[84:87], v[198:201], v[182:185], v[84:87]
	v_mfma_f32_16x16x32_bf16 v[80:83], v[208:211], v[182:185], v[80:83]
	v_mfma_f32_16x16x32_bf16 v[68:71], v[198:201], v[190:193], v[68:71]
	v_mfma_f32_16x16x32_bf16 v[64:67], v[208:211], v[190:193], v[64:67]
	s_mov_b32 m0, s40
	s_barrier
	ds_read_b128 v[162:165], v144 offset:49152
	ds_read_b128 v[166:169], v144 offset:50176
	ds_read_b128 v[170:173], v144 offset:51200
	ds_read_b128 v[174:177], v144 offset:52224
	ds_read_b128 v[178:181], v144 offset:53248
	ds_read_b128 v[182:185], v144 offset:54272
	ds_read_b128 v[186:189], v144 offset:55296
	ds_read_b128 v[190:193], v144 offset:56320
	s_add_u32 s100, s98, 0x80
	s_addc_u32 s101, s99, 0
	global_load_lds_dwordx4 v134, s[100:101]
	s_mov_b32 m0, s41
	s_nop 0
	s_add_u32 s100, s98, 0x80
	s_addc_u32 s101, s99, 0
	global_load_lds_dwordx4 v130, s[100:101]
	s_barrier
	s_waitcnt lgkmcnt(0)
	s_waitcnt lgkmcnt(0)
	v_mfma_f32_16x16x32_bf16 v[60:63], v[146:149], v[162:165], v[60:63]
	v_mfma_f32_16x16x32_bf16 v[56:59], v[154:157], v[162:165], v[56:59]
	v_mfma_f32_16x16x32_bf16 v[44:47], v[146:149], v[170:173], v[44:47]
	v_mfma_f32_16x16x32_bf16 v[40:43], v[154:157], v[170:173], v[40:43]
	v_mfma_f32_16x16x32_bf16 v[28:31], v[146:149], v[178:181], v[28:31]
	v_mfma_f32_16x16x32_bf16 v[24:27], v[154:157], v[178:181], v[24:27]
	v_mfma_f32_16x16x32_bf16 v[12:15], v[146:149], v[186:189], v[12:15]
	v_mfma_f32_16x16x32_bf16 v[8:11], v[154:157], v[186:189], v[8:11]
	v_mfma_f32_16x16x32_bf16 v[60:63], v[150:153], v[166:169], v[60:63]
	v_mfma_f32_16x16x32_bf16 v[56:59], v[158:161], v[166:169], v[56:59]
	v_mfma_f32_16x16x32_bf16 v[44:47], v[150:153], v[174:177], v[44:47]
	v_mfma_f32_16x16x32_bf16 v[40:43], v[158:161], v[174:177], v[40:43]
	v_mfma_f32_16x16x32_bf16 v[28:31], v[150:153], v[182:185], v[28:31]
	v_mfma_f32_16x16x32_bf16 v[24:27], v[158:161], v[182:185], v[24:27]
	v_mfma_f32_16x16x32_bf16 v[12:15], v[150:153], v[190:193], v[12:15]
	v_mfma_f32_16x16x32_bf16 v[8:11], v[158:161], v[190:193], v[8:11]
	s_barrier
	s_add_u32 s26, s26, 0x20080
	s_addc_u32 s27, s27, 0
	s_add_i32 s28, s28, s31
	s_mov_b32 m0, s28
	s_nop 0
	global_load_lds_dwordx4 v132, s[26:27]
	s_add_i32 m0, s28, 0x2000
	s_nop 0
	global_load_lds_dwordx4 v128, s[26:27]
	s_waitcnt vmcnt(6)
	s_barrier
	v_mfma_f32_16x16x32_bf16 v[52:55], v[194:197], v[162:165], v[52:55]
	v_mfma_f32_16x16x32_bf16 v[48:51], v[204:207], v[162:165], v[48:51]
	v_mfma_f32_16x16x32_bf16 v[36:39], v[194:197], v[170:173], v[36:39]
	v_mfma_f32_16x16x32_bf16 v[32:35], v[204:207], v[170:173], v[32:35]
	v_mfma_f32_16x16x32_bf16 v[20:23], v[194:197], v[178:181], v[20:23]
	v_mfma_f32_16x16x32_bf16 v[16:19], v[204:207], v[178:181], v[16:19]
	v_mfma_f32_16x16x32_bf16 v[4:7], v[194:197], v[186:189], v[4:7]
	v_mfma_f32_16x16x32_bf16 v[0:3], v[204:207], v[186:189], v[0:3]
	v_mfma_f32_16x16x32_bf16 v[52:55], v[198:201], v[166:169], v[52:55]
	v_mfma_f32_16x16x32_bf16 v[48:51], v[208:211], v[166:169], v[48:51]
	v_mfma_f32_16x16x32_bf16 v[36:39], v[198:201], v[174:177], v[36:39]
	v_mfma_f32_16x16x32_bf16 v[32:35], v[208:211], v[174:177], v[32:35]
	v_mfma_f32_16x16x32_bf16 v[20:23], v[198:201], v[182:185], v[20:23]
	v_mfma_f32_16x16x32_bf16 v[16:19], v[208:211], v[182:185], v[16:19]
	v_mfma_f32_16x16x32_bf16 v[4:7], v[198:201], v[190:193], v[4:7]
	v_mfma_f32_16x16x32_bf16 v[0:3], v[208:211], v[190:193], v[0:3]
	s_add_u32 s24, s24, 0x100
	s_addc_u32 s25, s25, 0
	s_add_u32 s50, s50, 0x100
	s_addc_u32 s51, s51, 0
	s_cmp_ge_i32 s52, s46
	s_mov_b32 s26, s52
	s_barrier
	s_cbranch_scc0 .LBB0_368
	s_branch .LBB0_363

.LBB0_531:
	ds_read_b128 v[152:155], v149
	ds_read_b128 v[156:159], v149 offset:1024
	ds_read_b128 v[160:163], v149 offset:2048
	ds_read_b128 v[164:167], v149 offset:3072
	s_add_u32 s24, s22, 0xfff80080
	s_addc_u32 s25, s23, -1
	s_cmp_eq_u32 s45, 28
	s_cselect_b32 s27, s15, s25
	s_cselect_b32 s26, s41, s24
	s_cselect_b32 s25, s9, s44
	s_cselect_b32 s24, s42, s43
	s_add_i32 m0, s21, 0xc000
	ds_read_b128 v[168:171], v150
	ds_read_b128 v[172:175], v150 offset:1024
	ds_read_b128 v[176:179], v150 offset:2048
	ds_read_b128 v[180:183], v150 offset:3072
	ds_read_b128 v[184:187], v150 offset:4096
	ds_read_b128 v[188:191], v150 offset:5120
	ds_read_b128 v[192:195], v150 offset:6144
	ds_read_b128 v[196:199], v150 offset:7168
	global_load_lds_dwordx4 v136, s[22:23]
	s_add_i32 m0, s21, 0xe000
	s_nop 0
	global_load_lds_dwordx4 v138, s[22:23]
	s_waitcnt lgkmcnt(8)
	s_barrier
	s_waitcnt lgkmcnt(0)
	s_waitcnt lgkmcnt(0)
	v_mfma_f32_16x16x32_bf16 v[124:127], v[152:155], v[168:171], v[124:127]
	v_mfma_f32_16x16x32_bf16 v[120:123], v[160:163], v[168:171], v[120:123]
	v_mfma_f32_16x16x32_bf16 v[108:111], v[152:155], v[176:179], v[108:111]
	v_mfma_f32_16x16x32_bf16 v[104:107], v[160:163], v[176:179], v[104:107]
	v_mfma_f32_16x16x32_bf16 v[92:95], v[152:155], v[184:187], v[92:95]
	v_mfma_f32_16x16x32_bf16 v[88:91], v[160:163], v[184:187], v[88:91]
	v_mfma_f32_16x16x32_bf16 v[76:79], v[152:155], v[192:195], v[76:79]
	v_mfma_f32_16x16x32_bf16 v[72:75], v[160:163], v[192:195], v[72:75]
	v_mfma_f32_16x16x32_bf16 v[124:127], v[156:159], v[172:175], v[124:127]
	v_mfma_f32_16x16x32_bf16 v[120:123], v[164:167], v[172:175], v[120:123]
	v_mfma_f32_16x16x32_bf16 v[108:111], v[156:159], v[180:183], v[108:111]
	v_mfma_f32_16x16x32_bf16 v[104:107], v[164:167], v[180:183], v[104:107]
	v_mfma_f32_16x16x32_bf16 v[92:95], v[156:159], v[188:191], v[92:95]
	v_mfma_f32_16x16x32_bf16 v[88:91], v[164:167], v[188:191], v[88:91]
	v_mfma_f32_16x16x32_bf16 v[76:79], v[156:159], v[196:199], v[76:79]
	v_mfma_f32_16x16x32_bf16 v[72:75], v[164:167], v[196:199], v[72:75]
	s_barrier
	s_add_i32 s46, s38, s29
	s_mov_b32 m0, s46
	ds_read_b128 v[204:207], v151
	ds_read_b128 v[208:211], v151 offset:1024
	ds_read_b128 v[212:215], v151 offset:2048
	ds_read_b128 v[216:219], v151 offset:3072
	global_load_lds_dwordx4 v132, s[24:25]
	s_add_i32 m0, s46, 0x2000
	s_nop 0
	global_load_lds_dwordx4 v128, s[24:25]
	s_barrier
	s_waitcnt lgkmcnt(0)
	s_waitcnt lgkmcnt(0)
	v_mfma_f32_16x16x32_bf16 v[116:119], v[204:207], v[168:171], v[116:119]
	v_mfma_f32_16x16x32_bf16 v[112:115], v[212:215], v[168:171], v[112:115]
	v_mfma_f32_16x16x32_bf16 v[100:103], v[204:207], v[176:179], v[100:103]
	v_mfma_f32_16x16x32_bf16 v[96:99], v[212:215], v[176:179], v[96:99]
	v_mfma_f32_16x16x32_bf16 v[84:87], v[204:207], v[184:187], v[84:87]
	v_mfma_f32_16x16x32_bf16 v[80:83], v[212:215], v[184:187], v[80:83]
	v_mfma_f32_16x16x32_bf16 v[68:71], v[204:207], v[192:195], v[68:71]
	v_mfma_f32_16x16x32_bf16 v[64:67], v[212:215], v[192:195], v[64:67]
	v_mfma_f32_16x16x32_bf16 v[116:119], v[208:211], v[172:175], v[116:119]
	v_mfma_f32_16x16x32_bf16 v[112:115], v[216:219], v[172:175], v[112:115]
	v_mfma_f32_16x16x32_bf16 v[100:103], v[208:211], v[180:183], v[100:103]
	v_mfma_f32_16x16x32_bf16 v[96:99], v[216:219], v[180:183], v[96:99]
	v_mfma_f32_16x16x32_bf16 v[84:87], v[208:211], v[188:191], v[84:87]
	v_mfma_f32_16x16x32_bf16 v[80:83], v[216:219], v[188:191], v[80:83]
	v_mfma_f32_16x16x32_bf16 v[68:71], v[208:211], v[196:199], v[68:71]
	v_mfma_f32_16x16x32_bf16 v[64:67], v[216:219], v[196:199], v[64:67]
	s_mov_b32 m0, s21
	s_mov_b64 s[98:99], s[26:27]
	s_barrier
	ds_read_b128 v[168:171], v150 offset:16384
	ds_read_b128 v[172:175], v150 offset:17408
	ds_read_b128 v[176:179], v150 offset:18432
	ds_read_b128 v[180:183], v150 offset:19456
	ds_read_b128 v[184:187], v150 offset:20480
	ds_read_b128 v[188:191], v150 offset:21504
	ds_read_b128 v[192:195], v150 offset:22528
	ds_read_b128 v[196:199], v150 offset:23552
	global_load_lds_dwordx4 v134, s[26:27]
	s_mov_b32 m0, s31
	s_nop 0
	global_load_lds_dwordx4 v130, s[26:27]
	s_barrier
	s_waitcnt lgkmcnt(0)
	s_waitcnt lgkmcnt(0)
	v_mfma_f32_16x16x32_bf16 v[60:63], v[152:155], v[168:171], v[60:63]
	v_mfma_f32_16x16x32_bf16 v[56:59], v[160:163], v[168:171], v[56:59]
	v_mfma_f32_16x16x32_bf16 v[44:47], v[152:155], v[176:179], v[44:47]
	v_mfma_f32_16x16x32_bf16 v[40:43], v[160:163], v[176:179], v[40:43]
	v_mfma_f32_16x16x32_bf16 v[28:31], v[152:155], v[184:187], v[28:31]
	v_mfma_f32_16x16x32_bf16 v[24:27], v[160:163], v[184:187], v[24:27]
	v_mfma_f32_16x16x32_bf16 v[12:15], v[152:155], v[192:195], v[12:15]
	v_mfma_f32_16x16x32_bf16 v[8:11], v[160:163], v[192:195], v[8:11]
	v_mfma_f32_16x16x32_bf16 v[60:63], v[156:159], v[172:175], v[60:63]
	v_mfma_f32_16x16x32_bf16 v[56:59], v[164:167], v[172:175], v[56:59]
	v_mfma_f32_16x16x32_bf16 v[44:47], v[156:159], v[180:183], v[44:47]
	v_mfma_f32_16x16x32_bf16 v[40:43], v[164:167], v[180:183], v[40:43]
	v_mfma_f32_16x16x32_bf16 v[28:31], v[156:159], v[188:191], v[28:31]
	v_mfma_f32_16x16x32_bf16 v[24:27], v[164:167], v[188:191], v[24:27]
	v_mfma_f32_16x16x32_bf16 v[12:15], v[156:159], v[196:199], v[12:15]
	v_mfma_f32_16x16x32_bf16 v[8:11], v[164:167], v[196:199], v[8:11]
	s_barrier
	s_add_u32 s46, s24, 0x20000
	s_addc_u32 s47, s25, 0
	s_add_i32 s48, s39, s29
	s_mov_b32 m0, s48
	s_nop 0
	global_load_lds_dwordx4 v132, s[46:47]
	s_add_i32 m0, s48, 0x2000
	s_nop 0
	global_load_lds_dwordx4 v128, s[46:47]
	s_waitcnt vmcnt(6)
	s_barrier
	v_mfma_f32_16x16x32_bf16 v[52:55], v[204:207], v[168:171], v[52:55]
	v_mfma_f32_16x16x32_bf16 v[48:51], v[212:215], v[168:171], v[48:51]
	v_mfma_f32_16x16x32_bf16 v[36:39], v[204:207], v[176:179], v[36:39]
	v_mfma_f32_16x16x32_bf16 v[32:35], v[212:215], v[176:179], v[32:35]
	v_mfma_f32_16x16x32_bf16 v[20:23], v[204:207], v[184:187], v[20:23]
	v_mfma_f32_16x16x32_bf16 v[16:19], v[212:215], v[184:187], v[16:19]
	v_mfma_f32_16x16x32_bf16 v[4:7], v[204:207], v[192:195], v[4:7]
	v_mfma_f32_16x16x32_bf16 v[0:3], v[212:215], v[192:195], v[0:3]
	v_mfma_f32_16x16x32_bf16 v[52:55], v[208:211], v[172:175], v[52:55]
	v_mfma_f32_16x16x32_bf16 v[48:51], v[216:219], v[172:175], v[48:51]
	v_mfma_f32_16x16x32_bf16 v[36:39], v[208:211], v[180:183], v[36:39]
	v_mfma_f32_16x16x32_bf16 v[32:35], v[216:219], v[180:183], v[32:35]
	v_mfma_f32_16x16x32_bf16 v[20:23], v[208:211], v[188:191], v[20:23]
	v_mfma_f32_16x16x32_bf16 v[16:19], v[216:219], v[188:191], v[16:19]
	v_mfma_f32_16x16x32_bf16 v[4:7], v[208:211], v[196:199], v[4:7]
	v_mfma_f32_16x16x32_bf16 v[0:3], v[216:219], v[196:199], v[0:3]
	s_add_i32 s46, 0, 0x18000
	v_add_u32_e32 v164, s46, v147
	s_barrier
	ds_read_b128 v[152:155], v164
	ds_read_b128 v[156:159], v164 offset:1024
	ds_read_b128 v[160:163], v164 offset:2048
	ds_read_b128 v[164:167], v164 offset:3072
	s_add_u32 s26, s26, 0x80000
	s_addc_u32 s27, s27, 0
	s_mov_b32 m0, s33
	ds_read_b128 v[168:171], v150 offset:32768
	ds_read_b128 v[172:175], v150 offset:33792
	ds_read_b128 v[176:179], v150 offset:34816
	ds_read_b128 v[180:183], v150 offset:35840
	ds_read_b128 v[184:187], v150 offset:36864
	ds_read_b128 v[188:191], v150 offset:37888
	ds_read_b128 v[192:195], v150 offset:38912
	ds_read_b128 v[196:199], v150 offset:39936
	global_load_lds_dwordx4 v134, s[26:27]
	s_mov_b32 m0, s34
	s_nop 0
	global_load_lds_dwordx4 v130, s[26:27]
	s_waitcnt lgkmcnt(8)
	s_barrier
	s_waitcnt lgkmcnt(0)
	s_waitcnt lgkmcnt(0)
	v_mfma_f32_16x16x32_bf16 v[124:127], v[152:155], v[168:171], v[124:127]
	v_mfma_f32_16x16x32_bf16 v[120:123], v[160:163], v[168:171], v[120:123]
	v_mfma_f32_16x16x32_bf16 v[108:111], v[152:155], v[176:179], v[108:111]
	v_mfma_f32_16x16x32_bf16 v[104:107], v[160:163], v[176:179], v[104:107]
	v_mfma_f32_16x16x32_bf16 v[92:95], v[152:155], v[184:187], v[92:95]
	v_mfma_f32_16x16x32_bf16 v[88:91], v[160:163], v[184:187], v[88:91]
	v_mfma_f32_16x16x32_bf16 v[76:79], v[152:155], v[192:195], v[76:79]
	v_mfma_f32_16x16x32_bf16 v[72:75], v[160:163], v[192:195], v[72:75]
	v_mfma_f32_16x16x32_bf16 v[124:127], v[156:159], v[172:175], v[124:127]
	v_mfma_f32_16x16x32_bf16 v[120:123], v[164:167], v[172:175], v[120:123]
	v_mfma_f32_16x16x32_bf16 v[108:111], v[156:159], v[180:183], v[108:111]
	v_mfma_f32_16x16x32_bf16 v[104:107], v[164:167], v[180:183], v[104:107]
	v_mfma_f32_16x16x32_bf16 v[92:95], v[156:159], v[188:191], v[92:95]
	v_mfma_f32_16x16x32_bf16 v[88:91], v[164:167], v[188:191], v[88:91]
	v_mfma_f32_16x16x32_bf16 v[76:79], v[156:159], v[196:199], v[76:79]
	v_mfma_f32_16x16x32_bf16 v[72:75], v[164:167], v[196:199], v[72:75]
	s_barrier
	s_add_i32 s26, 0, 0x1c000
	s_add_i32 s27, s46, s29
	v_add_u32_e32 v216, s26, v147
	s_mov_b32 m0, s27
	ds_read_b128 v[204:207], v216
	ds_read_b128 v[208:211], v216 offset:1024
	ds_read_b128 v[212:215], v216 offset:2048
	ds_read_b128 v[216:219], v216 offset:3072
	s_add_u32 s100, s24, 0x80
	s_addc_u32 s101, s25, 0
	global_load_lds_dwordx4 v132, s[100:101]
	s_add_i32 m0, s27, 0x2000
	s_nop 0
	s_add_u32 s100, s24, 0x80
	s_addc_u32 s101, s25, 0
	global_load_lds_dwordx4 v128, s[100:101]
	s_barrier
	s_waitcnt lgkmcnt(0)
	s_waitcnt lgkmcnt(0)
	v_mfma_f32_16x16x32_bf16 v[116:119], v[204:207], v[168:171], v[116:119]
	v_mfma_f32_16x16x32_bf16 v[112:115], v[212:215], v[168:171], v[112:115]
	v_mfma_f32_16x16x32_bf16 v[100:103], v[204:207], v[176:179], v[100:103]
	v_mfma_f32_16x16x32_bf16 v[96:99], v[212:215], v[176:179], v[96:99]
	v_mfma_f32_16x16x32_bf16 v[84:87], v[204:207], v[184:187], v[84:87]
	v_mfma_f32_16x16x32_bf16 v[80:83], v[212:215], v[184:187], v[80:83]
	v_mfma_f32_16x16x32_bf16 v[68:71], v[204:207], v[192:195], v[68:71]
	v_mfma_f32_16x16x32_bf16 v[64:67], v[212:215], v[192:195], v[64:67]
	v_mfma_f32_16x16x32_bf16 v[116:119], v[208:211], v[172:175], v[116:119]
	v_mfma_f32_16x16x32_bf16 v[112:115], v[216:219], v[172:175], v[112:115]
	v_mfma_f32_16x16x32_bf16 v[100:103], v[208:211], v[180:183], v[100:103]
	v_mfma_f32_16x16x32_bf16 v[96:99], v[216:219], v[180:183], v[96:99]
	v_mfma_f32_16x16x32_bf16 v[84:87], v[208:211], v[188:191], v[84:87]
	v_mfma_f32_16x16x32_bf16 v[80:83], v[216:219], v[188:191], v[80:83]
	v_mfma_f32_16x16x32_bf16 v[68:71], v[208:211], v[196:199], v[68:71]
	v_mfma_f32_16x16x32_bf16 v[64:67], v[216:219], v[196:199], v[64:67]
	s_mov_b32 m0, s36
	s_barrier
	ds_read_b128 v[168:171], v150 offset:49152
	ds_read_b128 v[172:175], v150 offset:50176
	ds_read_b128 v[176:179], v150 offset:51200
	ds_read_b128 v[180:183], v150 offset:52224
	ds_read_b128 v[184:187], v150 offset:53248
	ds_read_b128 v[188:191], v150 offset:54272
	ds_read_b128 v[192:195], v150 offset:55296
	ds_read_b128 v[196:199], v150 offset:56320
	s_add_u32 s100, s98, 0x80
	s_addc_u32 s101, s99, 0
	global_load_lds_dwordx4 v134, s[100:101]
	s_mov_b32 m0, s37
	s_nop 0
	s_add_u32 s100, s98, 0x80
	s_addc_u32 s101, s99, 0
	global_load_lds_dwordx4 v130, s[100:101]
	s_barrier
	s_waitcnt lgkmcnt(0)
	s_waitcnt lgkmcnt(0)
	v_mfma_f32_16x16x32_bf16 v[60:63], v[152:155], v[168:171], v[60:63]
	v_mfma_f32_16x16x32_bf16 v[56:59], v[160:163], v[168:171], v[56:59]
	v_mfma_f32_16x16x32_bf16 v[44:47], v[152:155], v[176:179], v[44:47]
	v_mfma_f32_16x16x32_bf16 v[40:43], v[160:163], v[176:179], v[40:43]
	v_mfma_f32_16x16x32_bf16 v[28:31], v[152:155], v[184:187], v[28:31]
	v_mfma_f32_16x16x32_bf16 v[24:27], v[160:163], v[184:187], v[24:27]
	v_mfma_f32_16x16x32_bf16 v[12:15], v[152:155], v[192:195], v[12:15]
	v_mfma_f32_16x16x32_bf16 v[8:11], v[160:163], v[192:195], v[8:11]
	v_mfma_f32_16x16x32_bf16 v[60:63], v[156:159], v[172:175], v[60:63]
	v_mfma_f32_16x16x32_bf16 v[56:59], v[164:167], v[172:175], v[56:59]
	v_mfma_f32_16x16x32_bf16 v[44:47], v[156:159], v[180:183], v[44:47]
	v_mfma_f32_16x16x32_bf16 v[40:43], v[164:167], v[180:183], v[40:43]
	v_mfma_f32_16x16x32_bf16 v[28:31], v[156:159], v[188:191], v[28:31]
	v_mfma_f32_16x16x32_bf16 v[24:27], v[164:167], v[188:191], v[24:27]
	v_mfma_f32_16x16x32_bf16 v[12:15], v[156:159], v[196:199], v[12:15]
	v_mfma_f32_16x16x32_bf16 v[8:11], v[164:167], v[196:199], v[8:11]
	s_barrier
	s_add_u32 s24, s24, 0x20080
	s_addc_u32 s25, s25, 0
	s_add_i32 s26, s26, s29
	s_mov_b32 m0, s26
	s_nop 0
	global_load_lds_dwordx4 v132, s[24:25]
	s_add_i32 m0, s26, 0x2000
	s_nop 0
	global_load_lds_dwordx4 v128, s[24:25]
	s_waitcnt vmcnt(6)
	s_barrier
	v_mfma_f32_16x16x32_bf16 v[52:55], v[204:207], v[168:171], v[52:55]
	v_mfma_f32_16x16x32_bf16 v[48:51], v[212:215], v[168:171], v[48:51]
	v_mfma_f32_16x16x32_bf16 v[36:39], v[204:207], v[176:179], v[36:39]
	v_mfma_f32_16x16x32_bf16 v[32:35], v[212:215], v[176:179], v[32:35]
	v_mfma_f32_16x16x32_bf16 v[20:23], v[204:207], v[184:187], v[20:23]
	v_mfma_f32_16x16x32_bf16 v[16:19], v[212:215], v[184:187], v[16:19]
	v_mfma_f32_16x16x32_bf16 v[4:7], v[204:207], v[192:195], v[4:7]
	v_mfma_f32_16x16x32_bf16 v[0:3], v[212:215], v[192:195], v[0:3]
	v_mfma_f32_16x16x32_bf16 v[52:55], v[208:211], v[172:175], v[52:55]
	v_mfma_f32_16x16x32_bf16 v[48:51], v[216:219], v[172:175], v[48:51]
	v_mfma_f32_16x16x32_bf16 v[36:39], v[208:211], v[180:183], v[36:39]
	v_mfma_f32_16x16x32_bf16 v[32:35], v[216:219], v[180:183], v[32:35]
	v_mfma_f32_16x16x32_bf16 v[20:23], v[208:211], v[188:191], v[20:23]
	v_mfma_f32_16x16x32_bf16 v[16:19], v[216:219], v[188:191], v[16:19]
	v_mfma_f32_16x16x32_bf16 v[4:7], v[208:211], v[196:199], v[4:7]
	v_mfma_f32_16x16x32_bf16 v[0:3], v[216:219], v[196:199], v[0:3]
	s_add_i32 s45, s45, 2
	s_add_u32 s22, s22, 0x100
	s_addc_u32 s23, s23, 0
	s_add_u32 s43, s43, 0x100
	s_addc_u32 s44, s44, 0
	s_cmp_gt_u32 s45, 29
	s_barrier
	s_cbranch_scc0 .LBB0_531
	v_readlane_b32 s100, v248, 63
	v_readlane_b32 s101, v247, 0
	v_and_b32_e32 v242, 15, v202
	v_bfe_u32 v243, v202, 4, 2
	v_bfe_u32 v244, v202, 6, 2
	v_lshrrev_b32_e32 v245, 8, v202
	v_and_b32_e32 v240, 7, v242
	v_lshl_add_u32 v240, v245, 6, v240
	v_lshl_add_u32 v240, s20, 8, v240
	v_lshlrev_b32_e32 v240, 14, v240
	v_lshrrev_b32_e32 v241, 3, v242
	v_lshlrev_b32_e32 v241, 6, v241
	v_lshl_add_u32 v241, v244, 7, v241
	v_lshl_add_u32 v241, v243, 4, v241
	v_add_u32_e32 v240, v240, v241
	s_lshl_b32 s98, s40, 9
	v_add_u32_e32 v240, s98, v240
	v_max_f32_e32 v124, 0, v124
	v_max_f32_e32 v125, 0, v125
	v_max_f32_e32 v126, 0, v126
	v_max_f32_e32 v127, 0, v127
	v_max_f32_e32 v120, 0, v120
	v_max_f32_e32 v121, 0, v121
	v_max_f32_e32 v122, 0, v122
	v_max_f32_e32 v123, 0, v123
	v_pk_mul_f32 v[124:125], v[124:125], v[124:125]
	v_pk_mul_f32 v[126:127], v[126:127], v[126:127]
	v_pk_mul_f32 v[120:121], v[120:121], v[120:121]
	v_pk_mul_f32 v[122:123], v[122:123], v[122:123]
	v_cvt_pk_bf16_f32 v228, v124, v125
	v_cvt_pk_bf16_f32 v229, v126, v127
	v_cvt_pk_bf16_f32 v230, v120, v121
	v_cvt_pk_bf16_f32 v231, v122, v123
	v_max_f32_e32 v116, 0, v116
	v_max_f32_e32 v117, 0, v117
	v_max_f32_e32 v118, 0, v118
	v_max_f32_e32 v119, 0, v119
	v_max_f32_e32 v112, 0, v112
	v_max_f32_e32 v113, 0, v113
	v_max_f32_e32 v114, 0, v114
	v_max_f32_e32 v115, 0, v115
	v_pk_mul_f32 v[116:117], v[116:117], v[116:117]
	v_pk_mul_f32 v[118:119], v[118:119], v[118:119]
	v_pk_mul_f32 v[112:113], v[112:113], v[112:113]
	v_pk_mul_f32 v[114:115], v[114:115], v[114:115]
	v_cvt_pk_bf16_f32 v232, v116, v117
	v_cvt_pk_bf16_f32 v233, v118, v119
	v_cvt_pk_bf16_f32 v234, v112, v113
	v_cvt_pk_bf16_f32 v235, v114, v115
	v_mov_b32_e32 v236, v228
	v_mov_b32_e32 v237, v229
	v_mov_b32_e32 v238, v230
	v_mov_b32_e32 v239, v231
	v_mov_b32_dpp v228, v232 row_ror:8 row_mask:0xf bank_mask:0xc
	v_mov_b32_dpp v229, v233 row_ror:8 row_mask:0xf bank_mask:0xc
	v_mov_b32_dpp v230, v234 row_ror:8 row_mask:0xf bank_mask:0xc
	v_mov_b32_dpp v231, v235 row_ror:8 row_mask:0xf bank_mask:0xc
	v_mov_b32_dpp v232, v236 row_ror:8 row_mask:0xf bank_mask:0x3
	v_mov_b32_dpp v233, v237 row_ror:8 row_mask:0xf bank_mask:0x3
	v_mov_b32_dpp v234, v238 row_ror:8 row_mask:0xf bank_mask:0x3
	v_mov_b32_dpp v235, v239 row_ror:8 row_mask:0xf bank_mask:0x3
	global_store_dwordx4 v240, v[228:231], s[100:101]
	s_add_u32 s100, s100, 0x20000
	s_addc_u32 s101, s101, 0
	global_store_dwordx4 v240, v[232:235], s[100:101]
	v_max_f32_e32 v108, 0, v108
	v_max_f32_e32 v109, 0, v109
	v_max_f32_e32 v110, 0, v110
	v_max_f32_e32 v111, 0, v111
	v_max_f32_e32 v104, 0, v104
	v_max_f32_e32 v105, 0, v105
	v_max_f32_e32 v106, 0, v106
	v_max_f32_e32 v107, 0, v107
	v_pk_mul_f32 v[108:109], v[108:109], v[108:109]
	v_pk_mul_f32 v[110:111], v[110:111], v[110:111]
	v_pk_mul_f32 v[104:105], v[104:105], v[104:105]
	v_pk_mul_f32 v[106:107], v[106:107], v[106:107]
	v_cvt_pk_bf16_f32 v228, v108, v109
	v_cvt_pk_bf16_f32 v229, v110, v111
	v_cvt_pk_bf16_f32 v230, v104, v105
	v_cvt_pk_bf16_f32 v231, v106, v107
	v_max_f32_e32 v100, 0, v100
	v_max_f32_e32 v101, 0, v101
	v_max_f32_e32 v102, 0, v102
	v_max_f32_e32 v103, 0, v103
	v_max_f32_e32 v96, 0, v96
	v_max_f32_e32 v97, 0, v97
	v_max_f32_e32 v98, 0, v98
	v_max_f32_e32 v99, 0, v99
	v_pk_mul_f32 v[100:101], v[100:101], v[100:101]
	v_pk_mul_f32 v[102:103], v[102:103], v[102:103]
	v_pk_mul_f32 v[96:97], v[96:97], v[96:97]
	v_pk_mul_f32 v[98:99], v[98:99], v[98:99]
	v_cvt_pk_bf16_f32 v232, v100, v101
	v_cvt_pk_bf16_f32 v233, v102, v103
	v_cvt_pk_bf16_f32 v234, v96, v97
	v_cvt_pk_bf16_f32 v235, v98, v99
	v_mov_b32_e32 v236, v228
	v_mov_b32_e32 v237, v229
	v_mov_b32_e32 v238, v230
	v_mov_b32_e32 v239, v231
	v_mov_b32_dpp v228, v232 row_ror:8 row_mask:0xf bank_mask:0xc
	v_mov_b32_dpp v229, v233 row_ror:8 row_mask:0xf bank_mask:0xc
	v_mov_b32_dpp v230, v234 row_ror:8 row_mask:0xf bank_mask:0xc
	v_mov_b32_dpp v231, v235 row_ror:8 row_mask:0xf bank_mask:0xc
	v_mov_b32_dpp v232, v236 row_ror:8 row_mask:0xf bank_mask:0x3
	v_mov_b32_dpp v233, v237 row_ror:8 row_mask:0xf bank_mask:0x3
	v_mov_b32_dpp v234, v238 row_ror:8 row_mask:0xf bank_mask:0x3
	v_mov_b32_dpp v235, v239 row_ror:8 row_mask:0xf bank_mask:0x3
	s_add_u32 s100, s100, 0x20000
	s_addc_u32 s101, s101, 0
	global_store_dwordx4 v240, v[228:231], s[100:101]
	s_add_u32 s100, s100, 0x20000
	s_addc_u32 s101, s101, 0
	global_store_dwordx4 v240, v[232:235], s[100:101]
	v_max_f32_e32 v92, 0, v92
	v_max_f32_e32 v93, 0, v93
	v_max_f32_e32 v94, 0, v94
	v_max_f32_e32 v95, 0, v95
	v_max_f32_e32 v88, 0, v88
	v_max_f32_e32 v89, 0, v89
	v_max_f32_e32 v90, 0, v90
	v_max_f32_e32 v91, 0, v91
	v_pk_mul_f32 v[92:93], v[92:93], v[92:93]
	v_pk_mul_f32 v[94:95], v[94:95], v[94:95]
	v_pk_mul_f32 v[88:89], v[88:89], v[88:89]
	v_pk_mul_f32 v[90:91], v[90:91], v[90:91]
	v_cvt_pk_bf16_f32 v228, v92, v93
	v_cvt_pk_bf16_f32 v229, v94, v95
	v_cvt_pk_bf16_f32 v230, v88, v89
	v_cvt_pk_bf16_f32 v231, v90, v91
	v_max_f32_e32 v84, 0, v84
	v_max_f32_e32 v85, 0, v85
	v_max_f32_e32 v86, 0, v86
	v_max_f32_e32 v87, 0, v87
	v_max_f32_e32 v80, 0, v80
	v_max_f32_e32 v81, 0, v81
	v_max_f32_e32 v82, 0, v82
	v_max_f32_e32 v83, 0, v83
	v_pk_mul_f32 v[84:85], v[84:85], v[84:85]
	v_pk_mul_f32 v[86:87], v[86:87], v[86:87]
	v_pk_mul_f32 v[80:81], v[80:81], v[80:81]
	v_pk_mul_f32 v[82:83], v[82:83], v[82:83]
	v_cvt_pk_bf16_f32 v232, v84, v85
	v_cvt_pk_bf16_f32 v233, v86, v87
	v_cvt_pk_bf16_f32 v234, v80, v81
	v_cvt_pk_bf16_f32 v235, v82, v83
	v_mov_b32_e32 v236, v228
	v_mov_b32_e32 v237, v229
	v_mov_b32_e32 v238, v230
	v_mov_b32_e32 v239, v231
	v_mov_b32_dpp v228, v232 row_ror:8 row_mask:0xf bank_mask:0xc
	v_mov_b32_dpp v229, v233 row_ror:8 row_mask:0xf bank_mask:0xc
	v_mov_b32_dpp v230, v234 row_ror:8 row_mask:0xf bank_mask:0xc
	v_mov_b32_dpp v231, v235 row_ror:8 row_mask:0xf bank_mask:0xc
	v_mov_b32_dpp v232, v236 row_ror:8 row_mask:0xf bank_mask:0x3
	v_mov_b32_dpp v233, v237 row_ror:8 row_mask:0xf bank_mask:0x3
	v_mov_b32_dpp v234, v238 row_ror:8 row_mask:0xf bank_mask:0x3
	v_mov_b32_dpp v235, v239 row_ror:8 row_mask:0xf bank_mask:0x3
	s_add_u32 s100, s100, 0x20000
	s_addc_u32 s101, s101, 0
	global_store_dwordx4 v240, v[228:231], s[100:101]
	s_add_u32 s100, s100, 0x20000
	s_addc_u32 s101, s101, 0
	global_store_dwordx4 v240, v[232:235], s[100:101]
	v_max_f32_e32 v76, 0, v76
	v_max_f32_e32 v77, 0, v77
	v_max_f32_e32 v78, 0, v78
	v_max_f32_e32 v79, 0, v79
	v_max_f32_e32 v72, 0, v72
	v_max_f32_e32 v73, 0, v73
	v_max_f32_e32 v74, 0, v74
	v_max_f32_e32 v75, 0, v75
	v_pk_mul_f32 v[76:77], v[76:77], v[76:77]
	v_pk_mul_f32 v[78:79], v[78:79], v[78:79]
	v_pk_mul_f32 v[72:73], v[72:73], v[72:73]
	v_pk_mul_f32 v[74:75], v[74:75], v[74:75]
	v_cvt_pk_bf16_f32 v228, v76, v77
	v_cvt_pk_bf16_f32 v229, v78, v79
	v_cvt_pk_bf16_f32 v230, v72, v73
	v_cvt_pk_bf16_f32 v231, v74, v75
	v_max_f32_e32 v68, 0, v68
	v_max_f32_e32 v69, 0, v69
	v_max_f32_e32 v70, 0, v70
	v_max_f32_e32 v71, 0, v71
	v_max_f32_e32 v64, 0, v64
	v_max_f32_e32 v65, 0, v65
	v_max_f32_e32 v66, 0, v66
	v_max_f32_e32 v67, 0, v67
	v_pk_mul_f32 v[68:69], v[68:69], v[68:69]
	v_pk_mul_f32 v[70:71], v[70:71], v[70:71]
	v_pk_mul_f32 v[64:65], v[64:65], v[64:65]
	v_pk_mul_f32 v[66:67], v[66:67], v[66:67]
	v_cvt_pk_bf16_f32 v232, v68, v69
	v_cvt_pk_bf16_f32 v233, v70, v71
	v_cvt_pk_bf16_f32 v234, v64, v65
	v_cvt_pk_bf16_f32 v235, v66, v67
	v_mov_b32_e32 v236, v228
	v_mov_b32_e32 v237, v229
	v_mov_b32_e32 v238, v230
	v_mov_b32_e32 v239, v231
	v_mov_b32_dpp v228, v232 row_ror:8 row_mask:0xf bank_mask:0xc
	v_mov_b32_dpp v229, v233 row_ror:8 row_mask:0xf bank_mask:0xc
	v_mov_b32_dpp v230, v234 row_ror:8 row_mask:0xf bank_mask:0xc
	v_mov_b32_dpp v231, v235 row_ror:8 row_mask:0xf bank_mask:0xc
	v_mov_b32_dpp v232, v236 row_ror:8 row_mask:0xf bank_mask:0x3
	v_mov_b32_dpp v233, v237 row_ror:8 row_mask:0xf bank_mask:0x3
	v_mov_b32_dpp v234, v238 row_ror:8 row_mask:0xf bank_mask:0x3
	v_mov_b32_dpp v235, v239 row_ror:8 row_mask:0xf bank_mask:0x3
	s_add_u32 s100, s100, 0x20000
	s_addc_u32 s101, s101, 0
	global_store_dwordx4 v240, v[228:231], s[100:101]
	s_add_u32 s100, s100, 0x20000
	s_addc_u32 s101, s101, 0
	global_store_dwordx4 v240, v[232:235], s[100:101]
	v_max_f32_e32 v60, 0, v60
	v_max_f32_e32 v61, 0, v61
	v_max_f32_e32 v62, 0, v62
	v_max_f32_e32 v63, 0, v63
	v_max_f32_e32 v56, 0, v56
	v_max_f32_e32 v57, 0, v57
	v_max_f32_e32 v58, 0, v58
	v_max_f32_e32 v59, 0, v59
	v_pk_mul_f32 v[60:61], v[60:61], v[60:61]
	v_pk_mul_f32 v[62:63], v[62:63], v[62:63]
	v_pk_mul_f32 v[56:57], v[56:57], v[56:57]
	v_pk_mul_f32 v[58:59], v[58:59], v[58:59]
	v_cvt_pk_bf16_f32 v228, v60, v61
	v_cvt_pk_bf16_f32 v229, v62, v63
	v_cvt_pk_bf16_f32 v230, v56, v57
	v_cvt_pk_bf16_f32 v231, v58, v59
	v_max_f32_e32 v52, 0, v52
	v_max_f32_e32 v53, 0, v53
	v_max_f32_e32 v54, 0, v54
	v_max_f32_e32 v55, 0, v55
	v_max_f32_e32 v48, 0, v48
	v_max_f32_e32 v49, 0, v49
	v_max_f32_e32 v50, 0, v50
	v_max_f32_e32 v51, 0, v51
	v_pk_mul_f32 v[52:53], v[52:53], v[52:53]
	v_pk_mul_f32 v[54:55], v[54:55], v[54:55]
	v_pk_mul_f32 v[48:49], v[48:49], v[48:49]
	v_pk_mul_f32 v[50:51], v[50:51], v[50:51]
	v_cvt_pk_bf16_f32 v232, v52, v53
	v_cvt_pk_bf16_f32 v233, v54, v55
	v_cvt_pk_bf16_f32 v234, v48, v49
	v_cvt_pk_bf16_f32 v235, v50, v51
	v_mov_b32_e32 v236, v228
	v_mov_b32_e32 v237, v229
	v_mov_b32_e32 v238, v230
	v_mov_b32_e32 v239, v231
	v_mov_b32_dpp v228, v232 row_ror:8 row_mask:0xf bank_mask:0xc
	v_mov_b32_dpp v229, v233 row_ror:8 row_mask:0xf bank_mask:0xc
	v_mov_b32_dpp v230, v234 row_ror:8 row_mask:0xf bank_mask:0xc
	v_mov_b32_dpp v231, v235 row_ror:8 row_mask:0xf bank_mask:0xc
	v_mov_b32_dpp v232, v236 row_ror:8 row_mask:0xf bank_mask:0x3
	v_mov_b32_dpp v233, v237 row_ror:8 row_mask:0xf bank_mask:0x3
	v_mov_b32_dpp v234, v238 row_ror:8 row_mask:0xf bank_mask:0x3
	v_mov_b32_dpp v235, v239 row_ror:8 row_mask:0xf bank_mask:0x3
	s_add_u32 s100, s100, 0x120000
	s_addc_u32 s101, s101, 0
	global_store_dwordx4 v240, v[228:231], s[100:101]
	s_add_u32 s100, s100, 0x20000
	s_addc_u32 s101, s101, 0
	global_store_dwordx4 v240, v[232:235], s[100:101]
	v_max_f32_e32 v44, 0, v44
	v_max_f32_e32 v45, 0, v45
	v_max_f32_e32 v46, 0, v46
	v_max_f32_e32 v47, 0, v47
	v_max_f32_e32 v40, 0, v40
	v_max_f32_e32 v41, 0, v41
	v_max_f32_e32 v42, 0, v42
	v_max_f32_e32 v43, 0, v43
	v_pk_mul_f32 v[44:45], v[44:45], v[44:45]
	v_pk_mul_f32 v[46:47], v[46:47], v[46:47]
	v_pk_mul_f32 v[40:41], v[40:41], v[40:41]
	v_pk_mul_f32 v[42:43], v[42:43], v[42:43]
	v_cvt_pk_bf16_f32 v228, v44, v45
	v_cvt_pk_bf16_f32 v229, v46, v47
	v_cvt_pk_bf16_f32 v230, v40, v41
	v_cvt_pk_bf16_f32 v231, v42, v43
	v_max_f32_e32 v36, 0, v36
	v_max_f32_e32 v37, 0, v37
	v_max_f32_e32 v38, 0, v38
	v_max_f32_e32 v39, 0, v39
	v_max_f32_e32 v32, 0, v32
	v_max_f32_e32 v33, 0, v33
	v_max_f32_e32 v34, 0, v34
	v_max_f32_e32 v35, 0, v35
	v_pk_mul_f32 v[36:37], v[36:37], v[36:37]
	v_pk_mul_f32 v[38:39], v[38:39], v[38:39]
	v_pk_mul_f32 v[32:33], v[32:33], v[32:33]
	v_pk_mul_f32 v[34:35], v[34:35], v[34:35]
	v_cvt_pk_bf16_f32 v232, v36, v37
	v_cvt_pk_bf16_f32 v233, v38, v39
	v_cvt_pk_bf16_f32 v234, v32, v33
	v_cvt_pk_bf16_f32 v235, v34, v35
	v_mov_b32_e32 v236, v228
	v_mov_b32_e32 v237, v229
	v_mov_b32_e32 v238, v230
	v_mov_b32_e32 v239, v231
	v_mov_b32_dpp v228, v232 row_ror:8 row_mask:0xf bank_mask:0xc
	v_mov_b32_dpp v229, v233 row_ror:8 row_mask:0xf bank_mask:0xc
	v_mov_b32_dpp v230, v234 row_ror:8 row_mask:0xf bank_mask:0xc
	v_mov_b32_dpp v231, v235 row_ror:8 row_mask:0xf bank_mask:0xc
	v_mov_b32_dpp v232, v236 row_ror:8 row_mask:0xf bank_mask:0x3
	v_mov_b32_dpp v233, v237 row_ror:8 row_mask:0xf bank_mask:0x3
	v_mov_b32_dpp v234, v238 row_ror:8 row_mask:0xf bank_mask:0x3
	v_mov_b32_dpp v235, v239 row_ror:8 row_mask:0xf bank_mask:0x3
	s_add_u32 s100, s100, 0x20000
	s_addc_u32 s101, s101, 0
	global_store_dwordx4 v240, v[228:231], s[100:101]
	s_add_u32 s100, s100, 0x20000
	s_addc_u32 s101, s101, 0
	global_store_dwordx4 v240, v[232:235], s[100:101]
	v_max_f32_e32 v28, 0, v28
	v_max_f32_e32 v29, 0, v29
	v_max_f32_e32 v30, 0, v30
	v_max_f32_e32 v31, 0, v31
	v_max_f32_e32 v24, 0, v24
	v_max_f32_e32 v25, 0, v25
	v_max_f32_e32 v26, 0, v26
	v_max_f32_e32 v27, 0, v27
	v_pk_mul_f32 v[28:29], v[28:29], v[28:29]
	v_pk_mul_f32 v[30:31], v[30:31], v[30:31]
	v_pk_mul_f32 v[24:25], v[24:25], v[24:25]
	v_pk_mul_f32 v[26:27], v[26:27], v[26:27]
	v_cvt_pk_bf16_f32 v228, v28, v29
	v_cvt_pk_bf16_f32 v229, v30, v31
	v_cvt_pk_bf16_f32 v230, v24, v25
	v_cvt_pk_bf16_f32 v231, v26, v27
	v_max_f32_e32 v20, 0, v20
	v_max_f32_e32 v21, 0, v21
	v_max_f32_e32 v22, 0, v22
	v_max_f32_e32 v23, 0, v23
	v_max_f32_e32 v16, 0, v16
	v_max_f32_e32 v17, 0, v17
	v_max_f32_e32 v18, 0, v18
	v_max_f32_e32 v19, 0, v19
	v_pk_mul_f32 v[20:21], v[20:21], v[20:21]
	v_pk_mul_f32 v[22:23], v[22:23], v[22:23]
	v_pk_mul_f32 v[16:17], v[16:17], v[16:17]
	v_pk_mul_f32 v[18:19], v[18:19], v[18:19]
	v_cvt_pk_bf16_f32 v232, v20, v21
	v_cvt_pk_bf16_f32 v233, v22, v23
	v_cvt_pk_bf16_f32 v234, v16, v17
	v_cvt_pk_bf16_f32 v235, v18, v19
	v_mov_b32_e32 v236, v228
	v_mov_b32_e32 v237, v229
	v_mov_b32_e32 v238, v230
	v_mov_b32_e32 v239, v231
	v_mov_b32_dpp v228, v232 row_ror:8 row_mask:0xf bank_mask:0xc
	v_mov_b32_dpp v229, v233 row_ror:8 row_mask:0xf bank_mask:0xc
	v_mov_b32_dpp v230, v234 row_ror:8 row_mask:0xf bank_mask:0xc
	v_mov_b32_dpp v231, v235 row_ror:8 row_mask:0xf bank_mask:0xc
	v_mov_b32_dpp v232, v236 row_ror:8 row_mask:0xf bank_mask:0x3
	v_mov_b32_dpp v233, v237 row_ror:8 row_mask:0xf bank_mask:0x3
	v_mov_b32_dpp v234, v238 row_ror:8 row_mask:0xf bank_mask:0x3
	v_mov_b32_dpp v235, v239 row_ror:8 row_mask:0xf bank_mask:0x3
	s_add_u32 s100, s100, 0x20000
	s_addc_u32 s101, s101, 0
	global_store_dwordx4 v240, v[228:231], s[100:101]
	s_add_u32 s100, s100, 0x20000
	s_addc_u32 s101, s101, 0
	global_store_dwordx4 v240, v[232:235], s[100:101]
	v_max_f32_e32 v12, 0, v12
	v_max_f32_e32 v13, 0, v13
	v_max_f32_e32 v14, 0, v14
	v_max_f32_e32 v15, 0, v15
	v_max_f32_e32 v8, 0, v8
	v_max_f32_e32 v9, 0, v9
	v_max_f32_e32 v10, 0, v10
	v_max_f32_e32 v11, 0, v11
	v_pk_mul_f32 v[12:13], v[12:13], v[12:13]
	v_pk_mul_f32 v[14:15], v[14:15], v[14:15]
	v_pk_mul_f32 v[8:9], v[8:9], v[8:9]
	v_pk_mul_f32 v[10:11], v[10:11], v[10:11]
	v_cvt_pk_bf16_f32 v228, v12, v13
	v_cvt_pk_bf16_f32 v229, v14, v15
	v_cvt_pk_bf16_f32 v230, v8, v9
	v_cvt_pk_bf16_f32 v231, v10, v11
	v_max_f32_e32 v4, 0, v4
	v_max_f32_e32 v5, 0, v5
	v_max_f32_e32 v6, 0, v6
	v_max_f32_e32 v7, 0, v7
	v_max_f32_e32 v0, 0, v0
	v_max_f32_e32 v1, 0, v1
	v_max_f32_e32 v2, 0, v2
	v_max_f32_e32 v3, 0, v3
	v_pk_mul_f32 v[4:5], v[4:5], v[4:5]
	v_pk_mul_f32 v[6:7], v[6:7], v[6:7]
	v_pk_mul_f32 v[0:1], v[0:1], v[0:1]
	v_pk_mul_f32 v[2:3], v[2:3], v[2:3]
	v_cvt_pk_bf16_f32 v232, v4, v5
	v_cvt_pk_bf16_f32 v233, v6, v7
	v_cvt_pk_bf16_f32 v234, v0, v1
	v_cvt_pk_bf16_f32 v235, v2, v3
	v_mov_b32_e32 v236, v228
	v_mov_b32_e32 v237, v229
	v_mov_b32_e32 v238, v230
	v_mov_b32_e32 v239, v231
	v_mov_b32_dpp v228, v232 row_ror:8 row_mask:0xf bank_mask:0xc
	v_mov_b32_dpp v229, v233 row_ror:8 row_mask:0xf bank_mask:0xc
	v_mov_b32_dpp v230, v234 row_ror:8 row_mask:0xf bank_mask:0xc
	v_mov_b32_dpp v231, v235 row_ror:8 row_mask:0xf bank_mask:0xc
	v_mov_b32_dpp v232, v236 row_ror:8 row_mask:0xf bank_mask:0x3
	v_mov_b32_dpp v233, v237 row_ror:8 row_mask:0xf bank_mask:0x3
	v_mov_b32_dpp v234, v238 row_ror:8 row_mask:0xf bank_mask:0x3
	v_mov_b32_dpp v235, v239 row_ror:8 row_mask:0xf bank_mask:0x3
	s_add_u32 s100, s100, 0x20000
	s_addc_u32 s101, s101, 0
	global_store_dwordx4 v240, v[228:231], s[100:101]
	s_add_u32 s100, s100, 0x20000
	s_addc_u32 s101, s101, 0
	global_store_dwordx4 v240, v[232:235], s[100:101]
	s_and_b64 vcc, exec, s[2:3]
	s_mov_b32 s40, s8
	s_mov_b32 s20, s14
	s_mov_b64 s[24:25], s[18:19]
	s_mov_b64 s[22:23], s[16:17]
	s_cbranch_vccz .LBB0_528
	s_waitcnt vmcnt(0)
	s_cmpk_gt_u32 s28, 0xff
	s_cbranch_scc1 .LBB0_535
	s_barrier

.LBB0_644:
	ds_read_b128 v[146:149], v143
	ds_read_b128 v[150:153], v143 offset:1024
	ds_read_b128 v[154:157], v143 offset:2048
	ds_read_b128 v[158:161], v143 offset:3072
	s_add_i32 s46, s18, 2
	s_add_u32 s19, s16, 0xffe00080
	s_addc_u32 s20, s17, -1
	s_cmp_eq_u32 s43, s18
	s_cselect_b32 s18, s42, s44
	s_cselect_b32 s21, s3, s20
	s_cselect_b32 s20, s5, s19
	s_cselect_b32 s19, s41, s45
	s_add_i32 m0, s26, 0xc000
	ds_read_b128 v[162:165], v144
	ds_read_b128 v[166:169], v144 offset:1024
	ds_read_b128 v[170:173], v144 offset:2048
	ds_read_b128 v[174:177], v144 offset:3072
	ds_read_b128 v[178:181], v144 offset:4096
	ds_read_b128 v[182:185], v144 offset:5120
	ds_read_b128 v[186:189], v144 offset:6144
	ds_read_b128 v[190:193], v144 offset:7168
	global_load_lds_dwordx4 v136, s[16:17]
	s_add_i32 m0, s26, 0xe000
	s_nop 0
	global_load_lds_dwordx4 v138, s[16:17]
	s_waitcnt lgkmcnt(8)
	s_barrier
	s_waitcnt lgkmcnt(0)
	s_waitcnt lgkmcnt(0)
	v_mfma_f32_16x16x32_bf16 v[124:127], v[146:149], v[162:165], v[124:127]
	v_mfma_f32_16x16x32_bf16 v[120:123], v[154:157], v[162:165], v[120:123]
	v_mfma_f32_16x16x32_bf16 v[108:111], v[146:149], v[170:173], v[108:111]
	v_mfma_f32_16x16x32_bf16 v[104:107], v[154:157], v[170:173], v[104:107]
	v_mfma_f32_16x16x32_bf16 v[92:95], v[146:149], v[178:181], v[92:95]
	v_mfma_f32_16x16x32_bf16 v[88:91], v[154:157], v[178:181], v[88:91]
	v_mfma_f32_16x16x32_bf16 v[76:79], v[146:149], v[186:189], v[76:79]
	v_mfma_f32_16x16x32_bf16 v[72:75], v[154:157], v[186:189], v[72:75]
	v_mfma_f32_16x16x32_bf16 v[124:127], v[150:153], v[166:169], v[124:127]
	v_mfma_f32_16x16x32_bf16 v[120:123], v[158:161], v[166:169], v[120:123]
	v_mfma_f32_16x16x32_bf16 v[108:111], v[150:153], v[174:177], v[108:111]
	v_mfma_f32_16x16x32_bf16 v[104:107], v[158:161], v[174:177], v[104:107]
	v_mfma_f32_16x16x32_bf16 v[92:95], v[150:153], v[182:185], v[92:95]
	v_mfma_f32_16x16x32_bf16 v[88:91], v[158:161], v[182:185], v[88:91]
	v_mfma_f32_16x16x32_bf16 v[76:79], v[150:153], v[190:193], v[76:79]
	v_mfma_f32_16x16x32_bf16 v[72:75], v[158:161], v[190:193], v[72:75]
	s_barrier
	s_add_i32 s47, s35, s25
	s_mov_b32 m0, s47
	ds_read_b128 v[194:197], v145
	ds_read_b128 v[198:201], v145 offset:1024
	ds_read_b128 v[204:207], v145 offset:2048
	ds_read_b128 v[208:211], v145 offset:3072
	global_load_lds_dwordx4 v132, s[18:19]
	s_add_i32 m0, s47, 0x2000
	s_nop 0
	global_load_lds_dwordx4 v128, s[18:19]
	s_barrier
	s_waitcnt lgkmcnt(0)
	s_waitcnt lgkmcnt(0)
	v_mfma_f32_16x16x32_bf16 v[116:119], v[194:197], v[162:165], v[116:119]
	v_mfma_f32_16x16x32_bf16 v[112:115], v[204:207], v[162:165], v[112:115]
	v_mfma_f32_16x16x32_bf16 v[100:103], v[194:197], v[170:173], v[100:103]
	v_mfma_f32_16x16x32_bf16 v[96:99], v[204:207], v[170:173], v[96:99]
	v_mfma_f32_16x16x32_bf16 v[84:87], v[194:197], v[178:181], v[84:87]
	v_mfma_f32_16x16x32_bf16 v[80:83], v[204:207], v[178:181], v[80:83]
	v_mfma_f32_16x16x32_bf16 v[68:71], v[194:197], v[186:189], v[68:71]
	v_mfma_f32_16x16x32_bf16 v[64:67], v[204:207], v[186:189], v[64:67]
	v_mfma_f32_16x16x32_bf16 v[116:119], v[198:201], v[166:169], v[116:119]
	v_mfma_f32_16x16x32_bf16 v[112:115], v[208:211], v[166:169], v[112:115]
	v_mfma_f32_16x16x32_bf16 v[100:103], v[198:201], v[174:177], v[100:103]
	v_mfma_f32_16x16x32_bf16 v[96:99], v[208:211], v[174:177], v[96:99]
	v_mfma_f32_16x16x32_bf16 v[84:87], v[198:201], v[182:185], v[84:87]
	v_mfma_f32_16x16x32_bf16 v[80:83], v[208:211], v[182:185], v[80:83]
	v_mfma_f32_16x16x32_bf16 v[68:71], v[198:201], v[190:193], v[68:71]
	v_mfma_f32_16x16x32_bf16 v[64:67], v[208:211], v[190:193], v[64:67]
	s_mov_b32 m0, s26
	s_mov_b64 s[98:99], s[20:21]
	s_barrier
	ds_read_b128 v[162:165], v144 offset:16384
	ds_read_b128 v[166:169], v144 offset:17408
	ds_read_b128 v[170:173], v144 offset:18432
	ds_read_b128 v[174:177], v144 offset:19456
	ds_read_b128 v[178:181], v144 offset:20480
	ds_read_b128 v[182:185], v144 offset:21504
	ds_read_b128 v[186:189], v144 offset:22528
	ds_read_b128 v[190:193], v144 offset:23552
	global_load_lds_dwordx4 v134, s[20:21]
	s_mov_b32 m0, s27
	s_nop 0
	global_load_lds_dwordx4 v130, s[20:21]
	s_barrier
	s_waitcnt lgkmcnt(0)
	s_waitcnt lgkmcnt(0)
	v_mfma_f32_16x16x32_bf16 v[60:63], v[146:149], v[162:165], v[60:63]
	v_mfma_f32_16x16x32_bf16 v[56:59], v[154:157], v[162:165], v[56:59]
	v_mfma_f32_16x16x32_bf16 v[44:47], v[146:149], v[170:173], v[44:47]
	v_mfma_f32_16x16x32_bf16 v[40:43], v[154:157], v[170:173], v[40:43]
	v_mfma_f32_16x16x32_bf16 v[28:31], v[146:149], v[178:181], v[28:31]
	v_mfma_f32_16x16x32_bf16 v[24:27], v[154:157], v[178:181], v[24:27]
	v_mfma_f32_16x16x32_bf16 v[12:15], v[146:149], v[186:189], v[12:15]
	v_mfma_f32_16x16x32_bf16 v[8:11], v[154:157], v[186:189], v[8:11]
	v_mfma_f32_16x16x32_bf16 v[60:63], v[150:153], v[166:169], v[60:63]
	v_mfma_f32_16x16x32_bf16 v[56:59], v[158:161], v[166:169], v[56:59]
	v_mfma_f32_16x16x32_bf16 v[44:47], v[150:153], v[174:177], v[44:47]
	v_mfma_f32_16x16x32_bf16 v[40:43], v[158:161], v[174:177], v[40:43]
	v_mfma_f32_16x16x32_bf16 v[28:31], v[150:153], v[182:185], v[28:31]
	v_mfma_f32_16x16x32_bf16 v[24:27], v[158:161], v[182:185], v[24:27]
	v_mfma_f32_16x16x32_bf16 v[12:15], v[150:153], v[190:193], v[12:15]
	v_mfma_f32_16x16x32_bf16 v[8:11], v[158:161], v[190:193], v[8:11]
	s_barrier
	s_add_u32 s48, s18, 0x80000
	s_addc_u32 s49, s19, 0
	s_add_i32 s47, s36, s25
	s_mov_b32 m0, s47
	s_nop 0
	global_load_lds_dwordx4 v132, s[48:49]
	s_add_i32 m0, s47, 0x2000
	s_nop 0
	global_load_lds_dwordx4 v128, s[48:49]
	s_waitcnt vmcnt(6)
	s_barrier
	v_mfma_f32_16x16x32_bf16 v[52:55], v[194:197], v[162:165], v[52:55]
	v_mfma_f32_16x16x32_bf16 v[48:51], v[204:207], v[162:165], v[48:51]
	v_mfma_f32_16x16x32_bf16 v[36:39], v[194:197], v[170:173], v[36:39]
	v_mfma_f32_16x16x32_bf16 v[32:35], v[204:207], v[170:173], v[32:35]
	v_mfma_f32_16x16x32_bf16 v[20:23], v[194:197], v[178:181], v[20:23]
	v_mfma_f32_16x16x32_bf16 v[16:19], v[204:207], v[178:181], v[16:19]
	v_mfma_f32_16x16x32_bf16 v[4:7], v[194:197], v[186:189], v[4:7]
	v_mfma_f32_16x16x32_bf16 v[0:3], v[204:207], v[186:189], v[0:3]
	v_mfma_f32_16x16x32_bf16 v[52:55], v[198:201], v[166:169], v[52:55]
	v_mfma_f32_16x16x32_bf16 v[48:51], v[208:211], v[166:169], v[48:51]
	v_mfma_f32_16x16x32_bf16 v[36:39], v[198:201], v[174:177], v[36:39]
	v_mfma_f32_16x16x32_bf16 v[32:35], v[208:211], v[174:177], v[32:35]
	v_mfma_f32_16x16x32_bf16 v[20:23], v[198:201], v[182:185], v[20:23]
	v_mfma_f32_16x16x32_bf16 v[16:19], v[208:211], v[182:185], v[16:19]
	v_mfma_f32_16x16x32_bf16 v[4:7], v[198:201], v[190:193], v[4:7]
	v_mfma_f32_16x16x32_bf16 v[0:3], v[208:211], v[190:193], v[0:3]
	s_add_i32 s47, 0, 0x18000
	v_add_u32_e32 v158, s47, v141
	s_barrier
	ds_read_b128 v[146:149], v158
	ds_read_b128 v[150:153], v158 offset:1024
	ds_read_b128 v[154:157], v158 offset:2048
	ds_read_b128 v[158:161], v158 offset:3072
	s_add_u32 s20, s20, 0x200000
	s_addc_u32 s21, s21, 0
	s_mov_b32 m0, s28
	ds_read_b128 v[162:165], v144 offset:32768
	ds_read_b128 v[166:169], v144 offset:33792
	ds_read_b128 v[170:173], v144 offset:34816
	ds_read_b128 v[174:177], v144 offset:35840
	ds_read_b128 v[178:181], v144 offset:36864
	ds_read_b128 v[182:185], v144 offset:37888
	ds_read_b128 v[186:189], v144 offset:38912
	ds_read_b128 v[190:193], v144 offset:39936
	global_load_lds_dwordx4 v134, s[20:21]
	s_mov_b32 m0, s29
	s_nop 0
	global_load_lds_dwordx4 v130, s[20:21]
	s_waitcnt lgkmcnt(8)
	s_barrier
	s_waitcnt lgkmcnt(0)
	s_waitcnt lgkmcnt(0)
	v_mfma_f32_16x16x32_bf16 v[124:127], v[146:149], v[162:165], v[124:127]
	v_mfma_f32_16x16x32_bf16 v[120:123], v[154:157], v[162:165], v[120:123]
	v_mfma_f32_16x16x32_bf16 v[108:111], v[146:149], v[170:173], v[108:111]
	v_mfma_f32_16x16x32_bf16 v[104:107], v[154:157], v[170:173], v[104:107]
	v_mfma_f32_16x16x32_bf16 v[92:95], v[146:149], v[178:181], v[92:95]
	v_mfma_f32_16x16x32_bf16 v[88:91], v[154:157], v[178:181], v[88:91]
	v_mfma_f32_16x16x32_bf16 v[76:79], v[146:149], v[186:189], v[76:79]
	v_mfma_f32_16x16x32_bf16 v[72:75], v[154:157], v[186:189], v[72:75]
	v_mfma_f32_16x16x32_bf16 v[124:127], v[150:153], v[166:169], v[124:127]
	v_mfma_f32_16x16x32_bf16 v[120:123], v[158:161], v[166:169], v[120:123]
	v_mfma_f32_16x16x32_bf16 v[108:111], v[150:153], v[174:177], v[108:111]
	v_mfma_f32_16x16x32_bf16 v[104:107], v[158:161], v[174:177], v[104:107]
	v_mfma_f32_16x16x32_bf16 v[92:95], v[150:153], v[182:185], v[92:95]
	v_mfma_f32_16x16x32_bf16 v[88:91], v[158:161], v[182:185], v[88:91]
	v_mfma_f32_16x16x32_bf16 v[76:79], v[150:153], v[190:193], v[76:79]
	v_mfma_f32_16x16x32_bf16 v[72:75], v[158:161], v[190:193], v[72:75]
	s_barrier
	s_add_i32 s20, 0, 0x1c000
	s_add_i32 s21, s47, s25
	v_add_u32_e32 v208, s20, v141
	s_mov_b32 m0, s21
	ds_read_b128 v[194:197], v208
	ds_read_b128 v[198:201], v208 offset:1024
	ds_read_b128 v[204:207], v208 offset:2048
	ds_read_b128 v[208:211], v208 offset:3072
	s_add_u32 s100, s18, 0x80
	s_addc_u32 s101, s19, 0
	global_load_lds_dwordx4 v132, s[100:101]
	s_add_i32 m0, s21, 0x2000
	s_nop 0
	s_add_u32 s100, s18, 0x80
	s_addc_u32 s101, s19, 0
	global_load_lds_dwordx4 v128, s[100:101]
	s_barrier
	s_waitcnt lgkmcnt(0)
	s_waitcnt lgkmcnt(0)
	v_mfma_f32_16x16x32_bf16 v[116:119], v[194:197], v[162:165], v[116:119]
	v_mfma_f32_16x16x32_bf16 v[112:115], v[204:207], v[162:165], v[112:115]
	v_mfma_f32_16x16x32_bf16 v[100:103], v[194:197], v[170:173], v[100:103]
	v_mfma_f32_16x16x32_bf16 v[96:99], v[204:207], v[170:173], v[96:99]
	v_mfma_f32_16x16x32_bf16 v[84:87], v[194:197], v[178:181], v[84:87]
	v_mfma_f32_16x16x32_bf16 v[80:83], v[204:207], v[178:181], v[80:83]
	v_mfma_f32_16x16x32_bf16 v[68:71], v[194:197], v[186:189], v[68:71]
	v_mfma_f32_16x16x32_bf16 v[64:67], v[204:207], v[186:189], v[64:67]
	v_mfma_f32_16x16x32_bf16 v[116:119], v[198:201], v[166:169], v[116:119]
	v_mfma_f32_16x16x32_bf16 v[112:115], v[208:211], v[166:169], v[112:115]
	v_mfma_f32_16x16x32_bf16 v[100:103], v[198:201], v[174:177], v[100:103]
	v_mfma_f32_16x16x32_bf16 v[96:99], v[208:211], v[174:177], v[96:99]
	v_mfma_f32_16x16x32_bf16 v[84:87], v[198:201], v[182:185], v[84:87]
	v_mfma_f32_16x16x32_bf16 v[80:83], v[208:211], v[182:185], v[80:83]
	v_mfma_f32_16x16x32_bf16 v[68:71], v[198:201], v[190:193], v[68:71]
	v_mfma_f32_16x16x32_bf16 v[64:67], v[208:211], v[190:193], v[64:67]
	s_mov_b32 m0, s30
	s_barrier
	ds_read_b128 v[162:165], v144 offset:49152
	ds_read_b128 v[166:169], v144 offset:50176
	ds_read_b128 v[170:173], v144 offset:51200
	ds_read_b128 v[174:177], v144 offset:52224
	ds_read_b128 v[178:181], v144 offset:53248
	ds_read_b128 v[182:185], v144 offset:54272
	ds_read_b128 v[186:189], v144 offset:55296
	ds_read_b128 v[190:193], v144 offset:56320
	s_add_u32 s100, s98, 0x80
	s_addc_u32 s101, s99, 0
	global_load_lds_dwordx4 v134, s[100:101]
	s_mov_b32 m0, s31
	s_nop 0
	s_add_u32 s100, s98, 0x80
	s_addc_u32 s101, s99, 0
	global_load_lds_dwordx4 v130, s[100:101]
	s_barrier
	s_waitcnt lgkmcnt(0)
	s_waitcnt lgkmcnt(0)
	v_mfma_f32_16x16x32_bf16 v[60:63], v[146:149], v[162:165], v[60:63]
	v_mfma_f32_16x16x32_bf16 v[56:59], v[154:157], v[162:165], v[56:59]
	v_mfma_f32_16x16x32_bf16 v[44:47], v[146:149], v[170:173], v[44:47]
	v_mfma_f32_16x16x32_bf16 v[40:43], v[154:157], v[170:173], v[40:43]
	v_mfma_f32_16x16x32_bf16 v[28:31], v[146:149], v[178:181], v[28:31]
	v_mfma_f32_16x16x32_bf16 v[24:27], v[154:157], v[178:181], v[24:27]
	v_mfma_f32_16x16x32_bf16 v[12:15], v[146:149], v[186:189], v[12:15]
	v_mfma_f32_16x16x32_bf16 v[8:11], v[154:157], v[186:189], v[8:11]
	v_mfma_f32_16x16x32_bf16 v[60:63], v[150:153], v[166:169], v[60:63]
	v_mfma_f32_16x16x32_bf16 v[56:59], v[158:161], v[166:169], v[56:59]
	v_mfma_f32_16x16x32_bf16 v[44:47], v[150:153], v[174:177], v[44:47]
	v_mfma_f32_16x16x32_bf16 v[40:43], v[158:161], v[174:177], v[40:43]
	v_mfma_f32_16x16x32_bf16 v[28:31], v[150:153], v[182:185], v[28:31]
	v_mfma_f32_16x16x32_bf16 v[24:27], v[158:161], v[182:185], v[24:27]
	v_mfma_f32_16x16x32_bf16 v[12:15], v[150:153], v[190:193], v[12:15]
	v_mfma_f32_16x16x32_bf16 v[8:11], v[158:161], v[190:193], v[8:11]
	s_barrier
	s_add_u32 s18, s18, 0x80080
	s_addc_u32 s19, s19, 0
	s_add_i32 s20, s20, s25
	s_mov_b32 m0, s20
	s_nop 0
	global_load_lds_dwordx4 v132, s[18:19]
	s_add_i32 m0, s20, 0x2000
	s_nop 0
	global_load_lds_dwordx4 v128, s[18:19]
	s_waitcnt vmcnt(6)
	s_barrier
	v_mfma_f32_16x16x32_bf16 v[52:55], v[194:197], v[162:165], v[52:55]
	v_mfma_f32_16x16x32_bf16 v[48:51], v[204:207], v[162:165], v[48:51]
	v_mfma_f32_16x16x32_bf16 v[36:39], v[194:197], v[170:173], v[36:39]
	v_mfma_f32_16x16x32_bf16 v[32:35], v[204:207], v[170:173], v[32:35]
	v_mfma_f32_16x16x32_bf16 v[20:23], v[194:197], v[178:181], v[20:23]
	v_mfma_f32_16x16x32_bf16 v[16:19], v[204:207], v[178:181], v[16:19]
	v_mfma_f32_16x16x32_bf16 v[4:7], v[194:197], v[186:189], v[4:7]
	v_mfma_f32_16x16x32_bf16 v[0:3], v[204:207], v[186:189], v[0:3]
	v_mfma_f32_16x16x32_bf16 v[52:55], v[198:201], v[166:169], v[52:55]
	v_mfma_f32_16x16x32_bf16 v[48:51], v[208:211], v[166:169], v[48:51]
	v_mfma_f32_16x16x32_bf16 v[36:39], v[198:201], v[174:177], v[36:39]
	v_mfma_f32_16x16x32_bf16 v[32:35], v[208:211], v[174:177], v[32:35]
	v_mfma_f32_16x16x32_bf16 v[20:23], v[198:201], v[182:185], v[20:23]
	v_mfma_f32_16x16x32_bf16 v[16:19], v[208:211], v[182:185], v[16:19]
	v_mfma_f32_16x16x32_bf16 v[4:7], v[198:201], v[190:193], v[4:7]
	v_mfma_f32_16x16x32_bf16 v[0:3], v[208:211], v[190:193], v[0:3]
	s_add_u32 s16, s16, 0x100
	s_addc_u32 s17, s17, 0
	s_add_u32 s44, s44, 0x100
	s_addc_u32 s45, s45, 0
	s_cmp_ge_i32 s46, s40
	s_mov_b32 s18, s46
	s_barrier
	s_cbranch_scc0 .LBB0_644
	s_branch .LBB0_639

.LBB0_804:
	ds_read_b128 v[154:157], v151
	ds_read_b128 v[158:161], v151 offset:1024
	ds_read_b128 v[162:165], v151 offset:2048
	ds_read_b128 v[166:169], v151 offset:3072
	s_add_u32 s22, s20, 0xfff80080
	s_addc_u32 s23, s21, -1
	s_cmp_eq_u32 s45, 28
	s_cselect_b32 s25, s9, s23
	s_cselect_b32 s24, s17, s22
	s_cselect_b32 s23, s7, s44
	s_cselect_b32 s22, s42, s43
	s_add_i32 m0, s30, 0xc000
	ds_read_b128 v[170:173], v152
	ds_read_b128 v[174:177], v152 offset:1024
	ds_read_b128 v[178:181], v152 offset:2048
	ds_read_b128 v[182:185], v152 offset:3072
	ds_read_b128 v[186:189], v152 offset:4096
	ds_read_b128 v[190:193], v152 offset:5120
	ds_read_b128 v[194:197], v152 offset:6144
	ds_read_b128 v[198:201], v152 offset:7168
	global_load_lds_dwordx4 v138, s[20:21]
	s_add_i32 m0, s30, 0xe000
	s_nop 0
	global_load_lds_dwordx4 v140, s[20:21]
	s_waitcnt lgkmcnt(8)
	s_barrier
	s_waitcnt lgkmcnt(0)
	s_waitcnt lgkmcnt(0)
	v_mfma_f32_16x16x32_bf16 v[124:127], v[154:157], v[170:173], v[124:127]
	v_mfma_f32_16x16x32_bf16 v[120:123], v[162:165], v[170:173], v[120:123]
	v_mfma_f32_16x16x32_bf16 v[116:119], v[154:157], v[178:181], v[116:119]
	v_mfma_f32_16x16x32_bf16 v[112:115], v[162:165], v[178:181], v[112:115]
	v_mfma_f32_16x16x32_bf16 v[100:103], v[154:157], v[186:189], v[100:103]
	v_mfma_f32_16x16x32_bf16 v[96:99], v[162:165], v[186:189], v[96:99]
	v_mfma_f32_16x16x32_bf16 v[84:87], v[154:157], v[194:197], v[84:87]
	v_mfma_f32_16x16x32_bf16 v[80:83], v[162:165], v[194:197], v[80:83]
	v_mfma_f32_16x16x32_bf16 v[124:127], v[158:161], v[174:177], v[124:127]
	v_mfma_f32_16x16x32_bf16 v[120:123], v[166:169], v[174:177], v[120:123]
	v_mfma_f32_16x16x32_bf16 v[116:119], v[158:161], v[182:185], v[116:119]
	v_mfma_f32_16x16x32_bf16 v[112:115], v[166:169], v[182:185], v[112:115]
	v_mfma_f32_16x16x32_bf16 v[100:103], v[158:161], v[190:193], v[100:103]
	v_mfma_f32_16x16x32_bf16 v[96:99], v[166:169], v[190:193], v[96:99]
	v_mfma_f32_16x16x32_bf16 v[84:87], v[158:161], v[198:201], v[84:87]
	v_mfma_f32_16x16x32_bf16 v[80:83], v[166:169], v[198:201], v[80:83]
	s_barrier
	s_add_i32 s46, s39, s29
	s_mov_b32 m0, s46
	ds_read_b128 v[204:207], v153
	ds_read_b128 v[208:211], v153 offset:1024
	ds_read_b128 v[212:215], v153 offset:2048
	ds_read_b128 v[216:219], v153 offset:3072
	global_load_lds_dwordx4 v132, s[22:23]
	s_add_i32 m0, s46, 0x2000
	s_nop 0
	global_load_lds_dwordx4 v128, s[22:23]
	s_barrier
	s_waitcnt lgkmcnt(0)
	s_waitcnt lgkmcnt(0)
	v_mfma_f32_16x16x32_bf16 v[108:111], v[204:207], v[170:173], v[108:111]
	v_mfma_f32_16x16x32_bf16 v[104:107], v[212:215], v[170:173], v[104:107]
	v_mfma_f32_16x16x32_bf16 v[92:95], v[204:207], v[178:181], v[92:95]
	v_mfma_f32_16x16x32_bf16 v[88:91], v[212:215], v[178:181], v[88:91]
	v_mfma_f32_16x16x32_bf16 v[76:79], v[204:207], v[186:189], v[76:79]
	v_mfma_f32_16x16x32_bf16 v[72:75], v[212:215], v[186:189], v[72:75]
	v_mfma_f32_16x16x32_bf16 v[68:71], v[204:207], v[194:197], v[68:71]
	v_mfma_f32_16x16x32_bf16 v[64:67], v[212:215], v[194:197], v[64:67]
	v_mfma_f32_16x16x32_bf16 v[108:111], v[208:211], v[174:177], v[108:111]
	v_mfma_f32_16x16x32_bf16 v[104:107], v[216:219], v[174:177], v[104:107]
	v_mfma_f32_16x16x32_bf16 v[92:95], v[208:211], v[182:185], v[92:95]
	v_mfma_f32_16x16x32_bf16 v[88:91], v[216:219], v[182:185], v[88:91]
	v_mfma_f32_16x16x32_bf16 v[76:79], v[208:211], v[190:193], v[76:79]
	v_mfma_f32_16x16x32_bf16 v[72:75], v[216:219], v[190:193], v[72:75]
	v_mfma_f32_16x16x32_bf16 v[68:71], v[208:211], v[198:201], v[68:71]
	v_mfma_f32_16x16x32_bf16 v[64:67], v[216:219], v[198:201], v[64:67]
	s_mov_b32 m0, s30
	s_mov_b64 s[98:99], s[24:25]
	s_barrier
	ds_read_b128 v[170:173], v152 offset:16384
	ds_read_b128 v[174:177], v152 offset:17408
	ds_read_b128 v[178:181], v152 offset:18432
	ds_read_b128 v[182:185], v152 offset:19456
	ds_read_b128 v[186:189], v152 offset:20480
	ds_read_b128 v[190:193], v152 offset:21504
	ds_read_b128 v[194:197], v152 offset:22528
	ds_read_b128 v[198:201], v152 offset:23552
	global_load_lds_dwordx4 v134, s[24:25]
	s_mov_b32 m0, s31
	s_nop 0
	global_load_lds_dwordx4 v130, s[24:25]
	s_barrier
	s_waitcnt lgkmcnt(0)
	s_waitcnt lgkmcnt(0)
	v_mfma_f32_16x16x32_bf16 v[60:63], v[154:157], v[170:173], v[60:63]
	v_mfma_f32_16x16x32_bf16 v[56:59], v[162:165], v[170:173], v[56:59]
	v_mfma_f32_16x16x32_bf16 v[52:55], v[154:157], v[178:181], v[52:55]
	v_mfma_f32_16x16x32_bf16 v[48:51], v[162:165], v[178:181], v[48:51]
	v_mfma_f32_16x16x32_bf16 v[36:39], v[154:157], v[186:189], v[36:39]
	v_mfma_f32_16x16x32_bf16 v[32:35], v[162:165], v[186:189], v[32:35]
	v_mfma_f32_16x16x32_bf16 v[20:23], v[154:157], v[194:197], v[20:23]
	v_mfma_f32_16x16x32_bf16 v[16:19], v[162:165], v[194:197], v[16:19]
	v_mfma_f32_16x16x32_bf16 v[60:63], v[158:161], v[174:177], v[60:63]
	v_mfma_f32_16x16x32_bf16 v[56:59], v[166:169], v[174:177], v[56:59]
	v_mfma_f32_16x16x32_bf16 v[52:55], v[158:161], v[182:185], v[52:55]
	v_mfma_f32_16x16x32_bf16 v[48:51], v[166:169], v[182:185], v[48:51]
	v_mfma_f32_16x16x32_bf16 v[36:39], v[158:161], v[190:193], v[36:39]
	v_mfma_f32_16x16x32_bf16 v[32:35], v[166:169], v[190:193], v[32:35]
	v_mfma_f32_16x16x32_bf16 v[20:23], v[158:161], v[198:201], v[20:23]
	v_mfma_f32_16x16x32_bf16 v[16:19], v[166:169], v[198:201], v[16:19]
	s_barrier
	s_add_u32 s46, s22, 0x20000
	s_addc_u32 s47, s23, 0
	s_add_i32 s48, s40, s29
	s_mov_b32 m0, s48
	s_nop 0
	global_load_lds_dwordx4 v132, s[46:47]
	s_add_i32 m0, s48, 0x2000
	s_nop 0
	global_load_lds_dwordx4 v128, s[46:47]
	s_waitcnt vmcnt(6)
	s_barrier
	v_mfma_f32_16x16x32_bf16 v[44:47], v[204:207], v[170:173], v[44:47]
	v_mfma_f32_16x16x32_bf16 v[40:43], v[212:215], v[170:173], v[40:43]
	v_mfma_f32_16x16x32_bf16 v[28:31], v[204:207], v[178:181], v[28:31]
	v_mfma_f32_16x16x32_bf16 v[24:27], v[212:215], v[178:181], v[24:27]
	v_mfma_f32_16x16x32_bf16 v[12:15], v[204:207], v[186:189], v[12:15]
	v_mfma_f32_16x16x32_bf16 v[8:11], v[212:215], v[186:189], v[8:11]
	v_mfma_f32_16x16x32_bf16 v[4:7], v[204:207], v[194:197], v[4:7]
	v_mfma_f32_16x16x32_bf16 v[0:3], v[212:215], v[194:197], v[0:3]
	v_mfma_f32_16x16x32_bf16 v[44:47], v[208:211], v[174:177], v[44:47]
	v_mfma_f32_16x16x32_bf16 v[40:43], v[216:219], v[174:177], v[40:43]
	v_mfma_f32_16x16x32_bf16 v[28:31], v[208:211], v[182:185], v[28:31]
	v_mfma_f32_16x16x32_bf16 v[24:27], v[216:219], v[182:185], v[24:27]
	v_mfma_f32_16x16x32_bf16 v[12:15], v[208:211], v[190:193], v[12:15]
	v_mfma_f32_16x16x32_bf16 v[8:11], v[216:219], v[190:193], v[8:11]
	v_mfma_f32_16x16x32_bf16 v[4:7], v[208:211], v[198:201], v[4:7]
	v_mfma_f32_16x16x32_bf16 v[0:3], v[216:219], v[198:201], v[0:3]
	s_add_i32 s46, 0, 0x18000
	v_add_u32_e32 v166, s46, v149
	s_barrier
	ds_read_b128 v[154:157], v166
	ds_read_b128 v[158:161], v166 offset:1024
	ds_read_b128 v[162:165], v166 offset:2048
	ds_read_b128 v[166:169], v166 offset:3072
	s_add_u32 s24, s24, 0x80000
	s_addc_u32 s25, s25, 0
	s_mov_b32 m0, s34
	ds_read_b128 v[170:173], v152 offset:32768
	ds_read_b128 v[174:177], v152 offset:33792
	ds_read_b128 v[178:181], v152 offset:34816
	ds_read_b128 v[182:185], v152 offset:35840
	ds_read_b128 v[186:189], v152 offset:36864
	ds_read_b128 v[190:193], v152 offset:37888
	ds_read_b128 v[194:197], v152 offset:38912
	ds_read_b128 v[198:201], v152 offset:39936
	global_load_lds_dwordx4 v134, s[24:25]
	s_mov_b32 m0, s35
	s_nop 0
	global_load_lds_dwordx4 v130, s[24:25]
	s_waitcnt lgkmcnt(8)
	s_barrier
	s_waitcnt lgkmcnt(0)
	s_waitcnt lgkmcnt(0)
	v_mfma_f32_16x16x32_bf16 v[124:127], v[154:157], v[170:173], v[124:127]
	v_mfma_f32_16x16x32_bf16 v[120:123], v[162:165], v[170:173], v[120:123]
	v_mfma_f32_16x16x32_bf16 v[116:119], v[154:157], v[178:181], v[116:119]
	v_mfma_f32_16x16x32_bf16 v[112:115], v[162:165], v[178:181], v[112:115]
	v_mfma_f32_16x16x32_bf16 v[100:103], v[154:157], v[186:189], v[100:103]
	v_mfma_f32_16x16x32_bf16 v[96:99], v[162:165], v[186:189], v[96:99]
	v_mfma_f32_16x16x32_bf16 v[84:87], v[154:157], v[194:197], v[84:87]
	v_mfma_f32_16x16x32_bf16 v[80:83], v[162:165], v[194:197], v[80:83]
	v_mfma_f32_16x16x32_bf16 v[124:127], v[158:161], v[174:177], v[124:127]
	v_mfma_f32_16x16x32_bf16 v[120:123], v[166:169], v[174:177], v[120:123]
	v_mfma_f32_16x16x32_bf16 v[116:119], v[158:161], v[182:185], v[116:119]
	v_mfma_f32_16x16x32_bf16 v[112:115], v[166:169], v[182:185], v[112:115]
	v_mfma_f32_16x16x32_bf16 v[100:103], v[158:161], v[190:193], v[100:103]
	v_mfma_f32_16x16x32_bf16 v[96:99], v[166:169], v[190:193], v[96:99]
	v_mfma_f32_16x16x32_bf16 v[84:87], v[158:161], v[198:201], v[84:87]
	v_mfma_f32_16x16x32_bf16 v[80:83], v[166:169], v[198:201], v[80:83]
	s_barrier
	s_add_i32 s24, 0, 0x1c000
	s_add_i32 s25, s46, s29
	v_add_u32_e32 v216, s24, v149
	s_mov_b32 m0, s25
	ds_read_b128 v[204:207], v216
	ds_read_b128 v[208:211], v216 offset:1024
	ds_read_b128 v[212:215], v216 offset:2048
	ds_read_b128 v[216:219], v216 offset:3072
	s_add_u32 s100, s22, 0x80
	s_addc_u32 s101, s23, 0
	global_load_lds_dwordx4 v132, s[100:101]
	s_add_i32 m0, s25, 0x2000
	s_nop 0
	s_add_u32 s100, s22, 0x80
	s_addc_u32 s101, s23, 0
	global_load_lds_dwordx4 v128, s[100:101]
	s_barrier
	s_waitcnt lgkmcnt(0)
	s_waitcnt lgkmcnt(0)
	v_mfma_f32_16x16x32_bf16 v[108:111], v[204:207], v[170:173], v[108:111]
	v_mfma_f32_16x16x32_bf16 v[104:107], v[212:215], v[170:173], v[104:107]
	v_mfma_f32_16x16x32_bf16 v[92:95], v[204:207], v[178:181], v[92:95]
	v_mfma_f32_16x16x32_bf16 v[88:91], v[212:215], v[178:181], v[88:91]
	v_mfma_f32_16x16x32_bf16 v[76:79], v[204:207], v[186:189], v[76:79]
	v_mfma_f32_16x16x32_bf16 v[72:75], v[212:215], v[186:189], v[72:75]
	v_mfma_f32_16x16x32_bf16 v[68:71], v[204:207], v[194:197], v[68:71]
	v_mfma_f32_16x16x32_bf16 v[64:67], v[212:215], v[194:197], v[64:67]
	v_mfma_f32_16x16x32_bf16 v[108:111], v[208:211], v[174:177], v[108:111]
	v_mfma_f32_16x16x32_bf16 v[104:107], v[216:219], v[174:177], v[104:107]
	v_mfma_f32_16x16x32_bf16 v[92:95], v[208:211], v[182:185], v[92:95]
	v_mfma_f32_16x16x32_bf16 v[88:91], v[216:219], v[182:185], v[88:91]
	v_mfma_f32_16x16x32_bf16 v[76:79], v[208:211], v[190:193], v[76:79]
	v_mfma_f32_16x16x32_bf16 v[72:75], v[216:219], v[190:193], v[72:75]
	v_mfma_f32_16x16x32_bf16 v[68:71], v[208:211], v[198:201], v[68:71]
	v_mfma_f32_16x16x32_bf16 v[64:67], v[216:219], v[198:201], v[64:67]
	s_mov_b32 m0, s37
	s_barrier
	ds_read_b128 v[170:173], v152 offset:49152
	ds_read_b128 v[174:177], v152 offset:50176
	ds_read_b128 v[178:181], v152 offset:51200
	ds_read_b128 v[182:185], v152 offset:52224
	ds_read_b128 v[186:189], v152 offset:53248
	ds_read_b128 v[190:193], v152 offset:54272
	ds_read_b128 v[194:197], v152 offset:55296
	ds_read_b128 v[198:201], v152 offset:56320
	s_add_u32 s100, s98, 0x80
	s_addc_u32 s101, s99, 0
	global_load_lds_dwordx4 v134, s[100:101]
	s_mov_b32 m0, s38
	s_nop 0
	s_add_u32 s100, s98, 0x80
	s_addc_u32 s101, s99, 0
	global_load_lds_dwordx4 v130, s[100:101]
	s_barrier
	s_waitcnt lgkmcnt(0)
	s_waitcnt lgkmcnt(0)
	v_mfma_f32_16x16x32_bf16 v[60:63], v[154:157], v[170:173], v[60:63]
	v_mfma_f32_16x16x32_bf16 v[56:59], v[162:165], v[170:173], v[56:59]
	v_mfma_f32_16x16x32_bf16 v[52:55], v[154:157], v[178:181], v[52:55]
	v_mfma_f32_16x16x32_bf16 v[48:51], v[162:165], v[178:181], v[48:51]
	v_mfma_f32_16x16x32_bf16 v[36:39], v[154:157], v[186:189], v[36:39]
	v_mfma_f32_16x16x32_bf16 v[32:35], v[162:165], v[186:189], v[32:35]
	v_mfma_f32_16x16x32_bf16 v[20:23], v[154:157], v[194:197], v[20:23]
	v_mfma_f32_16x16x32_bf16 v[16:19], v[162:165], v[194:197], v[16:19]
	v_mfma_f32_16x16x32_bf16 v[60:63], v[158:161], v[174:177], v[60:63]
	v_mfma_f32_16x16x32_bf16 v[56:59], v[166:169], v[174:177], v[56:59]
	v_mfma_f32_16x16x32_bf16 v[52:55], v[158:161], v[182:185], v[52:55]
	v_mfma_f32_16x16x32_bf16 v[48:51], v[166:169], v[182:185], v[48:51]
	v_mfma_f32_16x16x32_bf16 v[36:39], v[158:161], v[190:193], v[36:39]
	v_mfma_f32_16x16x32_bf16 v[32:35], v[166:169], v[190:193], v[32:35]
	v_mfma_f32_16x16x32_bf16 v[20:23], v[158:161], v[198:201], v[20:23]
	v_mfma_f32_16x16x32_bf16 v[16:19], v[166:169], v[198:201], v[16:19]
	s_barrier
	s_add_u32 s22, s22, 0x20080
	s_addc_u32 s23, s23, 0
	s_add_i32 s24, s24, s29
	s_mov_b32 m0, s24
	s_nop 0
	global_load_lds_dwordx4 v132, s[22:23]
	s_add_i32 m0, s24, 0x2000
	s_nop 0
	global_load_lds_dwordx4 v128, s[22:23]
	s_waitcnt vmcnt(6)
	s_barrier
	v_mfma_f32_16x16x32_bf16 v[44:47], v[204:207], v[170:173], v[44:47]
	v_mfma_f32_16x16x32_bf16 v[40:43], v[212:215], v[170:173], v[40:43]
	v_mfma_f32_16x16x32_bf16 v[28:31], v[204:207], v[178:181], v[28:31]
	v_mfma_f32_16x16x32_bf16 v[24:27], v[212:215], v[178:181], v[24:27]
	v_mfma_f32_16x16x32_bf16 v[12:15], v[204:207], v[186:189], v[12:15]
	v_mfma_f32_16x16x32_bf16 v[8:11], v[212:215], v[186:189], v[8:11]
	v_mfma_f32_16x16x32_bf16 v[4:7], v[204:207], v[194:197], v[4:7]
	v_mfma_f32_16x16x32_bf16 v[0:3], v[212:215], v[194:197], v[0:3]
	v_mfma_f32_16x16x32_bf16 v[44:47], v[208:211], v[174:177], v[44:47]
	v_mfma_f32_16x16x32_bf16 v[40:43], v[216:219], v[174:177], v[40:43]
	v_mfma_f32_16x16x32_bf16 v[28:31], v[208:211], v[182:185], v[28:31]
	v_mfma_f32_16x16x32_bf16 v[24:27], v[216:219], v[182:185], v[24:27]
	v_mfma_f32_16x16x32_bf16 v[12:15], v[208:211], v[190:193], v[12:15]
	v_mfma_f32_16x16x32_bf16 v[8:11], v[216:219], v[190:193], v[8:11]
	v_mfma_f32_16x16x32_bf16 v[4:7], v[208:211], v[198:201], v[4:7]
	v_mfma_f32_16x16x32_bf16 v[0:3], v[216:219], v[198:201], v[0:3]
	s_add_i32 s45, s45, 2
	s_add_u32 s20, s20, 0x100
	s_addc_u32 s21, s21, 0
	s_add_u32 s43, s43, 0x100
	s_addc_u32 s44, s44, 0
	s_cmp_gt_u32 s45, 29
	s_barrier
	s_cbranch_scc0 .LBB0_804
	v_and_b32_e32 v242, 15, v202
	v_bfe_u32 v243, v202, 4, 2
	v_bfe_u32 v244, v202, 6, 2
	v_lshrrev_b32_e32 v245, 8, v202
	s_cmp_gt_i32 s41, 47
	s_cbranch_scc1 .Lfl8_ba
	s_cmp_gt_i32 s41, 31
	s_cbranch_scc1 .Lfl8_z
	v_readlane_b32 s100, v248, 63
	v_readlane_b32 s101, v247, 0
	v_and_b32_e32 v240, 7, v242
	v_lshl_add_u32 v240, v245, 6, v240
	v_lshl_add_u32 v240, s16, 8, v240
	v_lshlrev_b32_e32 v240, 14, v240
	v_lshrrev_b32_e32 v241, 3, v242
	v_lshlrev_b32_e32 v241, 6, v241
	v_lshl_add_u32 v241, v244, 7, v241
	v_lshl_add_u32 v241, v243, 4, v241
	v_add_u32_e32 v240, v240, v241
	s_lshl_b32 s98, s41, 9
	v_add_u32_e32 v240, s98, v240
	v_cvt_pk_bf16_f32 v228, v124, v125
	v_cvt_pk_bf16_f32 v229, v126, v127
	v_cvt_pk_bf16_f32 v230, v120, v121
	v_cvt_pk_bf16_f32 v231, v122, v123
	v_cvt_pk_bf16_f32 v232, v108, v109
	v_cvt_pk_bf16_f32 v233, v110, v111
	v_cvt_pk_bf16_f32 v234, v104, v105
	v_cvt_pk_bf16_f32 v235, v106, v107
	v_mov_b32_e32 v236, v228
	v_mov_b32_e32 v237, v229
	v_mov_b32_e32 v238, v230
	v_mov_b32_e32 v239, v231
	v_mov_b32_dpp v228, v232 row_ror:8 row_mask:0xf bank_mask:0xc
	v_mov_b32_dpp v229, v233 row_ror:8 row_mask:0xf bank_mask:0xc
	v_mov_b32_dpp v230, v234 row_ror:8 row_mask:0xf bank_mask:0xc
	v_mov_b32_dpp v231, v235 row_ror:8 row_mask:0xf bank_mask:0xc
	v_mov_b32_dpp v232, v236 row_ror:8 row_mask:0xf bank_mask:0x3
	v_mov_b32_dpp v233, v237 row_ror:8 row_mask:0xf bank_mask:0x3
	v_mov_b32_dpp v234, v238 row_ror:8 row_mask:0xf bank_mask:0x3
	v_mov_b32_dpp v235, v239 row_ror:8 row_mask:0xf bank_mask:0x3
	global_store_dwordx4 v240, v[228:231], s[100:101]
	s_add_u32 s100, s100, 0x20000
	s_addc_u32 s101, s101, 0
	global_store_dwordx4 v240, v[232:235], s[100:101]
	v_cvt_pk_bf16_f32 v228, v116, v117
	v_cvt_pk_bf16_f32 v229, v118, v119
	v_cvt_pk_bf16_f32 v230, v112, v113
	v_cvt_pk_bf16_f32 v231, v114, v115
	v_cvt_pk_bf16_f32 v232, v92, v93
	v_cvt_pk_bf16_f32 v233, v94, v95
	v_cvt_pk_bf16_f32 v234, v88, v89
	v_cvt_pk_bf16_f32 v235, v90, v91
	v_mov_b32_e32 v236, v228
	v_mov_b32_e32 v237, v229
	v_mov_b32_e32 v238, v230
	v_mov_b32_e32 v239, v231
	v_mov_b32_dpp v228, v232 row_ror:8 row_mask:0xf bank_mask:0xc
	v_mov_b32_dpp v229, v233 row_ror:8 row_mask:0xf bank_mask:0xc
	v_mov_b32_dpp v230, v234 row_ror:8 row_mask:0xf bank_mask:0xc
	v_mov_b32_dpp v231, v235 row_ror:8 row_mask:0xf bank_mask:0xc
	v_mov_b32_dpp v232, v236 row_ror:8 row_mask:0xf bank_mask:0x3
	v_mov_b32_dpp v233, v237 row_ror:8 row_mask:0xf bank_mask:0x3
	v_mov_b32_dpp v234, v238 row_ror:8 row_mask:0xf bank_mask:0x3
	v_mov_b32_dpp v235, v239 row_ror:8 row_mask:0xf bank_mask:0x3
	s_add_u32 s100, s100, 0x20000
	s_addc_u32 s101, s101, 0
	global_store_dwordx4 v240, v[228:231], s[100:101]
	s_add_u32 s100, s100, 0x20000
	s_addc_u32 s101, s101, 0
	global_store_dwordx4 v240, v[232:235], s[100:101]
	v_cvt_pk_bf16_f32 v228, v100, v101
	v_cvt_pk_bf16_f32 v229, v102, v103
	v_cvt_pk_bf16_f32 v230, v96, v97
	v_cvt_pk_bf16_f32 v231, v98, v99
	v_cvt_pk_bf16_f32 v232, v76, v77
	v_cvt_pk_bf16_f32 v233, v78, v79
	v_cvt_pk_bf16_f32 v234, v72, v73
	v_cvt_pk_bf16_f32 v235, v74, v75
	v_mov_b32_e32 v236, v228
	v_mov_b32_e32 v237, v229
	v_mov_b32_e32 v238, v230
	v_mov_b32_e32 v239, v231
	v_mov_b32_dpp v228, v232 row_ror:8 row_mask:0xf bank_mask:0xc
	v_mov_b32_dpp v229, v233 row_ror:8 row_mask:0xf bank_mask:0xc
	v_mov_b32_dpp v230, v234 row_ror:8 row_mask:0xf bank_mask:0xc
	v_mov_b32_dpp v231, v235 row_ror:8 row_mask:0xf bank_mask:0xc
	v_mov_b32_dpp v232, v236 row_ror:8 row_mask:0xf bank_mask:0x3
	v_mov_b32_dpp v233, v237 row_ror:8 row_mask:0xf bank_mask:0x3
	v_mov_b32_dpp v234, v238 row_ror:8 row_mask:0xf bank_mask:0x3
	v_mov_b32_dpp v235, v239 row_ror:8 row_mask:0xf bank_mask:0x3
	s_add_u32 s100, s100, 0x20000
	s_addc_u32 s101, s101, 0
	global_store_dwordx4 v240, v[228:231], s[100:101]
	s_add_u32 s100, s100, 0x20000
	s_addc_u32 s101, s101, 0
	global_store_dwordx4 v240, v[232:235], s[100:101]
	v_cvt_pk_bf16_f32 v228, v84, v85
	v_cvt_pk_bf16_f32 v229, v86, v87
	v_cvt_pk_bf16_f32 v230, v80, v81
	v_cvt_pk_bf16_f32 v231, v82, v83
	v_cvt_pk_bf16_f32 v232, v68, v69
	v_cvt_pk_bf16_f32 v233, v70, v71
	v_cvt_pk_bf16_f32 v234, v64, v65
	v_cvt_pk_bf16_f32 v235, v66, v67
	v_mov_b32_e32 v236, v228
	v_mov_b32_e32 v237, v229
	v_mov_b32_e32 v238, v230
	v_mov_b32_e32 v239, v231
	v_mov_b32_dpp v228, v232 row_ror:8 row_mask:0xf bank_mask:0xc
	v_mov_b32_dpp v229, v233 row_ror:8 row_mask:0xf bank_mask:0xc
	v_mov_b32_dpp v230, v234 row_ror:8 row_mask:0xf bank_mask:0xc
	v_mov_b32_dpp v231, v235 row_ror:8 row_mask:0xf bank_mask:0xc
	v_mov_b32_dpp v232, v236 row_ror:8 row_mask:0xf bank_mask:0x3
	v_mov_b32_dpp v233, v237 row_ror:8 row_mask:0xf bank_mask:0x3
	v_mov_b32_dpp v234, v238 row_ror:8 row_mask:0xf bank_mask:0x3
	v_mov_b32_dpp v235, v239 row_ror:8 row_mask:0xf bank_mask:0x3
	s_add_u32 s100, s100, 0x20000
	s_addc_u32 s101, s101, 0
	global_store_dwordx4 v240, v[228:231], s[100:101]
	s_add_u32 s100, s100, 0x20000
	s_addc_u32 s101, s101, 0
	global_store_dwordx4 v240, v[232:235], s[100:101]
	v_cvt_pk_bf16_f32 v228, v60, v61
	v_cvt_pk_bf16_f32 v229, v62, v63
	v_cvt_pk_bf16_f32 v230, v56, v57
	v_cvt_pk_bf16_f32 v231, v58, v59
	v_cvt_pk_bf16_f32 v232, v44, v45
	v_cvt_pk_bf16_f32 v233, v46, v47
	v_cvt_pk_bf16_f32 v234, v40, v41
	v_cvt_pk_bf16_f32 v235, v42, v43
	v_mov_b32_e32 v236, v228
	v_mov_b32_e32 v237, v229
	v_mov_b32_e32 v238, v230
	v_mov_b32_e32 v239, v231
	v_mov_b32_dpp v228, v232 row_ror:8 row_mask:0xf bank_mask:0xc
	v_mov_b32_dpp v229, v233 row_ror:8 row_mask:0xf bank_mask:0xc
	v_mov_b32_dpp v230, v234 row_ror:8 row_mask:0xf bank_mask:0xc
	v_mov_b32_dpp v231, v235 row_ror:8 row_mask:0xf bank_mask:0xc
	v_mov_b32_dpp v232, v236 row_ror:8 row_mask:0xf bank_mask:0x3
	v_mov_b32_dpp v233, v237 row_ror:8 row_mask:0xf bank_mask:0x3
	v_mov_b32_dpp v234, v238 row_ror:8 row_mask:0xf bank_mask:0x3
	v_mov_b32_dpp v235, v239 row_ror:8 row_mask:0xf bank_mask:0x3
	s_add_u32 s100, s100, 0x120000
	s_addc_u32 s101, s101, 0
	global_store_dwordx4 v240, v[228:231], s[100:101]
	s_add_u32 s100, s100, 0x20000
	s_addc_u32 s101, s101, 0
	global_store_dwordx4 v240, v[232:235], s[100:101]
	v_cvt_pk_bf16_f32 v228, v52, v53
	v_cvt_pk_bf16_f32 v229, v54, v55
	v_cvt_pk_bf16_f32 v230, v48, v49
	v_cvt_pk_bf16_f32 v231, v50, v51
	v_cvt_pk_bf16_f32 v232, v28, v29
	v_cvt_pk_bf16_f32 v233, v30, v31
	v_cvt_pk_bf16_f32 v234, v24, v25
	v_cvt_pk_bf16_f32 v235, v26, v27
	v_mov_b32_e32 v236, v228
	v_mov_b32_e32 v237, v229
	v_mov_b32_e32 v238, v230
	v_mov_b32_e32 v239, v231
	v_mov_b32_dpp v228, v232 row_ror:8 row_mask:0xf bank_mask:0xc
	v_mov_b32_dpp v229, v233 row_ror:8 row_mask:0xf bank_mask:0xc
	v_mov_b32_dpp v230, v234 row_ror:8 row_mask:0xf bank_mask:0xc
	v_mov_b32_dpp v231, v235 row_ror:8 row_mask:0xf bank_mask:0xc
	v_mov_b32_dpp v232, v236 row_ror:8 row_mask:0xf bank_mask:0x3
	v_mov_b32_dpp v233, v237 row_ror:8 row_mask:0xf bank_mask:0x3
	v_mov_b32_dpp v234, v238 row_ror:8 row_mask:0xf bank_mask:0x3
	v_mov_b32_dpp v235, v239 row_ror:8 row_mask:0xf bank_mask:0x3
	s_add_u32 s100, s100, 0x20000
	s_addc_u32 s101, s101, 0
	global_store_dwordx4 v240, v[228:231], s[100:101]
	s_add_u32 s100, s100, 0x20000
	s_addc_u32 s101, s101, 0
	global_store_dwordx4 v240, v[232:235], s[100:101]
	v_cvt_pk_bf16_f32 v228, v36, v37
	v_cvt_pk_bf16_f32 v229, v38, v39
	v_cvt_pk_bf16_f32 v230, v32, v33
	v_cvt_pk_bf16_f32 v231, v34, v35
	v_cvt_pk_bf16_f32 v232, v12, v13
	v_cvt_pk_bf16_f32 v233, v14, v15
	v_cvt_pk_bf16_f32 v234, v8, v9
	v_cvt_pk_bf16_f32 v235, v10, v11
	v_mov_b32_e32 v236, v228
	v_mov_b32_e32 v237, v229
	v_mov_b32_e32 v238, v230
	v_mov_b32_e32 v239, v231
	v_mov_b32_dpp v228, v232 row_ror:8 row_mask:0xf bank_mask:0xc
	v_mov_b32_dpp v229, v233 row_ror:8 row_mask:0xf bank_mask:0xc
	v_mov_b32_dpp v230, v234 row_ror:8 row_mask:0xf bank_mask:0xc
	v_mov_b32_dpp v231, v235 row_ror:8 row_mask:0xf bank_mask:0xc
	v_mov_b32_dpp v232, v236 row_ror:8 row_mask:0xf bank_mask:0x3
	v_mov_b32_dpp v233, v237 row_ror:8 row_mask:0xf bank_mask:0x3
	v_mov_b32_dpp v234, v238 row_ror:8 row_mask:0xf bank_mask:0x3
	v_mov_b32_dpp v235, v239 row_ror:8 row_mask:0xf bank_mask:0x3
	s_add_u32 s100, s100, 0x20000
	s_addc_u32 s101, s101, 0
	global_store_dwordx4 v240, v[228:231], s[100:101]
	s_add_u32 s100, s100, 0x20000
	s_addc_u32 s101, s101, 0
	global_store_dwordx4 v240, v[232:235], s[100:101]
	v_cvt_pk_bf16_f32 v228, v20, v21
	v_cvt_pk_bf16_f32 v229, v22, v23
	v_cvt_pk_bf16_f32 v230, v16, v17
	v_cvt_pk_bf16_f32 v231, v18, v19
	v_cvt_pk_bf16_f32 v232, v4, v5
	v_cvt_pk_bf16_f32 v233, v6, v7
	v_cvt_pk_bf16_f32 v234, v0, v1
	v_cvt_pk_bf16_f32 v235, v2, v3
	v_mov_b32_e32 v236, v228
	v_mov_b32_e32 v237, v229
	v_mov_b32_e32 v238, v230
	v_mov_b32_e32 v239, v231
	v_mov_b32_dpp v228, v232 row_ror:8 row_mask:0xf bank_mask:0xc
	v_mov_b32_dpp v229, v233 row_ror:8 row_mask:0xf bank_mask:0xc
	v_mov_b32_dpp v230, v234 row_ror:8 row_mask:0xf bank_mask:0xc
	v_mov_b32_dpp v231, v235 row_ror:8 row_mask:0xf bank_mask:0xc
	v_mov_b32_dpp v232, v236 row_ror:8 row_mask:0xf bank_mask:0x3
	v_mov_b32_dpp v233, v237 row_ror:8 row_mask:0xf bank_mask:0x3
	v_mov_b32_dpp v234, v238 row_ror:8 row_mask:0xf bank_mask:0x3
	v_mov_b32_dpp v235, v239 row_ror:8 row_mask:0xf bank_mask:0x3
	s_add_u32 s100, s100, 0x20000
	s_addc_u32 s101, s101, 0
	global_store_dwordx4 v240, v[228:231], s[100:101]
	s_add_u32 s100, s100, 0x20000
	s_addc_u32 s101, s101, 0
	global_store_dwordx4 v240, v[232:235], s[100:101]
	s_branch .Lfl8_done

.LBB0_1409:
	ds_read_b128 v[146:149], v143
	ds_read_b128 v[150:153], v143 offset:1024
	ds_read_b128 v[154:157], v143 offset:2048
	ds_read_b128 v[158:161], v143 offset:3072
	s_add_i32 s51, s20, 2
	s_add_u32 s21, s18, 0xfff00080
	s_addc_u32 s22, s19, -1
	s_cmp_eq_u32 s48, s20
	s_cselect_b32 s20, s47, s49
	s_cselect_b32 s23, s7, s22
	s_cselect_b32 s22, s9, s21
	s_cselect_b32 s21, s46, s50
	s_add_i32 m0, s3, 0xc000
	ds_read_b128 v[162:165], v144
	ds_read_b128 v[166:169], v144 offset:1024
	ds_read_b128 v[170:173], v144 offset:2048
	ds_read_b128 v[174:177], v144 offset:3072
	ds_read_b128 v[178:181], v144 offset:4096
	ds_read_b128 v[182:185], v144 offset:5120
	ds_read_b128 v[186:189], v144 offset:6144
	ds_read_b128 v[190:193], v144 offset:7168
	global_load_lds_dwordx4 v136, s[18:19]
	s_add_i32 m0, s3, 0xe000
	s_nop 0
	global_load_lds_dwordx4 v138, s[18:19]
	s_waitcnt lgkmcnt(8)
	s_barrier
	s_waitcnt lgkmcnt(0)
	s_waitcnt lgkmcnt(0)
	v_mfma_f32_16x16x32_bf16 v[124:127], v[146:149], v[162:165], v[124:127]
	v_mfma_f32_16x16x32_bf16 v[120:123], v[154:157], v[162:165], v[120:123]
	v_mfma_f32_16x16x32_bf16 v[108:111], v[146:149], v[170:173], v[108:111]
	v_mfma_f32_16x16x32_bf16 v[104:107], v[154:157], v[170:173], v[104:107]
	v_mfma_f32_16x16x32_bf16 v[92:95], v[146:149], v[178:181], v[92:95]
	v_mfma_f32_16x16x32_bf16 v[88:91], v[154:157], v[178:181], v[88:91]
	v_mfma_f32_16x16x32_bf16 v[76:79], v[146:149], v[186:189], v[76:79]
	v_mfma_f32_16x16x32_bf16 v[72:75], v[154:157], v[186:189], v[72:75]
	v_mfma_f32_16x16x32_bf16 v[124:127], v[150:153], v[166:169], v[124:127]
	v_mfma_f32_16x16x32_bf16 v[120:123], v[158:161], v[166:169], v[120:123]
	v_mfma_f32_16x16x32_bf16 v[108:111], v[150:153], v[174:177], v[108:111]
	v_mfma_f32_16x16x32_bf16 v[104:107], v[158:161], v[174:177], v[104:107]
	v_mfma_f32_16x16x32_bf16 v[92:95], v[150:153], v[182:185], v[92:95]
	v_mfma_f32_16x16x32_bf16 v[88:91], v[158:161], v[182:185], v[88:91]
	v_mfma_f32_16x16x32_bf16 v[76:79], v[150:153], v[190:193], v[76:79]
	v_mfma_f32_16x16x32_bf16 v[72:75], v[158:161], v[190:193], v[72:75]
	s_barrier
	s_add_i32 s52, s39, s27
	s_mov_b32 m0, s52
	ds_read_b128 v[194:197], v145
	ds_read_b128 v[198:201], v145 offset:1024
	ds_read_b128 v[204:207], v145 offset:2048
	ds_read_b128 v[208:211], v145 offset:3072
	global_load_lds_dwordx4 v132, s[20:21]
	s_add_i32 m0, s52, 0x2000
	s_nop 0
	global_load_lds_dwordx4 v128, s[20:21]
	s_barrier
	s_waitcnt lgkmcnt(0)
	s_waitcnt lgkmcnt(0)
	v_mfma_f32_16x16x32_bf16 v[116:119], v[194:197], v[162:165], v[116:119]
	v_mfma_f32_16x16x32_bf16 v[112:115], v[204:207], v[162:165], v[112:115]
	v_mfma_f32_16x16x32_bf16 v[100:103], v[194:197], v[170:173], v[100:103]
	v_mfma_f32_16x16x32_bf16 v[96:99], v[204:207], v[170:173], v[96:99]
	v_mfma_f32_16x16x32_bf16 v[84:87], v[194:197], v[178:181], v[84:87]
	v_mfma_f32_16x16x32_bf16 v[80:83], v[204:207], v[178:181], v[80:83]
	v_mfma_f32_16x16x32_bf16 v[68:71], v[194:197], v[186:189], v[68:71]
	v_mfma_f32_16x16x32_bf16 v[64:67], v[204:207], v[186:189], v[64:67]
	v_mfma_f32_16x16x32_bf16 v[116:119], v[198:201], v[166:169], v[116:119]
	v_mfma_f32_16x16x32_bf16 v[112:115], v[208:211], v[166:169], v[112:115]
	v_mfma_f32_16x16x32_bf16 v[100:103], v[198:201], v[174:177], v[100:103]
	v_mfma_f32_16x16x32_bf16 v[96:99], v[208:211], v[174:177], v[96:99]
	v_mfma_f32_16x16x32_bf16 v[84:87], v[198:201], v[182:185], v[84:87]
	v_mfma_f32_16x16x32_bf16 v[80:83], v[208:211], v[182:185], v[80:83]
	v_mfma_f32_16x16x32_bf16 v[68:71], v[198:201], v[190:193], v[68:71]
	v_mfma_f32_16x16x32_bf16 v[64:67], v[208:211], v[190:193], v[64:67]
	s_mov_b32 m0, s3
	s_mov_b64 s[98:99], s[22:23]
	s_barrier
	ds_read_b128 v[162:165], v144 offset:16384
	ds_read_b128 v[166:169], v144 offset:17408
	ds_read_b128 v[170:173], v144 offset:18432
	ds_read_b128 v[174:177], v144 offset:19456
	ds_read_b128 v[178:181], v144 offset:20480
	ds_read_b128 v[182:185], v144 offset:21504
	ds_read_b128 v[186:189], v144 offset:22528
	ds_read_b128 v[190:193], v144 offset:23552
	global_load_lds_dwordx4 v134, s[22:23]
	s_mov_b32 m0, s28
	s_nop 0
	global_load_lds_dwordx4 v130, s[22:23]
	s_barrier
	s_waitcnt lgkmcnt(0)
	s_waitcnt lgkmcnt(0)
	v_mfma_f32_16x16x32_bf16 v[60:63], v[146:149], v[162:165], v[60:63]
	v_mfma_f32_16x16x32_bf16 v[56:59], v[154:157], v[162:165], v[56:59]
	v_mfma_f32_16x16x32_bf16 v[44:47], v[146:149], v[170:173], v[44:47]
	v_mfma_f32_16x16x32_bf16 v[40:43], v[154:157], v[170:173], v[40:43]
	v_mfma_f32_16x16x32_bf16 v[28:31], v[146:149], v[178:181], v[28:31]
	v_mfma_f32_16x16x32_bf16 v[24:27], v[154:157], v[178:181], v[24:27]
	v_mfma_f32_16x16x32_bf16 v[12:15], v[146:149], v[186:189], v[12:15]
	v_mfma_f32_16x16x32_bf16 v[8:11], v[154:157], v[186:189], v[8:11]
	v_mfma_f32_16x16x32_bf16 v[60:63], v[150:153], v[166:169], v[60:63]
	v_mfma_f32_16x16x32_bf16 v[56:59], v[158:161], v[166:169], v[56:59]
	v_mfma_f32_16x16x32_bf16 v[44:47], v[150:153], v[174:177], v[44:47]
	v_mfma_f32_16x16x32_bf16 v[40:43], v[158:161], v[174:177], v[40:43]
	v_mfma_f32_16x16x32_bf16 v[28:31], v[150:153], v[182:185], v[28:31]
	v_mfma_f32_16x16x32_bf16 v[24:27], v[158:161], v[182:185], v[24:27]
	v_mfma_f32_16x16x32_bf16 v[12:15], v[150:153], v[190:193], v[12:15]
	v_mfma_f32_16x16x32_bf16 v[8:11], v[158:161], v[190:193], v[8:11]
	s_barrier
	s_add_u32 s52, s20, 0x40000
	s_addc_u32 s53, s21, 0
	s_add_i32 s54, s40, s27
	s_mov_b32 m0, s54
	s_nop 0
	global_load_lds_dwordx4 v132, s[52:53]
	s_add_i32 m0, s54, 0x2000
	s_nop 0
	global_load_lds_dwordx4 v128, s[52:53]
	s_waitcnt vmcnt(6)
	s_barrier
	v_mfma_f32_16x16x32_bf16 v[52:55], v[194:197], v[162:165], v[52:55]
	v_mfma_f32_16x16x32_bf16 v[48:51], v[204:207], v[162:165], v[48:51]
	v_mfma_f32_16x16x32_bf16 v[36:39], v[194:197], v[170:173], v[36:39]
	v_mfma_f32_16x16x32_bf16 v[32:35], v[204:207], v[170:173], v[32:35]
	v_mfma_f32_16x16x32_bf16 v[20:23], v[194:197], v[178:181], v[20:23]
	v_mfma_f32_16x16x32_bf16 v[16:19], v[204:207], v[178:181], v[16:19]
	v_mfma_f32_16x16x32_bf16 v[4:7], v[194:197], v[186:189], v[4:7]
	v_mfma_f32_16x16x32_bf16 v[0:3], v[204:207], v[186:189], v[0:3]
	v_mfma_f32_16x16x32_bf16 v[52:55], v[198:201], v[166:169], v[52:55]
	v_mfma_f32_16x16x32_bf16 v[48:51], v[208:211], v[166:169], v[48:51]
	v_mfma_f32_16x16x32_bf16 v[36:39], v[198:201], v[174:177], v[36:39]
	v_mfma_f32_16x16x32_bf16 v[32:35], v[208:211], v[174:177], v[32:35]
	v_mfma_f32_16x16x32_bf16 v[20:23], v[198:201], v[182:185], v[20:23]
	v_mfma_f32_16x16x32_bf16 v[16:19], v[208:211], v[182:185], v[16:19]
	v_mfma_f32_16x16x32_bf16 v[4:7], v[198:201], v[190:193], v[4:7]
	v_mfma_f32_16x16x32_bf16 v[0:3], v[208:211], v[190:193], v[0:3]
	s_add_i32 s52, 0, 0x18000
	v_add_u32_e32 v158, s52, v141
	s_barrier
	ds_read_b128 v[146:149], v158
	ds_read_b128 v[150:153], v158 offset:1024
	ds_read_b128 v[154:157], v158 offset:2048
	ds_read_b128 v[158:161], v158 offset:3072
	s_add_u32 s22, s22, 0x100000
	s_addc_u32 s23, s23, 0
	s_mov_b32 m0, s29
	ds_read_b128 v[162:165], v144 offset:32768
	ds_read_b128 v[166:169], v144 offset:33792
	ds_read_b128 v[170:173], v144 offset:34816
	ds_read_b128 v[174:177], v144 offset:35840
	ds_read_b128 v[178:181], v144 offset:36864
	ds_read_b128 v[182:185], v144 offset:37888
	ds_read_b128 v[186:189], v144 offset:38912
	ds_read_b128 v[190:193], v144 offset:39936
	global_load_lds_dwordx4 v134, s[22:23]
	s_mov_b32 m0, s30
	s_nop 0
	global_load_lds_dwordx4 v130, s[22:23]
	s_waitcnt lgkmcnt(8)
	s_barrier
	s_waitcnt lgkmcnt(0)
	s_waitcnt lgkmcnt(0)
	v_mfma_f32_16x16x32_bf16 v[124:127], v[146:149], v[162:165], v[124:127]
	v_mfma_f32_16x16x32_bf16 v[120:123], v[154:157], v[162:165], v[120:123]
	v_mfma_f32_16x16x32_bf16 v[108:111], v[146:149], v[170:173], v[108:111]
	v_mfma_f32_16x16x32_bf16 v[104:107], v[154:157], v[170:173], v[104:107]
	v_mfma_f32_16x16x32_bf16 v[92:95], v[146:149], v[178:181], v[92:95]
	v_mfma_f32_16x16x32_bf16 v[88:91], v[154:157], v[178:181], v[88:91]
	v_mfma_f32_16x16x32_bf16 v[76:79], v[146:149], v[186:189], v[76:79]
	v_mfma_f32_16x16x32_bf16 v[72:75], v[154:157], v[186:189], v[72:75]
	v_mfma_f32_16x16x32_bf16 v[124:127], v[150:153], v[166:169], v[124:127]
	v_mfma_f32_16x16x32_bf16 v[120:123], v[158:161], v[166:169], v[120:123]
	v_mfma_f32_16x16x32_bf16 v[108:111], v[150:153], v[174:177], v[108:111]
	v_mfma_f32_16x16x32_bf16 v[104:107], v[158:161], v[174:177], v[104:107]
	v_mfma_f32_16x16x32_bf16 v[92:95], v[150:153], v[182:185], v[92:95]
	v_mfma_f32_16x16x32_bf16 v[88:91], v[158:161], v[182:185], v[88:91]
	v_mfma_f32_16x16x32_bf16 v[76:79], v[150:153], v[190:193], v[76:79]
	v_mfma_f32_16x16x32_bf16 v[72:75], v[158:161], v[190:193], v[72:75]
	s_barrier
	s_add_i32 s22, 0, 0x1c000
	s_add_i32 s23, s52, s27
	v_add_u32_e32 v208, s22, v141
	s_mov_b32 m0, s23
	ds_read_b128 v[194:197], v208
	ds_read_b128 v[198:201], v208 offset:1024
	ds_read_b128 v[204:207], v208 offset:2048
	ds_read_b128 v[208:211], v208 offset:3072
	s_add_u32 s100, s20, 0x80
	s_addc_u32 s101, s21, 0
	global_load_lds_dwordx4 v132, s[100:101]
	s_add_i32 m0, s23, 0x2000
	s_nop 0
	s_add_u32 s100, s20, 0x80
	s_addc_u32 s101, s21, 0
	global_load_lds_dwordx4 v128, s[100:101]
	s_barrier
	s_waitcnt lgkmcnt(0)
	s_waitcnt lgkmcnt(0)
	v_mfma_f32_16x16x32_bf16 v[116:119], v[194:197], v[162:165], v[116:119]
	v_mfma_f32_16x16x32_bf16 v[112:115], v[204:207], v[162:165], v[112:115]
	v_mfma_f32_16x16x32_bf16 v[100:103], v[194:197], v[170:173], v[100:103]
	v_mfma_f32_16x16x32_bf16 v[96:99], v[204:207], v[170:173], v[96:99]
	v_mfma_f32_16x16x32_bf16 v[84:87], v[194:197], v[178:181], v[84:87]
	v_mfma_f32_16x16x32_bf16 v[80:83], v[204:207], v[178:181], v[80:83]
	v_mfma_f32_16x16x32_bf16 v[68:71], v[194:197], v[186:189], v[68:71]
	v_mfma_f32_16x16x32_bf16 v[64:67], v[204:207], v[186:189], v[64:67]
	v_mfma_f32_16x16x32_bf16 v[116:119], v[198:201], v[166:169], v[116:119]
	v_mfma_f32_16x16x32_bf16 v[112:115], v[208:211], v[166:169], v[112:115]
	v_mfma_f32_16x16x32_bf16 v[100:103], v[198:201], v[174:177], v[100:103]
	v_mfma_f32_16x16x32_bf16 v[96:99], v[208:211], v[174:177], v[96:99]
	v_mfma_f32_16x16x32_bf16 v[84:87], v[198:201], v[182:185], v[84:87]
	v_mfma_f32_16x16x32_bf16 v[80:83], v[208:211], v[182:185], v[80:83]
	v_mfma_f32_16x16x32_bf16 v[68:71], v[198:201], v[190:193], v[68:71]
	v_mfma_f32_16x16x32_bf16 v[64:67], v[208:211], v[190:193], v[64:67]
	s_mov_b32 m0, s36
	s_barrier
	ds_read_b128 v[162:165], v144 offset:49152
	ds_read_b128 v[166:169], v144 offset:50176
	ds_read_b128 v[170:173], v144 offset:51200
	ds_read_b128 v[174:177], v144 offset:52224
	ds_read_b128 v[178:181], v144 offset:53248
	ds_read_b128 v[182:185], v144 offset:54272
	ds_read_b128 v[186:189], v144 offset:55296
	ds_read_b128 v[190:193], v144 offset:56320
	s_add_u32 s100, s98, 0x80
	s_addc_u32 s101, s99, 0
	global_load_lds_dwordx4 v134, s[100:101]
	s_mov_b32 m0, s37
	s_nop 0
	s_add_u32 s100, s98, 0x80
	s_addc_u32 s101, s99, 0
	global_load_lds_dwordx4 v130, s[100:101]
	s_barrier
	s_waitcnt lgkmcnt(0)
	s_waitcnt lgkmcnt(0)
	v_mfma_f32_16x16x32_bf16 v[60:63], v[146:149], v[162:165], v[60:63]
	v_mfma_f32_16x16x32_bf16 v[56:59], v[154:157], v[162:165], v[56:59]
	v_mfma_f32_16x16x32_bf16 v[44:47], v[146:149], v[170:173], v[44:47]
	v_mfma_f32_16x16x32_bf16 v[40:43], v[154:157], v[170:173], v[40:43]
	v_mfma_f32_16x16x32_bf16 v[28:31], v[146:149], v[178:181], v[28:31]
	v_mfma_f32_16x16x32_bf16 v[24:27], v[154:157], v[178:181], v[24:27]
	v_mfma_f32_16x16x32_bf16 v[12:15], v[146:149], v[186:189], v[12:15]
	v_mfma_f32_16x16x32_bf16 v[8:11], v[154:157], v[186:189], v[8:11]
	v_mfma_f32_16x16x32_bf16 v[60:63], v[150:153], v[166:169], v[60:63]
	v_mfma_f32_16x16x32_bf16 v[56:59], v[158:161], v[166:169], v[56:59]
	v_mfma_f32_16x16x32_bf16 v[44:47], v[150:153], v[174:177], v[44:47]
	v_mfma_f32_16x16x32_bf16 v[40:43], v[158:161], v[174:177], v[40:43]
	v_mfma_f32_16x16x32_bf16 v[28:31], v[150:153], v[182:185], v[28:31]
	v_mfma_f32_16x16x32_bf16 v[24:27], v[158:161], v[182:185], v[24:27]
	v_mfma_f32_16x16x32_bf16 v[12:15], v[150:153], v[190:193], v[12:15]
	v_mfma_f32_16x16x32_bf16 v[8:11], v[158:161], v[190:193], v[8:11]
	s_barrier
	s_add_u32 s20, s20, 0x40080
	s_addc_u32 s21, s21, 0
	s_add_i32 s22, s22, s27
	s_mov_b32 m0, s22
	s_nop 0
	global_load_lds_dwordx4 v132, s[20:21]
	s_add_i32 m0, s22, 0x2000
	s_nop 0
	global_load_lds_dwordx4 v128, s[20:21]
	s_waitcnt vmcnt(6)
	s_barrier
	v_mfma_f32_16x16x32_bf16 v[52:55], v[194:197], v[162:165], v[52:55]
	v_mfma_f32_16x16x32_bf16 v[48:51], v[204:207], v[162:165], v[48:51]
	v_mfma_f32_16x16x32_bf16 v[36:39], v[194:197], v[170:173], v[36:39]
	v_mfma_f32_16x16x32_bf16 v[32:35], v[204:207], v[170:173], v[32:35]
	v_mfma_f32_16x16x32_bf16 v[20:23], v[194:197], v[178:181], v[20:23]
	v_mfma_f32_16x16x32_bf16 v[16:19], v[204:207], v[178:181], v[16:19]
	v_mfma_f32_16x16x32_bf16 v[4:7], v[194:197], v[186:189], v[4:7]
	v_mfma_f32_16x16x32_bf16 v[0:3], v[204:207], v[186:189], v[0:3]
	v_mfma_f32_16x16x32_bf16 v[52:55], v[198:201], v[166:169], v[52:55]
	v_mfma_f32_16x16x32_bf16 v[48:51], v[208:211], v[166:169], v[48:51]
	v_mfma_f32_16x16x32_bf16 v[36:39], v[198:201], v[174:177], v[36:39]
	v_mfma_f32_16x16x32_bf16 v[32:35], v[208:211], v[174:177], v[32:35]
	v_mfma_f32_16x16x32_bf16 v[20:23], v[198:201], v[182:185], v[20:23]
	v_mfma_f32_16x16x32_bf16 v[16:19], v[208:211], v[182:185], v[16:19]
	v_mfma_f32_16x16x32_bf16 v[4:7], v[198:201], v[190:193], v[4:7]
	v_mfma_f32_16x16x32_bf16 v[0:3], v[208:211], v[190:193], v[0:3]
	s_add_u32 s18, s18, 0x100
	s_addc_u32 s19, s19, 0
	s_add_u32 s49, s49, 0x100
	s_addc_u32 s50, s50, 0
	s_cmp_ge_i32 s51, s45
	s_mov_b32 s20, s51
	s_barrier
	s_cbranch_scc0 .LBB0_1409
	s_branch .LBB0_1404

.LBB0_1564:
	ds_read_b128 v[152:155], v149
	ds_read_b128 v[156:159], v149 offset:1024
	ds_read_b128 v[160:163], v149 offset:2048
	ds_read_b128 v[164:167], v149 offset:3072
	s_add_u32 s24, s22, 0xfff80080
	s_addc_u32 s25, s23, -1
	s_cmp_eq_u32 s52, 28
	s_cselect_b32 s27, s15, s25
	s_cselect_b32 s26, s48, s24
	s_cselect_b32 s25, s13, s51
	s_cselect_b32 s24, s49, s50
	s_add_i32 m0, s21, 0xc000
	ds_read_b128 v[168:171], v150
	ds_read_b128 v[172:175], v150 offset:1024
	ds_read_b128 v[176:179], v150 offset:2048
	ds_read_b128 v[180:183], v150 offset:3072
	ds_read_b128 v[184:187], v150 offset:4096
	ds_read_b128 v[188:191], v150 offset:5120
	ds_read_b128 v[192:195], v150 offset:6144
	ds_read_b128 v[196:199], v150 offset:7168
	global_load_lds_dwordx4 v136, s[22:23]
	s_add_i32 m0, s21, 0xe000
	s_nop 0
	global_load_lds_dwordx4 v138, s[22:23]
	s_waitcnt lgkmcnt(8)
	s_barrier
	s_waitcnt lgkmcnt(0)
	s_waitcnt lgkmcnt(0)
	v_mfma_f32_16x16x32_bf16 v[124:127], v[152:155], v[168:171], v[124:127]
	v_mfma_f32_16x16x32_bf16 v[120:123], v[160:163], v[168:171], v[120:123]
	v_mfma_f32_16x16x32_bf16 v[108:111], v[152:155], v[176:179], v[108:111]
	v_mfma_f32_16x16x32_bf16 v[104:107], v[160:163], v[176:179], v[104:107]
	v_mfma_f32_16x16x32_bf16 v[92:95], v[152:155], v[184:187], v[92:95]
	v_mfma_f32_16x16x32_bf16 v[88:91], v[160:163], v[184:187], v[88:91]
	v_mfma_f32_16x16x32_bf16 v[76:79], v[152:155], v[192:195], v[76:79]
	v_mfma_f32_16x16x32_bf16 v[72:75], v[160:163], v[192:195], v[72:75]
	v_mfma_f32_16x16x32_bf16 v[124:127], v[156:159], v[172:175], v[124:127]
	v_mfma_f32_16x16x32_bf16 v[120:123], v[164:167], v[172:175], v[120:123]
	v_mfma_f32_16x16x32_bf16 v[108:111], v[156:159], v[180:183], v[108:111]
	v_mfma_f32_16x16x32_bf16 v[104:107], v[164:167], v[180:183], v[104:107]
	v_mfma_f32_16x16x32_bf16 v[92:95], v[156:159], v[188:191], v[92:95]
	v_mfma_f32_16x16x32_bf16 v[88:91], v[164:167], v[188:191], v[88:91]
	v_mfma_f32_16x16x32_bf16 v[76:79], v[156:159], v[196:199], v[76:79]
	v_mfma_f32_16x16x32_bf16 v[72:75], v[164:167], v[196:199], v[72:75]
	s_barrier
	s_add_i32 s53, s41, s31
	s_mov_b32 m0, s53
	ds_read_b128 v[204:207], v151
	ds_read_b128 v[208:211], v151 offset:1024
	ds_read_b128 v[212:215], v151 offset:2048
	ds_read_b128 v[216:219], v151 offset:3072
	global_load_lds_dwordx4 v132, s[24:25]
	s_add_i32 m0, s53, 0x2000
	s_nop 0
	global_load_lds_dwordx4 v128, s[24:25]
	s_barrier
	s_waitcnt lgkmcnt(0)
	s_waitcnt lgkmcnt(0)
	v_mfma_f32_16x16x32_bf16 v[116:119], v[204:207], v[168:171], v[116:119]
	v_mfma_f32_16x16x32_bf16 v[112:115], v[212:215], v[168:171], v[112:115]
	v_mfma_f32_16x16x32_bf16 v[100:103], v[204:207], v[176:179], v[100:103]
	v_mfma_f32_16x16x32_bf16 v[96:99], v[212:215], v[176:179], v[96:99]
	v_mfma_f32_16x16x32_bf16 v[84:87], v[204:207], v[184:187], v[84:87]
	v_mfma_f32_16x16x32_bf16 v[80:83], v[212:215], v[184:187], v[80:83]
	v_mfma_f32_16x16x32_bf16 v[68:71], v[204:207], v[192:195], v[68:71]
	v_mfma_f32_16x16x32_bf16 v[64:67], v[212:215], v[192:195], v[64:67]
	v_mfma_f32_16x16x32_bf16 v[116:119], v[208:211], v[172:175], v[116:119]
	v_mfma_f32_16x16x32_bf16 v[112:115], v[216:219], v[172:175], v[112:115]
	v_mfma_f32_16x16x32_bf16 v[100:103], v[208:211], v[180:183], v[100:103]
	v_mfma_f32_16x16x32_bf16 v[96:99], v[216:219], v[180:183], v[96:99]
	v_mfma_f32_16x16x32_bf16 v[84:87], v[208:211], v[188:191], v[84:87]
	v_mfma_f32_16x16x32_bf16 v[80:83], v[216:219], v[188:191], v[80:83]
	v_mfma_f32_16x16x32_bf16 v[68:71], v[208:211], v[196:199], v[68:71]
	v_mfma_f32_16x16x32_bf16 v[64:67], v[216:219], v[196:199], v[64:67]
	s_mov_b32 m0, s21
	s_mov_b64 s[98:99], s[26:27]
	s_barrier
	ds_read_b128 v[168:171], v150 offset:16384
	ds_read_b128 v[172:175], v150 offset:17408
	ds_read_b128 v[176:179], v150 offset:18432
	ds_read_b128 v[180:183], v150 offset:19456
	ds_read_b128 v[184:187], v150 offset:20480
	ds_read_b128 v[188:191], v150 offset:21504
	ds_read_b128 v[192:195], v150 offset:22528
	ds_read_b128 v[196:199], v150 offset:23552
	global_load_lds_dwordx4 v134, s[26:27]
	s_mov_b32 m0, s35
	s_nop 0
	global_load_lds_dwordx4 v130, s[26:27]
	s_barrier
	s_waitcnt lgkmcnt(0)
	s_waitcnt lgkmcnt(0)
	v_mfma_f32_16x16x32_bf16 v[60:63], v[152:155], v[168:171], v[60:63]
	v_mfma_f32_16x16x32_bf16 v[56:59], v[160:163], v[168:171], v[56:59]
	v_mfma_f32_16x16x32_bf16 v[44:47], v[152:155], v[176:179], v[44:47]
	v_mfma_f32_16x16x32_bf16 v[40:43], v[160:163], v[176:179], v[40:43]
	v_mfma_f32_16x16x32_bf16 v[28:31], v[152:155], v[184:187], v[28:31]
	v_mfma_f32_16x16x32_bf16 v[24:27], v[160:163], v[184:187], v[24:27]
	v_mfma_f32_16x16x32_bf16 v[12:15], v[152:155], v[192:195], v[12:15]
	v_mfma_f32_16x16x32_bf16 v[8:11], v[160:163], v[192:195], v[8:11]
	v_mfma_f32_16x16x32_bf16 v[60:63], v[156:159], v[172:175], v[60:63]
	v_mfma_f32_16x16x32_bf16 v[56:59], v[164:167], v[172:175], v[56:59]
	v_mfma_f32_16x16x32_bf16 v[44:47], v[156:159], v[180:183], v[44:47]
	v_mfma_f32_16x16x32_bf16 v[40:43], v[164:167], v[180:183], v[40:43]
	v_mfma_f32_16x16x32_bf16 v[28:31], v[156:159], v[188:191], v[28:31]
	v_mfma_f32_16x16x32_bf16 v[24:27], v[164:167], v[188:191], v[24:27]
	v_mfma_f32_16x16x32_bf16 v[12:15], v[156:159], v[196:199], v[12:15]
	v_mfma_f32_16x16x32_bf16 v[8:11], v[164:167], v[196:199], v[8:11]
	s_barrier
	s_add_u32 s54, s24, 0x20000
	s_addc_u32 s55, s25, 0
	s_add_i32 s53, s42, s31
	s_mov_b32 m0, s53
	s_nop 0
	global_load_lds_dwordx4 v132, s[54:55]
	s_add_i32 m0, s53, 0x2000
	s_nop 0
	global_load_lds_dwordx4 v128, s[54:55]
	s_waitcnt vmcnt(6)
	s_barrier
	v_mfma_f32_16x16x32_bf16 v[52:55], v[204:207], v[168:171], v[52:55]
	v_mfma_f32_16x16x32_bf16 v[48:51], v[212:215], v[168:171], v[48:51]
	v_mfma_f32_16x16x32_bf16 v[36:39], v[204:207], v[176:179], v[36:39]
	v_mfma_f32_16x16x32_bf16 v[32:35], v[212:215], v[176:179], v[32:35]
	v_mfma_f32_16x16x32_bf16 v[20:23], v[204:207], v[184:187], v[20:23]
	v_mfma_f32_16x16x32_bf16 v[16:19], v[212:215], v[184:187], v[16:19]
	v_mfma_f32_16x16x32_bf16 v[4:7], v[204:207], v[192:195], v[4:7]
	v_mfma_f32_16x16x32_bf16 v[0:3], v[212:215], v[192:195], v[0:3]
	v_mfma_f32_16x16x32_bf16 v[52:55], v[208:211], v[172:175], v[52:55]
	v_mfma_f32_16x16x32_bf16 v[48:51], v[216:219], v[172:175], v[48:51]
	v_mfma_f32_16x16x32_bf16 v[36:39], v[208:211], v[180:183], v[36:39]
	v_mfma_f32_16x16x32_bf16 v[32:35], v[216:219], v[180:183], v[32:35]
	v_mfma_f32_16x16x32_bf16 v[20:23], v[208:211], v[188:191], v[20:23]
	v_mfma_f32_16x16x32_bf16 v[16:19], v[216:219], v[188:191], v[16:19]
	v_mfma_f32_16x16x32_bf16 v[4:7], v[208:211], v[196:199], v[4:7]
	v_mfma_f32_16x16x32_bf16 v[0:3], v[216:219], v[196:199], v[0:3]
	s_add_i32 s53, 0, 0x18000
	v_add_u32_e32 v164, s53, v147
	s_barrier
	ds_read_b128 v[152:155], v164
	ds_read_b128 v[156:159], v164 offset:1024
	ds_read_b128 v[160:163], v164 offset:2048
	ds_read_b128 v[164:167], v164 offset:3072
	s_add_u32 s26, s26, 0x80000
	s_addc_u32 s27, s27, 0
	s_mov_b32 m0, s36
	ds_read_b128 v[168:171], v150 offset:32768
	ds_read_b128 v[172:175], v150 offset:33792
	ds_read_b128 v[176:179], v150 offset:34816
	ds_read_b128 v[180:183], v150 offset:35840
	ds_read_b128 v[184:187], v150 offset:36864
	ds_read_b128 v[188:191], v150 offset:37888
	ds_read_b128 v[192:195], v150 offset:38912
	ds_read_b128 v[196:199], v150 offset:39936
	global_load_lds_dwordx4 v134, s[26:27]
	s_mov_b32 m0, s37
	s_nop 0
	global_load_lds_dwordx4 v130, s[26:27]
	s_waitcnt lgkmcnt(8)
	s_barrier
	s_waitcnt lgkmcnt(0)
	s_waitcnt lgkmcnt(0)
	v_mfma_f32_16x16x32_bf16 v[124:127], v[152:155], v[168:171], v[124:127]
	v_mfma_f32_16x16x32_bf16 v[120:123], v[160:163], v[168:171], v[120:123]
	v_mfma_f32_16x16x32_bf16 v[108:111], v[152:155], v[176:179], v[108:111]
	v_mfma_f32_16x16x32_bf16 v[104:107], v[160:163], v[176:179], v[104:107]
	v_mfma_f32_16x16x32_bf16 v[92:95], v[152:155], v[184:187], v[92:95]
	v_mfma_f32_16x16x32_bf16 v[88:91], v[160:163], v[184:187], v[88:91]
	v_mfma_f32_16x16x32_bf16 v[76:79], v[152:155], v[192:195], v[76:79]
	v_mfma_f32_16x16x32_bf16 v[72:75], v[160:163], v[192:195], v[72:75]
	v_mfma_f32_16x16x32_bf16 v[124:127], v[156:159], v[172:175], v[124:127]
	v_mfma_f32_16x16x32_bf16 v[120:123], v[164:167], v[172:175], v[120:123]
	v_mfma_f32_16x16x32_bf16 v[108:111], v[156:159], v[180:183], v[108:111]
	v_mfma_f32_16x16x32_bf16 v[104:107], v[164:167], v[180:183], v[104:107]
	v_mfma_f32_16x16x32_bf16 v[92:95], v[156:159], v[188:191], v[92:95]
	v_mfma_f32_16x16x32_bf16 v[88:91], v[164:167], v[188:191], v[88:91]
	v_mfma_f32_16x16x32_bf16 v[76:79], v[156:159], v[196:199], v[76:79]
	v_mfma_f32_16x16x32_bf16 v[72:75], v[164:167], v[196:199], v[72:75]
	s_barrier
	s_add_i32 s26, 0, 0x1c000
	s_add_i32 s27, s53, s31
	v_add_u32_e32 v216, s26, v147
	s_mov_b32 m0, s27
	ds_read_b128 v[204:207], v216
	ds_read_b128 v[208:211], v216 offset:1024
	ds_read_b128 v[212:215], v216 offset:2048
	ds_read_b128 v[216:219], v216 offset:3072
	s_add_u32 s100, s24, 0x80
	s_addc_u32 s101, s25, 0
	global_load_lds_dwordx4 v132, s[100:101]
	s_add_i32 m0, s27, 0x2000
	s_nop 0
	s_add_u32 s100, s24, 0x80
	s_addc_u32 s101, s25, 0
	global_load_lds_dwordx4 v128, s[100:101]
	s_barrier
	s_waitcnt lgkmcnt(0)
	s_waitcnt lgkmcnt(0)
	v_mfma_f32_16x16x32_bf16 v[116:119], v[204:207], v[168:171], v[116:119]
	v_mfma_f32_16x16x32_bf16 v[112:115], v[212:215], v[168:171], v[112:115]
	v_mfma_f32_16x16x32_bf16 v[100:103], v[204:207], v[176:179], v[100:103]
	v_mfma_f32_16x16x32_bf16 v[96:99], v[212:215], v[176:179], v[96:99]
	v_mfma_f32_16x16x32_bf16 v[84:87], v[204:207], v[184:187], v[84:87]
	v_mfma_f32_16x16x32_bf16 v[80:83], v[212:215], v[184:187], v[80:83]
	v_mfma_f32_16x16x32_bf16 v[68:71], v[204:207], v[192:195], v[68:71]
	v_mfma_f32_16x16x32_bf16 v[64:67], v[212:215], v[192:195], v[64:67]
	v_mfma_f32_16x16x32_bf16 v[116:119], v[208:211], v[172:175], v[116:119]
	v_mfma_f32_16x16x32_bf16 v[112:115], v[216:219], v[172:175], v[112:115]
	v_mfma_f32_16x16x32_bf16 v[100:103], v[208:211], v[180:183], v[100:103]
	v_mfma_f32_16x16x32_bf16 v[96:99], v[216:219], v[180:183], v[96:99]
	v_mfma_f32_16x16x32_bf16 v[84:87], v[208:211], v[188:191], v[84:87]
	v_mfma_f32_16x16x32_bf16 v[80:83], v[216:219], v[188:191], v[80:83]
	v_mfma_f32_16x16x32_bf16 v[68:71], v[208:211], v[196:199], v[68:71]
	v_mfma_f32_16x16x32_bf16 v[64:67], v[216:219], v[196:199], v[64:67]
	s_mov_b32 m0, s39
	s_barrier
	ds_read_b128 v[168:171], v150 offset:49152
	ds_read_b128 v[172:175], v150 offset:50176
	ds_read_b128 v[176:179], v150 offset:51200
	ds_read_b128 v[180:183], v150 offset:52224
	ds_read_b128 v[184:187], v150 offset:53248
	ds_read_b128 v[188:191], v150 offset:54272
	ds_read_b128 v[192:195], v150 offset:55296
	ds_read_b128 v[196:199], v150 offset:56320
	s_add_u32 s100, s98, 0x80
	s_addc_u32 s101, s99, 0
	global_load_lds_dwordx4 v134, s[100:101]
	s_mov_b32 m0, s40
	s_nop 0
	s_add_u32 s100, s98, 0x80
	s_addc_u32 s101, s99, 0
	global_load_lds_dwordx4 v130, s[100:101]
	s_barrier
	s_waitcnt lgkmcnt(0)
	s_waitcnt lgkmcnt(0)
	v_mfma_f32_16x16x32_bf16 v[60:63], v[152:155], v[168:171], v[60:63]
	v_mfma_f32_16x16x32_bf16 v[56:59], v[160:163], v[168:171], v[56:59]
	v_mfma_f32_16x16x32_bf16 v[44:47], v[152:155], v[176:179], v[44:47]
	v_mfma_f32_16x16x32_bf16 v[40:43], v[160:163], v[176:179], v[40:43]
	v_mfma_f32_16x16x32_bf16 v[28:31], v[152:155], v[184:187], v[28:31]
	v_mfma_f32_16x16x32_bf16 v[24:27], v[160:163], v[184:187], v[24:27]
	v_mfma_f32_16x16x32_bf16 v[12:15], v[152:155], v[192:195], v[12:15]
	v_mfma_f32_16x16x32_bf16 v[8:11], v[160:163], v[192:195], v[8:11]
	v_mfma_f32_16x16x32_bf16 v[60:63], v[156:159], v[172:175], v[60:63]
	v_mfma_f32_16x16x32_bf16 v[56:59], v[164:167], v[172:175], v[56:59]
	v_mfma_f32_16x16x32_bf16 v[44:47], v[156:159], v[180:183], v[44:47]
	v_mfma_f32_16x16x32_bf16 v[40:43], v[164:167], v[180:183], v[40:43]
	v_mfma_f32_16x16x32_bf16 v[28:31], v[156:159], v[188:191], v[28:31]
	v_mfma_f32_16x16x32_bf16 v[24:27], v[164:167], v[188:191], v[24:27]
	v_mfma_f32_16x16x32_bf16 v[12:15], v[156:159], v[196:199], v[12:15]
	v_mfma_f32_16x16x32_bf16 v[8:11], v[164:167], v[196:199], v[8:11]
	s_barrier
	s_add_u32 s24, s24, 0x20080
	s_addc_u32 s25, s25, 0
	s_add_i32 s26, s26, s31
	s_mov_b32 m0, s26
	s_nop 0
	global_load_lds_dwordx4 v132, s[24:25]
	s_add_i32 m0, s26, 0x2000
	s_nop 0
	global_load_lds_dwordx4 v128, s[24:25]
	s_waitcnt vmcnt(6)
	s_barrier
	v_mfma_f32_16x16x32_bf16 v[52:55], v[204:207], v[168:171], v[52:55]
	v_mfma_f32_16x16x32_bf16 v[48:51], v[212:215], v[168:171], v[48:51]
	v_mfma_f32_16x16x32_bf16 v[36:39], v[204:207], v[176:179], v[36:39]
	v_mfma_f32_16x16x32_bf16 v[32:35], v[212:215], v[176:179], v[32:35]
	v_mfma_f32_16x16x32_bf16 v[20:23], v[204:207], v[184:187], v[20:23]
	v_mfma_f32_16x16x32_bf16 v[16:19], v[212:215], v[184:187], v[16:19]
	v_mfma_f32_16x16x32_bf16 v[4:7], v[204:207], v[192:195], v[4:7]
	v_mfma_f32_16x16x32_bf16 v[0:3], v[212:215], v[192:195], v[0:3]
	v_mfma_f32_16x16x32_bf16 v[52:55], v[208:211], v[172:175], v[52:55]
	v_mfma_f32_16x16x32_bf16 v[48:51], v[216:219], v[172:175], v[48:51]
	v_mfma_f32_16x16x32_bf16 v[36:39], v[208:211], v[180:183], v[36:39]
	v_mfma_f32_16x16x32_bf16 v[32:35], v[216:219], v[180:183], v[32:35]
	v_mfma_f32_16x16x32_bf16 v[20:23], v[208:211], v[188:191], v[20:23]
	v_mfma_f32_16x16x32_bf16 v[16:19], v[216:219], v[188:191], v[16:19]
	v_mfma_f32_16x16x32_bf16 v[4:7], v[208:211], v[196:199], v[4:7]
	v_mfma_f32_16x16x32_bf16 v[0:3], v[216:219], v[196:199], v[0:3]
	s_add_i32 s52, s52, 2
	s_add_u32 s22, s22, 0x100
	s_addc_u32 s23, s23, 0
	s_add_u32 s50, s50, 0x100
	s_addc_u32 s51, s51, 0
	s_cmp_gt_u32 s52, 29
	s_barrier
	s_cbranch_scc0 .LBB0_1564
	v_readlane_b32 s100, v248, 63
	v_readlane_b32 s101, v247, 0
	v_and_b32_e32 v242, 15, v202
	v_bfe_u32 v243, v202, 4, 2
	v_bfe_u32 v244, v202, 6, 2
	v_lshrrev_b32_e32 v245, 8, v202
	v_and_b32_e32 v240, 7, v242
	v_lshl_add_u32 v240, v245, 6, v240
	v_lshl_add_u32 v240, s20, 8, v240
	v_lshlrev_b32_e32 v240, 14, v240
	v_lshrrev_b32_e32 v241, 3, v242
	v_lshlrev_b32_e32 v241, 6, v241
	v_lshl_add_u32 v241, v244, 7, v241
	v_lshl_add_u32 v241, v243, 4, v241
	v_add_u32_e32 v240, v240, v241
	s_lshl_b32 s98, s47, 9
	v_add_u32_e32 v240, s98, v240
	v_max_f32_e32 v124, 0, v124
	v_max_f32_e32 v125, 0, v125
	v_max_f32_e32 v126, 0, v126
	v_max_f32_e32 v127, 0, v127
	v_max_f32_e32 v120, 0, v120
	v_max_f32_e32 v121, 0, v121
	v_max_f32_e32 v122, 0, v122
	v_max_f32_e32 v123, 0, v123
	v_pk_mul_f32 v[124:125], v[124:125], v[124:125]
	v_pk_mul_f32 v[126:127], v[126:127], v[126:127]
	v_pk_mul_f32 v[120:121], v[120:121], v[120:121]
	v_pk_mul_f32 v[122:123], v[122:123], v[122:123]
	v_cvt_pk_bf16_f32 v228, v124, v125
	v_cvt_pk_bf16_f32 v229, v126, v127
	v_cvt_pk_bf16_f32 v230, v120, v121
	v_cvt_pk_bf16_f32 v231, v122, v123
	v_max_f32_e32 v116, 0, v116
	v_max_f32_e32 v117, 0, v117
	v_max_f32_e32 v118, 0, v118
	v_max_f32_e32 v119, 0, v119
	v_max_f32_e32 v112, 0, v112
	v_max_f32_e32 v113, 0, v113
	v_max_f32_e32 v114, 0, v114
	v_max_f32_e32 v115, 0, v115
	v_pk_mul_f32 v[116:117], v[116:117], v[116:117]
	v_pk_mul_f32 v[118:119], v[118:119], v[118:119]
	v_pk_mul_f32 v[112:113], v[112:113], v[112:113]
	v_pk_mul_f32 v[114:115], v[114:115], v[114:115]
	v_cvt_pk_bf16_f32 v232, v116, v117
	v_cvt_pk_bf16_f32 v233, v118, v119
	v_cvt_pk_bf16_f32 v234, v112, v113
	v_cvt_pk_bf16_f32 v235, v114, v115
	v_mov_b32_e32 v236, v228
	v_mov_b32_e32 v237, v229
	v_mov_b32_e32 v238, v230
	v_mov_b32_e32 v239, v231
	v_mov_b32_dpp v228, v232 row_ror:8 row_mask:0xf bank_mask:0xc
	v_mov_b32_dpp v229, v233 row_ror:8 row_mask:0xf bank_mask:0xc
	v_mov_b32_dpp v230, v234 row_ror:8 row_mask:0xf bank_mask:0xc
	v_mov_b32_dpp v231, v235 row_ror:8 row_mask:0xf bank_mask:0xc
	v_mov_b32_dpp v232, v236 row_ror:8 row_mask:0xf bank_mask:0x3
	v_mov_b32_dpp v233, v237 row_ror:8 row_mask:0xf bank_mask:0x3
	v_mov_b32_dpp v234, v238 row_ror:8 row_mask:0xf bank_mask:0x3
	v_mov_b32_dpp v235, v239 row_ror:8 row_mask:0xf bank_mask:0x3
	global_store_dwordx4 v240, v[228:231], s[100:101]
	s_add_u32 s100, s100, 0x20000
	s_addc_u32 s101, s101, 0
	global_store_dwordx4 v240, v[232:235], s[100:101]
	v_max_f32_e32 v108, 0, v108
	v_max_f32_e32 v109, 0, v109
	v_max_f32_e32 v110, 0, v110
	v_max_f32_e32 v111, 0, v111
	v_max_f32_e32 v104, 0, v104
	v_max_f32_e32 v105, 0, v105
	v_max_f32_e32 v106, 0, v106
	v_max_f32_e32 v107, 0, v107
	v_pk_mul_f32 v[108:109], v[108:109], v[108:109]
	v_pk_mul_f32 v[110:111], v[110:111], v[110:111]
	v_pk_mul_f32 v[104:105], v[104:105], v[104:105]
	v_pk_mul_f32 v[106:107], v[106:107], v[106:107]
	v_cvt_pk_bf16_f32 v228, v108, v109
	v_cvt_pk_bf16_f32 v229, v110, v111
	v_cvt_pk_bf16_f32 v230, v104, v105
	v_cvt_pk_bf16_f32 v231, v106, v107
	v_max_f32_e32 v100, 0, v100
	v_max_f32_e32 v101, 0, v101
	v_max_f32_e32 v102, 0, v102
	v_max_f32_e32 v103, 0, v103
	v_max_f32_e32 v96, 0, v96
	v_max_f32_e32 v97, 0, v97
	v_max_f32_e32 v98, 0, v98
	v_max_f32_e32 v99, 0, v99
	v_pk_mul_f32 v[100:101], v[100:101], v[100:101]
	v_pk_mul_f32 v[102:103], v[102:103], v[102:103]
	v_pk_mul_f32 v[96:97], v[96:97], v[96:97]
	v_pk_mul_f32 v[98:99], v[98:99], v[98:99]
	v_cvt_pk_bf16_f32 v232, v100, v101
	v_cvt_pk_bf16_f32 v233, v102, v103
	v_cvt_pk_bf16_f32 v234, v96, v97
	v_cvt_pk_bf16_f32 v235, v98, v99
	v_mov_b32_e32 v236, v228
	v_mov_b32_e32 v237, v229
	v_mov_b32_e32 v238, v230
	v_mov_b32_e32 v239, v231
	v_mov_b32_dpp v228, v232 row_ror:8 row_mask:0xf bank_mask:0xc
	v_mov_b32_dpp v229, v233 row_ror:8 row_mask:0xf bank_mask:0xc
	v_mov_b32_dpp v230, v234 row_ror:8 row_mask:0xf bank_mask:0xc
	v_mov_b32_dpp v231, v235 row_ror:8 row_mask:0xf bank_mask:0xc
	v_mov_b32_dpp v232, v236 row_ror:8 row_mask:0xf bank_mask:0x3
	v_mov_b32_dpp v233, v237 row_ror:8 row_mask:0xf bank_mask:0x3
	v_mov_b32_dpp v234, v238 row_ror:8 row_mask:0xf bank_mask:0x3
	v_mov_b32_dpp v235, v239 row_ror:8 row_mask:0xf bank_mask:0x3
	s_add_u32 s100, s100, 0x20000
	s_addc_u32 s101, s101, 0
	global_store_dwordx4 v240, v[228:231], s[100:101]
	s_add_u32 s100, s100, 0x20000
	s_addc_u32 s101, s101, 0
	global_store_dwordx4 v240, v[232:235], s[100:101]
	v_max_f32_e32 v92, 0, v92
	v_max_f32_e32 v93, 0, v93
	v_max_f32_e32 v94, 0, v94
	v_max_f32_e32 v95, 0, v95
	v_max_f32_e32 v88, 0, v88
	v_max_f32_e32 v89, 0, v89
	v_max_f32_e32 v90, 0, v90
	v_max_f32_e32 v91, 0, v91
	v_pk_mul_f32 v[92:93], v[92:93], v[92:93]
	v_pk_mul_f32 v[94:95], v[94:95], v[94:95]
	v_pk_mul_f32 v[88:89], v[88:89], v[88:89]
	v_pk_mul_f32 v[90:91], v[90:91], v[90:91]
	v_cvt_pk_bf16_f32 v228, v92, v93
	v_cvt_pk_bf16_f32 v229, v94, v95
	v_cvt_pk_bf16_f32 v230, v88, v89
	v_cvt_pk_bf16_f32 v231, v90, v91
	v_max_f32_e32 v84, 0, v84
	v_max_f32_e32 v85, 0, v85
	v_max_f32_e32 v86, 0, v86
	v_max_f32_e32 v87, 0, v87
	v_max_f32_e32 v80, 0, v80
	v_max_f32_e32 v81, 0, v81
	v_max_f32_e32 v82, 0, v82
	v_max_f32_e32 v83, 0, v83
	v_pk_mul_f32 v[84:85], v[84:85], v[84:85]
	v_pk_mul_f32 v[86:87], v[86:87], v[86:87]
	v_pk_mul_f32 v[80:81], v[80:81], v[80:81]
	v_pk_mul_f32 v[82:83], v[82:83], v[82:83]
	v_cvt_pk_bf16_f32 v232, v84, v85
	v_cvt_pk_bf16_f32 v233, v86, v87
	v_cvt_pk_bf16_f32 v234, v80, v81
	v_cvt_pk_bf16_f32 v235, v82, v83
	v_mov_b32_e32 v236, v228
	v_mov_b32_e32 v237, v229
	v_mov_b32_e32 v238, v230
	v_mov_b32_e32 v239, v231
	v_mov_b32_dpp v228, v232 row_ror:8 row_mask:0xf bank_mask:0xc
	v_mov_b32_dpp v229, v233 row_ror:8 row_mask:0xf bank_mask:0xc
	v_mov_b32_dpp v230, v234 row_ror:8 row_mask:0xf bank_mask:0xc
	v_mov_b32_dpp v231, v235 row_ror:8 row_mask:0xf bank_mask:0xc
	v_mov_b32_dpp v232, v236 row_ror:8 row_mask:0xf bank_mask:0x3
	v_mov_b32_dpp v233, v237 row_ror:8 row_mask:0xf bank_mask:0x3
	v_mov_b32_dpp v234, v238 row_ror:8 row_mask:0xf bank_mask:0x3
	v_mov_b32_dpp v235, v239 row_ror:8 row_mask:0xf bank_mask:0x3
	s_add_u32 s100, s100, 0x20000
	s_addc_u32 s101, s101, 0
	global_store_dwordx4 v240, v[228:231], s[100:101]
	s_add_u32 s100, s100, 0x20000
	s_addc_u32 s101, s101, 0
	global_store_dwordx4 v240, v[232:235], s[100:101]
	v_max_f32_e32 v76, 0, v76
	v_max_f32_e32 v77, 0, v77
	v_max_f32_e32 v78, 0, v78
	v_max_f32_e32 v79, 0, v79
	v_max_f32_e32 v72, 0, v72
	v_max_f32_e32 v73, 0, v73
	v_max_f32_e32 v74, 0, v74
	v_max_f32_e32 v75, 0, v75
	v_pk_mul_f32 v[76:77], v[76:77], v[76:77]
	v_pk_mul_f32 v[78:79], v[78:79], v[78:79]
	v_pk_mul_f32 v[72:73], v[72:73], v[72:73]
	v_pk_mul_f32 v[74:75], v[74:75], v[74:75]
	v_cvt_pk_bf16_f32 v228, v76, v77
	v_cvt_pk_bf16_f32 v229, v78, v79
	v_cvt_pk_bf16_f32 v230, v72, v73
	v_cvt_pk_bf16_f32 v231, v74, v75
	v_max_f32_e32 v68, 0, v68
	v_max_f32_e32 v69, 0, v69
	v_max_f32_e32 v70, 0, v70
	v_max_f32_e32 v71, 0, v71
	v_max_f32_e32 v64, 0, v64
	v_max_f32_e32 v65, 0, v65
	v_max_f32_e32 v66, 0, v66
	v_max_f32_e32 v67, 0, v67
	v_pk_mul_f32 v[68:69], v[68:69], v[68:69]
	v_pk_mul_f32 v[70:71], v[70:71], v[70:71]
	v_pk_mul_f32 v[64:65], v[64:65], v[64:65]
	v_pk_mul_f32 v[66:67], v[66:67], v[66:67]
	v_cvt_pk_bf16_f32 v232, v68, v69
	v_cvt_pk_bf16_f32 v233, v70, v71
	v_cvt_pk_bf16_f32 v234, v64, v65
	v_cvt_pk_bf16_f32 v235, v66, v67
	v_mov_b32_e32 v236, v228
	v_mov_b32_e32 v237, v229
	v_mov_b32_e32 v238, v230
	v_mov_b32_e32 v239, v231
	v_mov_b32_dpp v228, v232 row_ror:8 row_mask:0xf bank_mask:0xc
	v_mov_b32_dpp v229, v233 row_ror:8 row_mask:0xf bank_mask:0xc
	v_mov_b32_dpp v230, v234 row_ror:8 row_mask:0xf bank_mask:0xc
	v_mov_b32_dpp v231, v235 row_ror:8 row_mask:0xf bank_mask:0xc
	v_mov_b32_dpp v232, v236 row_ror:8 row_mask:0xf bank_mask:0x3
	v_mov_b32_dpp v233, v237 row_ror:8 row_mask:0xf bank_mask:0x3
	v_mov_b32_dpp v234, v238 row_ror:8 row_mask:0xf bank_mask:0x3
	v_mov_b32_dpp v235, v239 row_ror:8 row_mask:0xf bank_mask:0x3
	s_add_u32 s100, s100, 0x20000
	s_addc_u32 s101, s101, 0
	global_store_dwordx4 v240, v[228:231], s[100:101]
	s_add_u32 s100, s100, 0x20000
	s_addc_u32 s101, s101, 0
	global_store_dwordx4 v240, v[232:235], s[100:101]
	v_max_f32_e32 v60, 0, v60
	v_max_f32_e32 v61, 0, v61
	v_max_f32_e32 v62, 0, v62
	v_max_f32_e32 v63, 0, v63
	v_max_f32_e32 v56, 0, v56
	v_max_f32_e32 v57, 0, v57
	v_max_f32_e32 v58, 0, v58
	v_max_f32_e32 v59, 0, v59
	v_pk_mul_f32 v[60:61], v[60:61], v[60:61]
	v_pk_mul_f32 v[62:63], v[62:63], v[62:63]
	v_pk_mul_f32 v[56:57], v[56:57], v[56:57]
	v_pk_mul_f32 v[58:59], v[58:59], v[58:59]
	v_cvt_pk_bf16_f32 v228, v60, v61
	v_cvt_pk_bf16_f32 v229, v62, v63
	v_cvt_pk_bf16_f32 v230, v56, v57
	v_cvt_pk_bf16_f32 v231, v58, v59
	v_max_f32_e32 v52, 0, v52
	v_max_f32_e32 v53, 0, v53
	v_max_f32_e32 v54, 0, v54
	v_max_f32_e32 v55, 0, v55
	v_max_f32_e32 v48, 0, v48
	v_max_f32_e32 v49, 0, v49
	v_max_f32_e32 v50, 0, v50
	v_max_f32_e32 v51, 0, v51
	v_pk_mul_f32 v[52:53], v[52:53], v[52:53]
	v_pk_mul_f32 v[54:55], v[54:55], v[54:55]
	v_pk_mul_f32 v[48:49], v[48:49], v[48:49]
	v_pk_mul_f32 v[50:51], v[50:51], v[50:51]
	v_cvt_pk_bf16_f32 v232, v52, v53
	v_cvt_pk_bf16_f32 v233, v54, v55
	v_cvt_pk_bf16_f32 v234, v48, v49
	v_cvt_pk_bf16_f32 v235, v50, v51
	v_mov_b32_e32 v236, v228
	v_mov_b32_e32 v237, v229
	v_mov_b32_e32 v238, v230
	v_mov_b32_e32 v239, v231
	v_mov_b32_dpp v228, v232 row_ror:8 row_mask:0xf bank_mask:0xc
	v_mov_b32_dpp v229, v233 row_ror:8 row_mask:0xf bank_mask:0xc
	v_mov_b32_dpp v230, v234 row_ror:8 row_mask:0xf bank_mask:0xc
	v_mov_b32_dpp v231, v235 row_ror:8 row_mask:0xf bank_mask:0xc
	v_mov_b32_dpp v232, v236 row_ror:8 row_mask:0xf bank_mask:0x3
	v_mov_b32_dpp v233, v237 row_ror:8 row_mask:0xf bank_mask:0x3
	v_mov_b32_dpp v234, v238 row_ror:8 row_mask:0xf bank_mask:0x3
	v_mov_b32_dpp v235, v239 row_ror:8 row_mask:0xf bank_mask:0x3
	s_add_u32 s100, s100, 0x120000
	s_addc_u32 s101, s101, 0
	global_store_dwordx4 v240, v[228:231], s[100:101]
	s_add_u32 s100, s100, 0x20000
	s_addc_u32 s101, s101, 0
	global_store_dwordx4 v240, v[232:235], s[100:101]
	v_max_f32_e32 v44, 0, v44
	v_max_f32_e32 v45, 0, v45
	v_max_f32_e32 v46, 0, v46
	v_max_f32_e32 v47, 0, v47
	v_max_f32_e32 v40, 0, v40
	v_max_f32_e32 v41, 0, v41
	v_max_f32_e32 v42, 0, v42
	v_max_f32_e32 v43, 0, v43
	v_pk_mul_f32 v[44:45], v[44:45], v[44:45]
	v_pk_mul_f32 v[46:47], v[46:47], v[46:47]
	v_pk_mul_f32 v[40:41], v[40:41], v[40:41]
	v_pk_mul_f32 v[42:43], v[42:43], v[42:43]
	v_cvt_pk_bf16_f32 v228, v44, v45
	v_cvt_pk_bf16_f32 v229, v46, v47
	v_cvt_pk_bf16_f32 v230, v40, v41
	v_cvt_pk_bf16_f32 v231, v42, v43
	v_max_f32_e32 v36, 0, v36
	v_max_f32_e32 v37, 0, v37
	v_max_f32_e32 v38, 0, v38
	v_max_f32_e32 v39, 0, v39
	v_max_f32_e32 v32, 0, v32
	v_max_f32_e32 v33, 0, v33
	v_max_f32_e32 v34, 0, v34
	v_max_f32_e32 v35, 0, v35
	v_pk_mul_f32 v[36:37], v[36:37], v[36:37]
	v_pk_mul_f32 v[38:39], v[38:39], v[38:39]
	v_pk_mul_f32 v[32:33], v[32:33], v[32:33]
	v_pk_mul_f32 v[34:35], v[34:35], v[34:35]
	v_cvt_pk_bf16_f32 v232, v36, v37
	v_cvt_pk_bf16_f32 v233, v38, v39
	v_cvt_pk_bf16_f32 v234, v32, v33
	v_cvt_pk_bf16_f32 v235, v34, v35
	v_mov_b32_e32 v236, v228
	v_mov_b32_e32 v237, v229
	v_mov_b32_e32 v238, v230
	v_mov_b32_e32 v239, v231
	v_mov_b32_dpp v228, v232 row_ror:8 row_mask:0xf bank_mask:0xc
	v_mov_b32_dpp v229, v233 row_ror:8 row_mask:0xf bank_mask:0xc
	v_mov_b32_dpp v230, v234 row_ror:8 row_mask:0xf bank_mask:0xc
	v_mov_b32_dpp v231, v235 row_ror:8 row_mask:0xf bank_mask:0xc
	v_mov_b32_dpp v232, v236 row_ror:8 row_mask:0xf bank_mask:0x3
	v_mov_b32_dpp v233, v237 row_ror:8 row_mask:0xf bank_mask:0x3
	v_mov_b32_dpp v234, v238 row_ror:8 row_mask:0xf bank_mask:0x3
	v_mov_b32_dpp v235, v239 row_ror:8 row_mask:0xf bank_mask:0x3
	s_add_u32 s100, s100, 0x20000
	s_addc_u32 s101, s101, 0
	global_store_dwordx4 v240, v[228:231], s[100:101]
	s_add_u32 s100, s100, 0x20000
	s_addc_u32 s101, s101, 0
	global_store_dwordx4 v240, v[232:235], s[100:101]
	v_max_f32_e32 v28, 0, v28
	v_max_f32_e32 v29, 0, v29
	v_max_f32_e32 v30, 0, v30
	v_max_f32_e32 v31, 0, v31
	v_max_f32_e32 v24, 0, v24
	v_max_f32_e32 v25, 0, v25
	v_max_f32_e32 v26, 0, v26
	v_max_f32_e32 v27, 0, v27
	v_pk_mul_f32 v[28:29], v[28:29], v[28:29]
	v_pk_mul_f32 v[30:31], v[30:31], v[30:31]
	v_pk_mul_f32 v[24:25], v[24:25], v[24:25]
	v_pk_mul_f32 v[26:27], v[26:27], v[26:27]
	v_cvt_pk_bf16_f32 v228, v28, v29
	v_cvt_pk_bf16_f32 v229, v30, v31
	v_cvt_pk_bf16_f32 v230, v24, v25
	v_cvt_pk_bf16_f32 v231, v26, v27
	v_max_f32_e32 v20, 0, v20
	v_max_f32_e32 v21, 0, v21
	v_max_f32_e32 v22, 0, v22
	v_max_f32_e32 v23, 0, v23
	v_max_f32_e32 v16, 0, v16
	v_max_f32_e32 v17, 0, v17
	v_max_f32_e32 v18, 0, v18
	v_max_f32_e32 v19, 0, v19
	v_pk_mul_f32 v[20:21], v[20:21], v[20:21]
	v_pk_mul_f32 v[22:23], v[22:23], v[22:23]
	v_pk_mul_f32 v[16:17], v[16:17], v[16:17]
	v_pk_mul_f32 v[18:19], v[18:19], v[18:19]
	v_cvt_pk_bf16_f32 v232, v20, v21
	v_cvt_pk_bf16_f32 v233, v22, v23
	v_cvt_pk_bf16_f32 v234, v16, v17
	v_cvt_pk_bf16_f32 v235, v18, v19
	v_mov_b32_e32 v236, v228
	v_mov_b32_e32 v237, v229
	v_mov_b32_e32 v238, v230
	v_mov_b32_e32 v239, v231
	v_mov_b32_dpp v228, v232 row_ror:8 row_mask:0xf bank_mask:0xc
	v_mov_b32_dpp v229, v233 row_ror:8 row_mask:0xf bank_mask:0xc
	v_mov_b32_dpp v230, v234 row_ror:8 row_mask:0xf bank_mask:0xc
	v_mov_b32_dpp v231, v235 row_ror:8 row_mask:0xf bank_mask:0xc
	v_mov_b32_dpp v232, v236 row_ror:8 row_mask:0xf bank_mask:0x3
	v_mov_b32_dpp v233, v237 row_ror:8 row_mask:0xf bank_mask:0x3
	v_mov_b32_dpp v234, v238 row_ror:8 row_mask:0xf bank_mask:0x3
	v_mov_b32_dpp v235, v239 row_ror:8 row_mask:0xf bank_mask:0x3
	s_add_u32 s100, s100, 0x20000
	s_addc_u32 s101, s101, 0
	global_store_dwordx4 v240, v[228:231], s[100:101]
	s_add_u32 s100, s100, 0x20000
	s_addc_u32 s101, s101, 0
	global_store_dwordx4 v240, v[232:235], s[100:101]
	v_max_f32_e32 v12, 0, v12
	v_max_f32_e32 v13, 0, v13
	v_max_f32_e32 v14, 0, v14
	v_max_f32_e32 v15, 0, v15
	v_max_f32_e32 v8, 0, v8
	v_max_f32_e32 v9, 0, v9
	v_max_f32_e32 v10, 0, v10
	v_max_f32_e32 v11, 0, v11
	v_pk_mul_f32 v[12:13], v[12:13], v[12:13]
	v_pk_mul_f32 v[14:15], v[14:15], v[14:15]
	v_pk_mul_f32 v[8:9], v[8:9], v[8:9]
	v_pk_mul_f32 v[10:11], v[10:11], v[10:11]
	v_cvt_pk_bf16_f32 v228, v12, v13
	v_cvt_pk_bf16_f32 v229, v14, v15
	v_cvt_pk_bf16_f32 v230, v8, v9
	v_cvt_pk_bf16_f32 v231, v10, v11
	v_max_f32_e32 v4, 0, v4
	v_max_f32_e32 v5, 0, v5
	v_max_f32_e32 v6, 0, v6
	v_max_f32_e32 v7, 0, v7
	v_max_f32_e32 v0, 0, v0
	v_max_f32_e32 v1, 0, v1
	v_max_f32_e32 v2, 0, v2
	v_max_f32_e32 v3, 0, v3
	v_pk_mul_f32 v[4:5], v[4:5], v[4:5]
	v_pk_mul_f32 v[6:7], v[6:7], v[6:7]
	v_pk_mul_f32 v[0:1], v[0:1], v[0:1]
	v_pk_mul_f32 v[2:3], v[2:3], v[2:3]
	v_cvt_pk_bf16_f32 v232, v4, v5
	v_cvt_pk_bf16_f32 v233, v6, v7
	v_cvt_pk_bf16_f32 v234, v0, v1
	v_cvt_pk_bf16_f32 v235, v2, v3
	v_mov_b32_e32 v236, v228
	v_mov_b32_e32 v237, v229
	v_mov_b32_e32 v238, v230
	v_mov_b32_e32 v239, v231
	v_mov_b32_dpp v228, v232 row_ror:8 row_mask:0xf bank_mask:0xc
	v_mov_b32_dpp v229, v233 row_ror:8 row_mask:0xf bank_mask:0xc
	v_mov_b32_dpp v230, v234 row_ror:8 row_mask:0xf bank_mask:0xc
	v_mov_b32_dpp v231, v235 row_ror:8 row_mask:0xf bank_mask:0xc
	v_mov_b32_dpp v232, v236 row_ror:8 row_mask:0xf bank_mask:0x3
	v_mov_b32_dpp v233, v237 row_ror:8 row_mask:0xf bank_mask:0x3
	v_mov_b32_dpp v234, v238 row_ror:8 row_mask:0xf bank_mask:0x3
	v_mov_b32_dpp v235, v239 row_ror:8 row_mask:0xf bank_mask:0x3
	s_add_u32 s100, s100, 0x20000
	s_addc_u32 s101, s101, 0
	global_store_dwordx4 v240, v[228:231], s[100:101]
	s_add_u32 s100, s100, 0x20000
	s_addc_u32 s101, s101, 0
	global_store_dwordx4 v240, v[232:235], s[100:101]
	s_and_b64 vcc, exec, s[2:3]
	s_mov_b32 s47, s12
	s_mov_b32 s20, s14
	s_mov_b64 s[24:25], s[18:19]
	s_mov_b64 s[22:23], s[16:17]
	s_cbranch_vccz .LBB0_1561
	s_waitcnt vmcnt(0)
	s_cmpk_gt_u32 s28, 0xff
	s_cbranch_scc1 .LBB0_1568
	s_barrier

.LBB0_1631:
	ds_read_b128 v[146:149], v143
	ds_read_b128 v[150:153], v143 offset:1024
	ds_read_b128 v[154:157], v143 offset:2048
	ds_read_b128 v[158:161], v143 offset:3072
	s_add_i32 s51, s22, 2
	s_add_u32 s23, s20, 0xffe00080
	s_addc_u32 s24, s21, -1
	s_cmp_eq_u32 s48, s22
	s_cselect_b32 s22, s47, s49
	s_cselect_b32 s25, s11, s24
	s_cselect_b32 s24, s13, s23
	s_cselect_b32 s23, s46, s50
	s_add_i32 m0, s30, 0xc000
	ds_read_b128 v[162:165], v144
	ds_read_b128 v[166:169], v144 offset:1024
	ds_read_b128 v[170:173], v144 offset:2048
	ds_read_b128 v[174:177], v144 offset:3072
	ds_read_b128 v[178:181], v144 offset:4096
	ds_read_b128 v[182:185], v144 offset:5120
	ds_read_b128 v[186:189], v144 offset:6144
	ds_read_b128 v[190:193], v144 offset:7168
	global_load_lds_dwordx4 v136, s[20:21]
	s_add_i32 m0, s30, 0xe000
	s_nop 0
	global_load_lds_dwordx4 v138, s[20:21]
	s_waitcnt lgkmcnt(8)
	s_barrier
	s_waitcnt lgkmcnt(0)
	s_waitcnt lgkmcnt(0)
	v_mfma_f32_16x16x32_bf16 v[124:127], v[146:149], v[162:165], v[124:127]
	v_mfma_f32_16x16x32_bf16 v[120:123], v[154:157], v[162:165], v[120:123]
	v_mfma_f32_16x16x32_bf16 v[108:111], v[146:149], v[170:173], v[108:111]
	v_mfma_f32_16x16x32_bf16 v[104:107], v[154:157], v[170:173], v[104:107]
	v_mfma_f32_16x16x32_bf16 v[92:95], v[146:149], v[178:181], v[92:95]
	v_mfma_f32_16x16x32_bf16 v[88:91], v[154:157], v[178:181], v[88:91]
	v_mfma_f32_16x16x32_bf16 v[76:79], v[146:149], v[186:189], v[76:79]
	v_mfma_f32_16x16x32_bf16 v[72:75], v[154:157], v[186:189], v[72:75]
	v_mfma_f32_16x16x32_bf16 v[124:127], v[150:153], v[166:169], v[124:127]
	v_mfma_f32_16x16x32_bf16 v[120:123], v[158:161], v[166:169], v[120:123]
	v_mfma_f32_16x16x32_bf16 v[108:111], v[150:153], v[174:177], v[108:111]
	v_mfma_f32_16x16x32_bf16 v[104:107], v[158:161], v[174:177], v[104:107]
	v_mfma_f32_16x16x32_bf16 v[92:95], v[150:153], v[182:185], v[92:95]
	v_mfma_f32_16x16x32_bf16 v[88:91], v[158:161], v[182:185], v[88:91]
	v_mfma_f32_16x16x32_bf16 v[76:79], v[150:153], v[190:193], v[76:79]
	v_mfma_f32_16x16x32_bf16 v[72:75], v[158:161], v[190:193], v[72:75]
	s_barrier
	s_add_i32 s52, s39, s29
	s_mov_b32 m0, s52
	ds_read_b128 v[194:197], v145
	ds_read_b128 v[198:201], v145 offset:1024
	ds_read_b128 v[204:207], v145 offset:2048
	ds_read_b128 v[208:211], v145 offset:3072
	global_load_lds_dwordx4 v132, s[22:23]
	s_add_i32 m0, s52, 0x2000
	s_nop 0
	global_load_lds_dwordx4 v128, s[22:23]
	s_barrier
	s_waitcnt lgkmcnt(0)
	s_waitcnt lgkmcnt(0)
	v_mfma_f32_16x16x32_bf16 v[116:119], v[194:197], v[162:165], v[116:119]
	v_mfma_f32_16x16x32_bf16 v[112:115], v[204:207], v[162:165], v[112:115]
	v_mfma_f32_16x16x32_bf16 v[100:103], v[194:197], v[170:173], v[100:103]
	v_mfma_f32_16x16x32_bf16 v[96:99], v[204:207], v[170:173], v[96:99]
	v_mfma_f32_16x16x32_bf16 v[84:87], v[194:197], v[178:181], v[84:87]
	v_mfma_f32_16x16x32_bf16 v[80:83], v[204:207], v[178:181], v[80:83]
	v_mfma_f32_16x16x32_bf16 v[68:71], v[194:197], v[186:189], v[68:71]
	v_mfma_f32_16x16x32_bf16 v[64:67], v[204:207], v[186:189], v[64:67]
	v_mfma_f32_16x16x32_bf16 v[116:119], v[198:201], v[166:169], v[116:119]
	v_mfma_f32_16x16x32_bf16 v[112:115], v[208:211], v[166:169], v[112:115]
	v_mfma_f32_16x16x32_bf16 v[100:103], v[198:201], v[174:177], v[100:103]
	v_mfma_f32_16x16x32_bf16 v[96:99], v[208:211], v[174:177], v[96:99]
	v_mfma_f32_16x16x32_bf16 v[84:87], v[198:201], v[182:185], v[84:87]
	v_mfma_f32_16x16x32_bf16 v[80:83], v[208:211], v[182:185], v[80:83]
	v_mfma_f32_16x16x32_bf16 v[68:71], v[198:201], v[190:193], v[68:71]
	v_mfma_f32_16x16x32_bf16 v[64:67], v[208:211], v[190:193], v[64:67]
	s_mov_b32 m0, s30
	s_mov_b64 s[98:99], s[24:25]
	s_barrier
	ds_read_b128 v[162:165], v144 offset:16384
	ds_read_b128 v[166:169], v144 offset:17408
	ds_read_b128 v[170:173], v144 offset:18432
	ds_read_b128 v[174:177], v144 offset:19456
	ds_read_b128 v[178:181], v144 offset:20480
	ds_read_b128 v[182:185], v144 offset:21504
	ds_read_b128 v[186:189], v144 offset:22528
	ds_read_b128 v[190:193], v144 offset:23552
	global_load_lds_dwordx4 v134, s[24:25]
	s_mov_b32 m0, s31
	s_nop 0
	global_load_lds_dwordx4 v130, s[24:25]
	s_barrier
	s_waitcnt lgkmcnt(0)
	s_waitcnt lgkmcnt(0)
	v_mfma_f32_16x16x32_bf16 v[60:63], v[146:149], v[162:165], v[60:63]
	v_mfma_f32_16x16x32_bf16 v[56:59], v[154:157], v[162:165], v[56:59]
	v_mfma_f32_16x16x32_bf16 v[44:47], v[146:149], v[170:173], v[44:47]
	v_mfma_f32_16x16x32_bf16 v[40:43], v[154:157], v[170:173], v[40:43]
	v_mfma_f32_16x16x32_bf16 v[28:31], v[146:149], v[178:181], v[28:31]
	v_mfma_f32_16x16x32_bf16 v[24:27], v[154:157], v[178:181], v[24:27]
	v_mfma_f32_16x16x32_bf16 v[12:15], v[146:149], v[186:189], v[12:15]
	v_mfma_f32_16x16x32_bf16 v[8:11], v[154:157], v[186:189], v[8:11]
	v_mfma_f32_16x16x32_bf16 v[60:63], v[150:153], v[166:169], v[60:63]
	v_mfma_f32_16x16x32_bf16 v[56:59], v[158:161], v[166:169], v[56:59]
	v_mfma_f32_16x16x32_bf16 v[44:47], v[150:153], v[174:177], v[44:47]
	v_mfma_f32_16x16x32_bf16 v[40:43], v[158:161], v[174:177], v[40:43]
	v_mfma_f32_16x16x32_bf16 v[28:31], v[150:153], v[182:185], v[28:31]
	v_mfma_f32_16x16x32_bf16 v[24:27], v[158:161], v[182:185], v[24:27]
	v_mfma_f32_16x16x32_bf16 v[12:15], v[150:153], v[190:193], v[12:15]
	v_mfma_f32_16x16x32_bf16 v[8:11], v[158:161], v[190:193], v[8:11]
	s_barrier
	s_add_u32 s52, s22, 0x80000
	s_addc_u32 s53, s23, 0
	s_add_i32 s54, s40, s29
	s_mov_b32 m0, s54
	s_nop 0
	global_load_lds_dwordx4 v132, s[52:53]
	s_add_i32 m0, s54, 0x2000
	s_nop 0
	global_load_lds_dwordx4 v128, s[52:53]
	s_waitcnt vmcnt(6)
	s_barrier
	v_mfma_f32_16x16x32_bf16 v[52:55], v[194:197], v[162:165], v[52:55]
	v_mfma_f32_16x16x32_bf16 v[48:51], v[204:207], v[162:165], v[48:51]
	v_mfma_f32_16x16x32_bf16 v[36:39], v[194:197], v[170:173], v[36:39]
	v_mfma_f32_16x16x32_bf16 v[32:35], v[204:207], v[170:173], v[32:35]
	v_mfma_f32_16x16x32_bf16 v[20:23], v[194:197], v[178:181], v[20:23]
	v_mfma_f32_16x16x32_bf16 v[16:19], v[204:207], v[178:181], v[16:19]
	v_mfma_f32_16x16x32_bf16 v[4:7], v[194:197], v[186:189], v[4:7]
	v_mfma_f32_16x16x32_bf16 v[0:3], v[204:207], v[186:189], v[0:3]
	v_mfma_f32_16x16x32_bf16 v[52:55], v[198:201], v[166:169], v[52:55]
	v_mfma_f32_16x16x32_bf16 v[48:51], v[208:211], v[166:169], v[48:51]
	v_mfma_f32_16x16x32_bf16 v[36:39], v[198:201], v[174:177], v[36:39]
	v_mfma_f32_16x16x32_bf16 v[32:35], v[208:211], v[174:177], v[32:35]
	v_mfma_f32_16x16x32_bf16 v[20:23], v[198:201], v[182:185], v[20:23]
	v_mfma_f32_16x16x32_bf16 v[16:19], v[208:211], v[182:185], v[16:19]
	v_mfma_f32_16x16x32_bf16 v[4:7], v[198:201], v[190:193], v[4:7]
	v_mfma_f32_16x16x32_bf16 v[0:3], v[208:211], v[190:193], v[0:3]
	s_add_i32 s52, 0, 0x18000
	v_add_u32_e32 v158, s52, v141
	s_barrier
	ds_read_b128 v[146:149], v158
	ds_read_b128 v[150:153], v158 offset:1024
	ds_read_b128 v[154:157], v158 offset:2048
	ds_read_b128 v[158:161], v158 offset:3072
	s_add_u32 s24, s24, 0x200000
	s_addc_u32 s25, s25, 0
	s_mov_b32 m0, s34
	ds_read_b128 v[162:165], v144 offset:32768
	ds_read_b128 v[166:169], v144 offset:33792
	ds_read_b128 v[170:173], v144 offset:34816
	ds_read_b128 v[174:177], v144 offset:35840
	ds_read_b128 v[178:181], v144 offset:36864
	ds_read_b128 v[182:185], v144 offset:37888
	ds_read_b128 v[186:189], v144 offset:38912
	ds_read_b128 v[190:193], v144 offset:39936
	global_load_lds_dwordx4 v134, s[24:25]
	s_mov_b32 m0, s35
	s_nop 0
	global_load_lds_dwordx4 v130, s[24:25]
	s_waitcnt lgkmcnt(8)
	s_barrier
	s_waitcnt lgkmcnt(0)
	s_waitcnt lgkmcnt(0)
	v_mfma_f32_16x16x32_bf16 v[124:127], v[146:149], v[162:165], v[124:127]
	v_mfma_f32_16x16x32_bf16 v[120:123], v[154:157], v[162:165], v[120:123]
	v_mfma_f32_16x16x32_bf16 v[108:111], v[146:149], v[170:173], v[108:111]
	v_mfma_f32_16x16x32_bf16 v[104:107], v[154:157], v[170:173], v[104:107]
	v_mfma_f32_16x16x32_bf16 v[92:95], v[146:149], v[178:181], v[92:95]
	v_mfma_f32_16x16x32_bf16 v[88:91], v[154:157], v[178:181], v[88:91]
	v_mfma_f32_16x16x32_bf16 v[76:79], v[146:149], v[186:189], v[76:79]
	v_mfma_f32_16x16x32_bf16 v[72:75], v[154:157], v[186:189], v[72:75]
	v_mfma_f32_16x16x32_bf16 v[124:127], v[150:153], v[166:169], v[124:127]
	v_mfma_f32_16x16x32_bf16 v[120:123], v[158:161], v[166:169], v[120:123]
	v_mfma_f32_16x16x32_bf16 v[108:111], v[150:153], v[174:177], v[108:111]
	v_mfma_f32_16x16x32_bf16 v[104:107], v[158:161], v[174:177], v[104:107]
	v_mfma_f32_16x16x32_bf16 v[92:95], v[150:153], v[182:185], v[92:95]
	v_mfma_f32_16x16x32_bf16 v[88:91], v[158:161], v[182:185], v[88:91]
	v_mfma_f32_16x16x32_bf16 v[76:79], v[150:153], v[190:193], v[76:79]
	v_mfma_f32_16x16x32_bf16 v[72:75], v[158:161], v[190:193], v[72:75]
	s_barrier
	s_add_i32 s24, 0, 0x1c000
	s_add_i32 s25, s52, s29
	v_add_u32_e32 v208, s24, v141
	s_mov_b32 m0, s25
	ds_read_b128 v[194:197], v208
	ds_read_b128 v[198:201], v208 offset:1024
	ds_read_b128 v[204:207], v208 offset:2048
	ds_read_b128 v[208:211], v208 offset:3072
	s_add_u32 s100, s22, 0x80
	s_addc_u32 s101, s23, 0
	global_load_lds_dwordx4 v132, s[100:101]
	s_add_i32 m0, s25, 0x2000
	s_nop 0
	s_add_u32 s100, s22, 0x80
	s_addc_u32 s101, s23, 0
	global_load_lds_dwordx4 v128, s[100:101]
	s_barrier
	s_waitcnt lgkmcnt(0)
	s_waitcnt lgkmcnt(0)
	v_mfma_f32_16x16x32_bf16 v[116:119], v[194:197], v[162:165], v[116:119]
	v_mfma_f32_16x16x32_bf16 v[112:115], v[204:207], v[162:165], v[112:115]
	v_mfma_f32_16x16x32_bf16 v[100:103], v[194:197], v[170:173], v[100:103]
	v_mfma_f32_16x16x32_bf16 v[96:99], v[204:207], v[170:173], v[96:99]
	v_mfma_f32_16x16x32_bf16 v[84:87], v[194:197], v[178:181], v[84:87]
	v_mfma_f32_16x16x32_bf16 v[80:83], v[204:207], v[178:181], v[80:83]
	v_mfma_f32_16x16x32_bf16 v[68:71], v[194:197], v[186:189], v[68:71]
	v_mfma_f32_16x16x32_bf16 v[64:67], v[204:207], v[186:189], v[64:67]
	v_mfma_f32_16x16x32_bf16 v[116:119], v[198:201], v[166:169], v[116:119]
	v_mfma_f32_16x16x32_bf16 v[112:115], v[208:211], v[166:169], v[112:115]
	v_mfma_f32_16x16x32_bf16 v[100:103], v[198:201], v[174:177], v[100:103]
	v_mfma_f32_16x16x32_bf16 v[96:99], v[208:211], v[174:177], v[96:99]
	v_mfma_f32_16x16x32_bf16 v[84:87], v[198:201], v[182:185], v[84:87]
	v_mfma_f32_16x16x32_bf16 v[80:83], v[208:211], v[182:185], v[80:83]
	v_mfma_f32_16x16x32_bf16 v[68:71], v[198:201], v[190:193], v[68:71]
	v_mfma_f32_16x16x32_bf16 v[64:67], v[208:211], v[190:193], v[64:67]
	s_mov_b32 m0, s37
	s_barrier
	ds_read_b128 v[162:165], v144 offset:49152
	ds_read_b128 v[166:169], v144 offset:50176
	ds_read_b128 v[170:173], v144 offset:51200
	ds_read_b128 v[174:177], v144 offset:52224
	ds_read_b128 v[178:181], v144 offset:53248
	ds_read_b128 v[182:185], v144 offset:54272
	ds_read_b128 v[186:189], v144 offset:55296
	ds_read_b128 v[190:193], v144 offset:56320
	s_add_u32 s100, s98, 0x80
	s_addc_u32 s101, s99, 0
	global_load_lds_dwordx4 v134, s[100:101]
	s_mov_b32 m0, s38
	s_nop 0
	s_add_u32 s100, s98, 0x80
	s_addc_u32 s101, s99, 0
	global_load_lds_dwordx4 v130, s[100:101]
	s_barrier
	s_waitcnt lgkmcnt(0)
	s_waitcnt lgkmcnt(0)
	v_mfma_f32_16x16x32_bf16 v[60:63], v[146:149], v[162:165], v[60:63]
	v_mfma_f32_16x16x32_bf16 v[56:59], v[154:157], v[162:165], v[56:59]
	v_mfma_f32_16x16x32_bf16 v[44:47], v[146:149], v[170:173], v[44:47]
	v_mfma_f32_16x16x32_bf16 v[40:43], v[154:157], v[170:173], v[40:43]
	v_mfma_f32_16x16x32_bf16 v[28:31], v[146:149], v[178:181], v[28:31]
	v_mfma_f32_16x16x32_bf16 v[24:27], v[154:157], v[178:181], v[24:27]
	v_mfma_f32_16x16x32_bf16 v[12:15], v[146:149], v[186:189], v[12:15]
	v_mfma_f32_16x16x32_bf16 v[8:11], v[154:157], v[186:189], v[8:11]
	v_mfma_f32_16x16x32_bf16 v[60:63], v[150:153], v[166:169], v[60:63]
	v_mfma_f32_16x16x32_bf16 v[56:59], v[158:161], v[166:169], v[56:59]
	v_mfma_f32_16x16x32_bf16 v[44:47], v[150:153], v[174:177], v[44:47]
	v_mfma_f32_16x16x32_bf16 v[40:43], v[158:161], v[174:177], v[40:43]
	v_mfma_f32_16x16x32_bf16 v[28:31], v[150:153], v[182:185], v[28:31]
	v_mfma_f32_16x16x32_bf16 v[24:27], v[158:161], v[182:185], v[24:27]
	v_mfma_f32_16x16x32_bf16 v[12:15], v[150:153], v[190:193], v[12:15]
	v_mfma_f32_16x16x32_bf16 v[8:11], v[158:161], v[190:193], v[8:11]
	s_barrier
	s_add_u32 s22, s22, 0x80080
	s_addc_u32 s23, s23, 0
	s_add_i32 s24, s24, s29
	s_mov_b32 m0, s24
	s_nop 0
	global_load_lds_dwordx4 v132, s[22:23]
	s_add_i32 m0, s24, 0x2000
	s_nop 0
	global_load_lds_dwordx4 v128, s[22:23]
	s_waitcnt vmcnt(6)
	s_barrier
	v_mfma_f32_16x16x32_bf16 v[52:55], v[194:197], v[162:165], v[52:55]
	v_mfma_f32_16x16x32_bf16 v[48:51], v[204:207], v[162:165], v[48:51]
	v_mfma_f32_16x16x32_bf16 v[36:39], v[194:197], v[170:173], v[36:39]
	v_mfma_f32_16x16x32_bf16 v[32:35], v[204:207], v[170:173], v[32:35]
	v_mfma_f32_16x16x32_bf16 v[20:23], v[194:197], v[178:181], v[20:23]
	v_mfma_f32_16x16x32_bf16 v[16:19], v[204:207], v[178:181], v[16:19]
	v_mfma_f32_16x16x32_bf16 v[4:7], v[194:197], v[186:189], v[4:7]
	v_mfma_f32_16x16x32_bf16 v[0:3], v[204:207], v[186:189], v[0:3]
	v_mfma_f32_16x16x32_bf16 v[52:55], v[198:201], v[166:169], v[52:55]
	v_mfma_f32_16x16x32_bf16 v[48:51], v[208:211], v[166:169], v[48:51]
	v_mfma_f32_16x16x32_bf16 v[36:39], v[198:201], v[174:177], v[36:39]
	v_mfma_f32_16x16x32_bf16 v[32:35], v[208:211], v[174:177], v[32:35]
	v_mfma_f32_16x16x32_bf16 v[20:23], v[198:201], v[182:185], v[20:23]
	v_mfma_f32_16x16x32_bf16 v[16:19], v[208:211], v[182:185], v[16:19]
	v_mfma_f32_16x16x32_bf16 v[4:7], v[198:201], v[190:193], v[4:7]
	v_mfma_f32_16x16x32_bf16 v[0:3], v[208:211], v[190:193], v[0:3]
	s_add_u32 s20, s20, 0x100
	s_addc_u32 s21, s21, 0
	s_add_u32 s49, s49, 0x100
	s_addc_u32 s50, s50, 0
	s_cmp_ge_i32 s51, s33
	s_mov_b32 s22, s51
	s_barrier
	s_cbranch_scc0 .LBB0_1631
	s_branch .LBB0_1626
